# 63 kernarg pointer fetches (vector load + immediate vmcnt(0)) converted to s_load_dwordx2 via scalar cache; s91 clobber in g1 items removed
# speedup vs baseline: 1.0079x; 1.0079x over previous
.LBB0_11:
	s_or_b64 exec, exec, s[6:7]
	s_memrealtime s[4:5]
	s_cmp_lt_i32 s90, 1
	s_waitcnt lgkmcnt(0)
	s_cselect_b64 s[4:5], -1, 0
	s_cmp_gt_i32 s91, 0
	s_cselect_b64 s[6:7], -1, 0
	s_and_b64 s[16:17], s[4:5], s[6:7]
	s_andn2_b64 vcc, exec, s[16:17]
	s_cbranch_vccnz .LBB0_673
	s_lshr_b32 s3, s2, 6
	s_lshl_b32 s2, s60, 3
	s_add_i32 s2, s3, s2
	s_min_i32 s13, s2, 0x53ff
	s_cmpk_lt_i32 s2, 0x5200
	s_cbranch_scc0 .LBB0_19
	s_mul_hi_i32 s4, s13, 0x63e7063f
	s_lshr_b32 s5, s4, 31
	s_ashr_i32 s4, s4, 12
	s_add_i32 s18, s4, s5
	s_mul_i32 s4, s18, 0x2900
	s_sub_i32 s22, s13, s4
	s_ashr_i32 s19, s18, 31
	s_mul_i32 s5, s18, 0x2a00000
	s_mul_hi_i32 s4, s18, 0x2a00000
	s_add_u32 s5, s94, s5
	s_addc_u32 s4, s95, s4
	s_add_u32 s6, s5, 0x200000
	s_addc_u32 s7, s4, 0
	s_cmpk_gt_i32 s22, 0xaff
	s_cbranch_scc0 .LBB0_20
	s_cmpk_gt_u32 s22, 0x107f
	s_cbranch_scc0 .LBB0_21
	s_cmpk_gt_u32 s22, 0x167f
	s_cbranch_scc0 .LBB0_22
	s_cmpk_gt_u32 s22, 0x187f
	s_cbranch_scc0 .LBB0_23
	s_cmpk_gt_u32 s22, 0x237f
	s_cbranch_scc0 .LBB0_24
	v_mov_b64_e32 v[2:3], s[0:1]
	s_load_dwordx2 s[98:99], s[0:1], 0xc0
	s_waitcnt vmcnt(0) lgkmcnt(0)
	v_mov_b32_e32 v2, s98
	v_mov_b32_e32 v3, s99
	s_add_u32 s8, s6, 0x2380000
	s_addc_u32 s9, s7, 0
	s_lshl_b32 s4, s22, 5
	s_lshl_b32 s5, s22, 1
	v_mov_b32_e32 v1, 0xb00000
	s_and_b32 s23, s4, 0x3e0
	s_and_b32 s4, s5, 0x7fffffc0
	s_add_i32 s12, s4, 0xffffb900
	s_mov_b64 s[10:11], 0
	s_waitcnt lgkmcnt(0)
	v_mad_i64_i32 v[2:3], s[4:5], s18, v1, v[2:3]
	s_branch .LBB0_25

.LBB0_25:
	s_andn2_b64 vcc, exec, s[10:11]
	s_cbranch_vccnz .LBB0_28
	v_mov_b64_e32 v[2:3], s[0:1]
	s_load_dwordx2 s[98:99], s[0:1], 0xb8
	s_waitcnt vmcnt(0) lgkmcnt(0)
	v_mov_b32_e32 v2, s98
	v_mov_b32_e32 v3, s99
	s_add_i32 s4, s22, 0xe780
	s_and_b32 s5, s4, 0xffff
	s_mul_i32 s5, s5, 0xba2f
	s_lshr_b32 s5, s5, 23
	s_mul_i32 s8, s5, 0xb0
	s_sub_i32 s4, s4, s8
	s_lshl_b32 s8, s4, 5
	s_and_b32 s23, s8, 0xffe0
	s_and_b32 s4, s4, 0xffff
	s_cmpk_gt_u32 s4, 0x57
	s_cbranch_scc0 .LBB0_29
	s_lshl_b32 s4, s23, 1
	s_add_i32 s4, s4, 0x7fffea00
	s_and_b32 s4, s4, 0x7fffff00
	s_and_b32 s8, s23, 0x60
	s_or_b32 s4, s8, s4
	s_bitset1_b32 s4, 7
	s_mov_b64 s[8:9], 0
	s_branch .LBB0_30

.LBB0_34:
	s_andn2_b64 vcc, exec, s[20:21]
	s_cbranch_vccnz .LBB0_36
	v_mov_b64_e32 v[2:3], s[0:1]
	s_load_dwordx2 s[98:99], s[0:1], 0xb0
	s_waitcnt vmcnt(0) lgkmcnt(0)
	v_mov_b32_e32 v2, s98
	v_mov_b32_e32 v3, s99
	s_lshl_b64 s[20:21], s[18:19], 22
	s_add_u32 s8, s6, 0x1680000
	s_addc_u32 s9, s7, 0
	s_lshl_b32 s4, s22, 5
	s_lshl_b32 s12, s22, 1
	s_and_b32 s23, s4, 0x3e0
	s_and_b32 s4, s12, 0x3fc0
	s_mov_b64 s[10:11], 0x400
	s_movk_i32 s5, 0x400
	s_add_i32 s12, s4, 0xffffd300
	s_mov_b32 s4, s23
	s_waitcnt lgkmcnt(0)
	v_lshl_add_u64 v[2:3], v[2:3], 0, s[20:21]

.LBB0_37:
	s_andn2_b64 vcc, exec, s[20:21]
	s_cbranch_vccnz .LBB0_39
	v_mov_b64_e32 v[2:3], s[0:1]
	s_load_dwordx2 s[98:99], s[0:1], 0x70
	s_waitcnt vmcnt(0) lgkmcnt(0)
	v_mov_b32_e32 v2, s98
	v_mov_b32_e32 v3, s99
	s_add_i32 s4, s22, 0xef80
	s_and_b32 s8, s4, 0xffff
	s_mul_i32 s8, s8, 0xaaab
	s_lshr_b32 s12, s8, 16
	s_lshr_b32 s8, s8, 22
	s_mulk_i32 s8, 0x60
	s_sub_i32 s4, s4, s8
	s_add_u32 s8, s6, 0x1080000
	s_addc_u32 s9, s7, 0
	s_lshl_b32 s4, s4, 5
	v_mov_b32_e32 v1, 0xb28000
	s_and_b32 s23, s4, 0xffe0
	s_mov_b64 s[10:11], 0x400
	s_movk_i32 s5, 0xb28
	s_and_b32 s12, s12, 0xffc0
	s_mov_b32 s4, s23
	s_waitcnt lgkmcnt(0)
	v_mad_i64_i32 v[2:3], s[20:21], s18, v1, v[2:3]

.LBB0_40:
	v_mov_b64_e32 v[2:3], s[0:1]
	s_load_dwordx2 s[98:99], s[0:1], 0x68
	s_waitcnt vmcnt(0) lgkmcnt(0)
	v_mov_b32_e32 v2, s98
	v_mov_b32_e32 v3, s99
	s_add_u32 s8, s6, 0xb00000
	s_addc_u32 s9, s7, 0
	s_lshl_b32 s4, s22, 5
	s_lshl_b32 s12, s22, 1
	v_mov_b32_e32 v1, 0xb00000
	s_and_b32 s23, s4, 0x3e0
	s_and_b32 s4, s12, 0x3fc0
	s_mov_b64 s[10:11], 0xb00
	s_movk_i32 s5, 0x400
	s_add_i32 s12, s4, 0xffffea00
	s_mov_b32 s4, s23
	s_waitcnt lgkmcnt(0)
	v_mad_i64_i32 v[2:3], s[20:21], s18, v1, v[2:3]

.LBB0_42:
	v_mov_b64_e32 v[2:3], s[0:1]
	s_load_dwordx2 s[98:99], s[0:1], 0x60
	s_waitcnt vmcnt(0) lgkmcnt(0)
	v_mov_b32_e32 v2, s98
	v_mov_b32_e32 v3, s99
	s_mul_i32 s4, s22, 0xba3
	s_lshr_b32 s5, s4, 31
	s_ashr_i32 s4, s4, 19
	s_add_i32 s5, s4, s5
	s_mul_i32 s4, s5, 0xb0
	s_sub_i32 s4, s22, s4
	s_sext_i32_i16 s4, s4
	s_lshl_b32 s23, s4, 5
	s_cmpk_gt_i32 s4, 0x57
	s_cbranch_scc0 .LBB0_44
	s_lshl_b32 s4, s4, 6
	s_add_i32 s4, s4, 0x7fffea00
	s_and_b32 s4, s4, 0x7fffff00
	s_and_b32 s8, s23, 0x60
	s_or_b32 s4, s8, s4
	s_bitset1_b32 s4, 7
	s_cbranch_execz .LBB0_45
	s_branch .LBB0_46

.LBB0_48:
	v_mov_b64_e32 v[2:3], s[0:1]
	s_load_dwordx2 s[98:99], s[0:1], 0x80
	s_waitcnt vmcnt(0) lgkmcnt(0)
	v_mov_b32_e32 v2, s98
	v_mov_b32_e32 v3, s99
	s_add_i32 s4, s13, 0xffffae00
	s_bfe_u32 s12, s13, 0x10006
	s_mov_b32 s7, 0
	s_lshr_b32 s6, s4, 7
	s_lshl_b32 s10, s12, 19
	s_mov_b32 s11, s7
	s_lshl_b64 s[18:19], s[6:7], 20
	s_lshl_b64 s[6:7], s[6:7], 19
	s_add_u32 s4, s94, s6
	s_addc_u32 s6, s95, s7
	s_add_u32 s8, s4, 0x28a00000
	s_addc_u32 s9, s6, 0
	s_lshl_b32 s6, s13, 5
	s_lshl_b32 s4, s12, 7
	s_lshl_b32 s7, s13, 4
	s_and_b32 s23, s6, 0x60
	s_movk_i32 s5, 0x80
	s_and_b32 s12, s7, 0x3c0
	s_or_b32 s4, s4, s23
	s_waitcnt lgkmcnt(0)
	v_lshl_add_u64 v[2:3], v[2:3], 0, s[18:19]
	v_lshl_add_u64 v[2:3], v[2:3], 0, s[10:11]
	s_mov_b64 s[10:11], 0x400

.LBB0_114:
	s_add_i32 s34, s13, s6
	s_cmpk_lt_i32 s34, 0x5400
	s_cselect_b64 s[20:21], -1, 0
	s_and_b64 s[22:23], s[20:21], exec
	s_cselect_b32 s36, s34, 0x53ff
	s_cmpk_lt_i32 s36, 0x5200
	s_mov_b64 s[38:39], -1
	s_cbranch_scc0 .LBB0_143
	s_mul_hi_i32 s18, s36, 0x63e7063f
	s_lshr_b32 s22, s18, 31
	s_ashr_i32 s18, s18, 12
	s_add_i32 s40, s18, s22
	s_mul_i32 s18, s40, 0x2900
	s_sub_i32 s18, s36, s18
	s_ashr_i32 s41, s40, 31
	s_mul_i32 s23, s40, 0x2a00000
	s_mul_hi_i32 s22, s40, 0x2a00000
	s_add_u32 s38, s5, s23
	s_addc_u32 s39, s7, s22
	s_cmpk_gt_i32 s18, 0xaff
	s_mov_b64 s[42:43], -1
	s_cbranch_scc0 .LBB0_136
	s_cmpk_gt_u32 s18, 0x107f
	s_cbranch_scc0 .LBB0_133
	s_cmpk_gt_u32 s18, 0x167f
	s_cbranch_scc0 .LBB0_130
	s_cmpk_gt_u32 s18, 0x187f
	s_cbranch_scc0 .LBB0_127
	s_cmpk_gt_u32 s18, 0x237f
	s_mov_b64 s[24:25], -1
	s_cbranch_scc0 .LBB0_121
	v_mov_b64_e32 v[34:35], s[0:1]
	s_load_dwordx2 s[98:99], s[0:1], 0xc0
	s_waitcnt vmcnt(0) lgkmcnt(0)
	v_mov_b32_e32 v34, s98
	v_mov_b32_e32 v35, s99
	s_add_u32 s22, s38, 0x2380000
	s_addc_u32 s23, s39, 0
	s_lshl_b32 s24, s18, 5
	s_lshl_b32 s25, s18, 1
	s_and_b32 s37, s24, 0x3e0
	s_and_b32 s24, s25, 0x7fffffc0
	s_add_i32 s26, s24, 0xffffb900
	s_waitcnt lgkmcnt(0)
	v_mad_i64_i32 v[34:35], s[24:25], s40, v110, v[34:35]
	s_mov_b64 s[24:25], 0
.LBB0_121:
	s_andn2_b64 vcc, exec, s[24:25]
	s_cbranch_vccnz .LBB0_274
	v_mov_b64_e32 v[34:35], s[0:1]
	s_load_dwordx2 s[98:99], s[0:1], 0xb8
	s_waitcnt vmcnt(0) lgkmcnt(0)
	v_mov_b32_e32 v34, s98
	v_mov_b32_e32 v35, s99
	s_add_i32 s22, s18, 0xe780
	s_and_b32 s23, s22, 0xffff
	s_mul_i32 s23, s23, 0xba2f
	s_lshr_b32 s24, s23, 23
	s_mul_i32 s23, s24, 0xb0
	s_sub_i32 s22, s22, s23
	s_lshl_b32 s23, s22, 5
	s_and_b32 s37, s23, 0xffe0
	s_and_b32 s22, s22, 0xffff
	s_cmpk_gt_u32 s22, 0x57
	s_mov_b64 s[22:23], -1
	s_cbranch_scc0 .LBB0_124
	s_lshl_b32 s22, s37, 1
	s_add_i32 s22, s22, 0x7fffea00
	s_and_b32 s22, s22, 0x7fffff00
	s_and_b32 s23, s37, 0x60
	s_or_b32 s22, s23, s22
	s_or_b32 s35, s22, 0x80
	s_mov_b64 s[22:23], 0

.LBB0_128:
	v_mov_b64_e32 v[34:35], s[0:1]
	s_load_dwordx2 s[98:99], s[0:1], 0xb0
	s_waitcnt vmcnt(0) lgkmcnt(0)
	v_mov_b32_e32 v34, s98
	v_mov_b32_e32 v35, s99
	s_lshl_b64 s[42:43], s[40:41], 22
	s_add_u32 s22, s38, 0x1680000
	s_addc_u32 s23, s39, 0
	s_lshl_b32 s26, s18, 5
	s_lshl_b32 s35, s18, 1
	s_and_b32 s37, s26, 0x3e0
	s_and_b32 s26, s35, 0x3fc0
	s_mov_b64 s[24:25], 0x400
	s_movk_i32 s27, 0x400
	s_addk_i32 s26, 0xd300
	s_mov_b32 s35, s37
	s_waitcnt lgkmcnt(0)
	v_lshl_add_u64 v[34:35], v[34:35], 0, s[42:43]

.LBB0_130:
	s_andn2_b64 vcc, exec, s[42:43]
	s_cbranch_vccnz .LBB0_132
	v_mov_b64_e32 v[34:35], s[0:1]
	s_load_dwordx2 s[98:99], s[0:1], 0x70
	s_waitcnt vmcnt(0) lgkmcnt(0)
	v_mov_b32_e32 v34, s98
	v_mov_b32_e32 v35, s99
	s_add_i32 s22, s18, 0xef80
	s_and_b32 s23, s22, 0xffff
	s_mul_i32 s23, s23, 0xaaab
	s_lshr_b32 s26, s23, 16
	s_lshr_b32 s23, s23, 22
	s_mulk_i32 s23, 0x60
	s_sub_i32 s35, s22, s23
	s_add_u32 s22, s38, 0x1080000
	s_addc_u32 s23, s39, 0
	s_lshl_b32 s35, s35, 5
	s_and_b32 s37, s35, 0xffe0
	s_mov_b64 s[24:25], 0x400
	s_movk_i32 s27, 0xb28
	s_and_b32 s26, s26, 0xffc0
	s_mov_b32 s35, s37
	s_waitcnt lgkmcnt(0)
	v_mad_i64_i32 v[34:35], s[42:43], s40, v112, v[34:35]

.LBB0_133:
	s_andn2_b64 vcc, exec, s[42:43]
	s_cbranch_vccnz .LBB0_135
	v_mov_b64_e32 v[34:35], s[0:1]
	s_load_dwordx2 s[98:99], s[0:1], 0x68
	s_waitcnt vmcnt(0) lgkmcnt(0)
	v_mov_b32_e32 v34, s98
	v_mov_b32_e32 v35, s99
	s_add_u32 s22, s38, 0xb00000
	s_addc_u32 s23, s39, 0
	s_lshl_b32 s26, s18, 5
	s_lshl_b32 s35, s18, 1
	s_and_b32 s37, s26, 0x3e0
	s_and_b32 s26, s35, 0x3fc0
	s_mov_b64 s[24:25], 0xb00
	s_movk_i32 s27, 0x400
	s_addk_i32 s26, 0xea00
	s_mov_b32 s35, s37
	s_waitcnt lgkmcnt(0)
	v_mad_i64_i32 v[34:35], s[42:43], s40, v110, v[34:35]

.LBB0_136:
	s_andn2_b64 vcc, exec, s[42:43]
	s_cbranch_vccnz .LBB0_142
	v_mov_b64_e32 v[34:35], s[0:1]
	s_load_dwordx2 s[98:99], s[0:1], 0x60
	s_waitcnt vmcnt(0) lgkmcnt(0)
	v_mov_b32_e32 v34, s98
	v_mov_b32_e32 v35, s99
	s_mul_i32 s22, s18, 0xba3
	s_lshr_b32 s23, s22, 31
	s_ashr_i32 s24, s22, 19
	s_add_i32 s24, s24, s23
	s_mul_i32 s22, s24, 0xb0
	s_sub_i32 s18, s18, s22
	s_sext_i32_i16 s18, s18
	s_lshl_b32 s37, s18, 5
	s_cmpk_gt_i32 s18, 0x57
	s_mov_b64 s[22:23], -1
	s_cbranch_scc0 .LBB0_139
	s_lshl_b32 s18, s18, 6
	s_add_i32 s18, s18, 0x7fffea00
	s_and_b32 s18, s18, 0x7fffff00
	s_and_b32 s22, s37, 0x60
	s_or_b32 s18, s22, s18
	s_or_b32 s35, s18, 0x80
	s_mov_b64 s[22:23], 0

.LBB0_143:
	s_andn2_b64 vcc, exec, s[38:39]
	s_cbranch_vccnz .LBB0_145
	v_mov_b64_e32 v[34:35], s[0:1]
	s_load_dwordx2 s[98:99], s[0:1], 0x80
	s_waitcnt vmcnt(0) lgkmcnt(0)
	v_mov_b32_e32 v34, s98
	v_mov_b32_e32 v35, s99
	s_add_i32 s18, s36, 0xffffae00
	s_bfe_u32 s26, s36, 0x10006
	s_lshr_b32 s18, s18, 7
	s_lshl_b32 s24, s26, 19
	s_lshl_b64 s[38:39], s[18:19], 20
	s_lshl_b64 s[22:23], s[18:19], 19
	s_add_u32 s22, s28, s22
	s_addc_u32 s23, s29, s23
	s_lshl_b32 s18, s26, 7
	s_lshl_b32 s26, s36, 5
	s_mov_b32 s25, s19
	s_lshl_b32 s35, s36, 4
	s_and_b32 s37, s26, 0x60
	s_movk_i32 s27, 0x80
	s_and_b32 s26, s35, 0x3c0
	s_or_b32 s35, s18, s37
	s_waitcnt lgkmcnt(0)
	v_lshl_add_u64 v[34:35], v[34:35], 0, s[38:39]
	v_lshl_add_u64 v[34:35], v[34:35], 0, s[24:25]
	s_mov_b64 s[24:25], 0x400

.LBB0_177:
	s_or_b64 exec, exec, s[38:39]
	v_add_u32_e32 v146, 0x400, v113
	v_add_u32_e32 v147, 0x800, v113
	v_add_u32_e32 v148, 0xc00, v113
	v_add_u32_e32 v149, 0x1000, v113
	v_add_u32_e32 v150, 0x1400, v113
	v_add_u32_e32 v151, 0x1800, v113
	v_add_u32_e32 v152, 0x1c00, v113
	s_waitcnt vmcnt(0)
	ds_write2_b32 v113, v2, v3 offset1:66
	ds_write2_b32 v113, v4, v5 offset0:132 offset1:198
	ds_write2_b32 v146, v6, v7 offset0:8 offset1:74
	ds_write2_b32 v146, v8, v9 offset0:140 offset1:206
	ds_write2_b32 v147, v10, v11 offset0:16 offset1:82
	ds_write2_b32 v147, v12, v13 offset0:148 offset1:214
	ds_write2_b32 v148, v14, v15 offset0:24 offset1:90
	ds_write2_b32 v148, v16, v17 offset0:156 offset1:222
	ds_write2_b32 v149, v18, v19 offset0:32 offset1:98
	ds_write2_b32 v149, v20, v21 offset0:164 offset1:230
	ds_write2_b32 v150, v22, v23 offset0:40 offset1:106
	ds_write2_b32 v150, v24, v25 offset0:172 offset1:238
	ds_write2_b32 v151, v26, v27 offset0:48 offset1:114
	ds_write2_b32 v151, v28, v29 offset0:180 offset1:246
	ds_write2_b32 v152, v30, v31 offset0:56 offset1:122
	ds_write2_b32 v152, v32, v33 offset0:188 offset1:254
	s_waitcnt lgkmcnt(0)
	ds_read2_b32 v[6:7], v106 offset1:8
	ds_read2_b32 v[8:9], v106 offset0:33 offset1:41
	ds_read2_b32 v[10:11], v106 offset0:66 offset1:74
	ds_read2_b32 v[12:13], v106 offset0:99 offset1:107
	ds_read2_b32 v[14:15], v106 offset0:132 offset1:140
	s_waitcnt lgkmcnt(4)
	s_waitcnt lgkmcnt(3)
	ds_read2_b32 v[16:17], v106 offset0:165 offset1:173
	v_cvt_pk_bf16_f32 v2, v6, v8
	s_waitcnt lgkmcnt(3)
	s_waitcnt lgkmcnt(2)
	ds_read2_b32 v[18:19], v106 offset0:198 offset1:206
	ds_read2_b32 v[20:21], v106 offset0:231 offset1:239
	v_cvt_pk_bf16_f32 v3, v10, v12
	s_waitcnt lgkmcnt(3)
	s_waitcnt lgkmcnt(2)
	v_cvt_pk_bf16_f32 v4, v14, v16
	s_waitcnt lgkmcnt(1)
	s_waitcnt lgkmcnt(0)
	v_cvt_pk_bf16_f32 v5, v18, v20
	v_add_u32_e32 v6, s4, v105
	v_ashrrev_i32_e32 v8, 31, v6
	v_mul_lo_u32 v8, s10, v8
	v_mul_lo_u32 v10, s11, v6
	v_mad_u64_u32 v[22:23], s[36:37], s10, v6, 0
	s_add_i32 s18, s30, s13
	v_add3_u32 v23, v23, v8, v10
	s_ashr_i32 s13, s12, 31
	v_lshl_add_u64 v[22:23], v[22:23], 1, s[8:9]
	s_lshl_b64 s[12:13], s[12:13], 1
	v_lshl_add_u64 v[22:23], v[22:23], 0, s[12:13]
	v_lshl_add_u64 v[22:23], v[22:23], 0, v[100:101]
	global_store_dwordx4 v[22:23], v[2:5], off
	s_nop 1
	v_cvt_pk_bf16_f32 v2, v7, v9
	v_cvt_pk_bf16_f32 v3, v11, v13
	v_cvt_pk_bf16_f32 v4, v15, v17
	v_cvt_pk_bf16_f32 v5, v19, v21
	v_add_u32_e32 v6, s4, v107
	v_ashrrev_i32_e32 v7, 31, v6
	v_mul_lo_u32 v8, s10, v7
	v_mul_lo_u32 v9, s11, v6
	v_mad_u64_u32 v[6:7], s[36:37], s10, v6, 0
	v_add3_u32 v7, v7, v8, v9
	v_lshl_add_u64 v[6:7], v[6:7], 1, s[8:9]
	v_lshl_add_u64 v[6:7], v[6:7], 0, s[12:13]
	ds_read2_b32 v[8:9], v106 offset0:16 offset1:24
	v_lshl_add_u64 v[6:7], v[6:7], 0, v[100:101]
	global_store_dwordx4 v[6:7], v[2:5], off
	ds_read2_b32 v[6:7], v106 offset0:49 offset1:57
	ds_read2_b32 v[10:11], v106 offset0:82 offset1:90
	ds_read2_b32 v[12:13], v106 offset0:115 offset1:123
	s_waitcnt lgkmcnt(3)
	s_waitcnt lgkmcnt(2)
	ds_read2_b32 v[14:15], v106 offset0:148 offset1:156
	ds_read2_b32 v[16:17], v106 offset0:181 offset1:189
	v_cvt_pk_bf16_f32 v2, v8, v6
	s_waitcnt lgkmcnt(3)
	s_waitcnt lgkmcnt(2)
	ds_read2_b32 v[18:19], v106 offset0:214 offset1:222
	ds_read2_b32 v[20:21], v106 offset0:247 offset1:255
	v_cvt_pk_bf16_f32 v3, v10, v12
	s_waitcnt lgkmcnt(3)
	s_waitcnt lgkmcnt(2)
	v_cvt_pk_bf16_f32 v4, v14, v16
	s_waitcnt lgkmcnt(1)
	s_waitcnt lgkmcnt(0)
	v_cvt_pk_bf16_f32 v5, v18, v20
	v_add_u32_e32 v6, s4, v108
	v_ashrrev_i32_e32 v8, 31, v6
	v_mul_lo_u32 v8, s10, v8
	v_mul_lo_u32 v10, s11, v6
	v_mad_u64_u32 v[22:23], s[36:37], s10, v6, 0
	v_add3_u32 v23, v23, v8, v10
	v_lshl_add_u64 v[22:23], v[22:23], 1, s[8:9]
	v_lshl_add_u64 v[22:23], v[22:23], 0, s[12:13]
	v_lshl_add_u64 v[22:23], v[22:23], 0, v[100:101]
	global_store_dwordx4 v[22:23], v[2:5], off
	s_nop 1
	v_cvt_pk_bf16_f32 v2, v9, v7
	v_cvt_pk_bf16_f32 v3, v11, v13
	v_cvt_pk_bf16_f32 v4, v15, v17
	v_cvt_pk_bf16_f32 v5, v19, v21
	v_add_u32_e32 v6, s4, v109
	v_ashrrev_i32_e32 v7, 31, v6
	v_mul_lo_u32 v8, s10, v7
	v_mul_lo_u32 v9, s11, v6
	v_mad_u64_u32 v[6:7], s[10:11], s10, v6, 0
	v_add3_u32 v7, v7, v8, v9
	v_lshl_add_u64 v[6:7], v[6:7], 1, s[8:9]
	v_lshl_add_u64 v[6:7], v[6:7], 0, s[12:13]
	v_lshl_add_u64 v[6:7], v[6:7], 0, v[100:101]
	global_store_dwordx4 v[6:7], v[2:5], off
	s_waitcnt lgkmcnt(0)
	s_min_i32 s27, s18, 0x53ff
	s_cmpk_lt_i32 s18, 0x5200
	s_mov_b64 s[38:39], -1
	s_cbranch_scc0 .LBB0_206
	s_mul_hi_i32 s4, s27, 0x63e7063f
	s_lshr_b32 s8, s4, 31
	s_ashr_i32 s4, s4, 12
	s_add_i32 s40, s4, s8
	s_mul_i32 s4, s40, 0x2900
	s_sub_i32 s18, s27, s4
	s_ashr_i32 s41, s40, 31
	s_mul_i32 s8, s40, 0x2a00000
	s_mul_hi_i32 s4, s40, 0x2a00000
	s_add_u32 s38, s5, s8
	s_addc_u32 s39, s7, s4
	s_cmpk_gt_i32 s18, 0xaff
	s_mov_b64 s[42:43], -1
	s_cbranch_scc0 .LBB0_199
	s_cmpk_gt_u32 s18, 0x107f
	s_cbranch_scc0 .LBB0_196
	s_cmpk_gt_u32 s18, 0x167f
	s_cbranch_scc0 .LBB0_193
	s_cmpk_gt_u32 s18, 0x187f
	s_cbranch_scc0 .LBB0_190
	s_cmpk_gt_u32 s18, 0x237f
	s_mov_b64 s[10:11], -1
	s_cbranch_scc0 .LBB0_184
	v_mov_b64_e32 v[2:3], s[0:1]
	s_load_dwordx2 s[98:99], s[0:1], 0xc0
	s_waitcnt vmcnt(0) lgkmcnt(0)
	v_mov_b32_e32 v2, s98
	v_mov_b32_e32 v3, s99
	s_add_u32 s8, s38, 0x2380000
	s_addc_u32 s9, s39, 0
	s_lshl_b32 s4, s18, 5
	s_lshl_b32 s10, s18, 1
	s_and_b32 s36, s4, 0x3e0
	s_and_b32 s4, s10, 0x7fffffc0
	s_add_i32 s12, s4, 0xffffb900
	s_waitcnt lgkmcnt(0)
	v_mad_i64_i32 v[34:35], s[10:11], s40, v110, v[2:3]
	s_mov_b64 s[10:11], 0
.LBB0_184:
	s_andn2_b64 vcc, exec, s[10:11]
	s_cbranch_vccnz .LBB0_275
	v_mov_b64_e32 v[2:3], s[0:1]
	s_load_dwordx2 s[98:99], s[0:1], 0xb8
	s_waitcnt vmcnt(0) lgkmcnt(0)
	v_mov_b32_e32 v2, s98
	v_mov_b32_e32 v3, s99
	s_add_i32 s4, s18, 0xe780
	s_and_b32 s8, s4, 0xffff
	s_mul_i32 s8, s8, 0xba2f
	s_lshr_b32 s10, s8, 23
	s_mul_i32 s8, s10, 0xb0
	s_sub_i32 s4, s4, s8
	s_lshl_b32 s8, s4, 5
	s_and_b32 s36, s8, 0xffe0
	s_and_b32 s4, s4, 0xffff
	s_cmpk_gt_u32 s4, 0x57
	s_mov_b64 s[8:9], -1
	s_cbranch_scc0 .LBB0_187
	s_lshl_b32 s4, s36, 1
	s_add_i32 s4, s4, 0x7fffea00
	s_and_b32 s4, s4, 0x7fffff00
	s_and_b32 s8, s36, 0x60
	s_or_b32 s4, s8, s4
	s_bitset1_b32 s4, 7
	s_mov_b64 s[8:9], 0

.LBB0_191:
	v_mov_b64_e32 v[2:3], s[0:1]
	s_load_dwordx2 s[98:99], s[0:1], 0xb0
	s_waitcnt vmcnt(0) lgkmcnt(0)
	v_mov_b32_e32 v2, s98
	v_mov_b32_e32 v3, s99
	s_lshl_b64 s[42:43], s[40:41], 22
	s_add_u32 s8, s38, 0x1680000
	s_addc_u32 s9, s39, 0
	s_lshl_b32 s4, s18, 5
	s_lshl_b32 s12, s18, 1
	s_and_b32 s36, s4, 0x3e0
	s_and_b32 s4, s12, 0x3fc0
	s_mov_b64 s[10:11], 0x400
	s_movk_i32 s13, 0x400
	s_add_i32 s12, s4, 0xffffd300
	s_mov_b32 s4, s36
	s_waitcnt lgkmcnt(0)
	v_lshl_add_u64 v[34:35], v[2:3], 0, s[42:43]

.LBB0_193:
	s_andn2_b64 vcc, exec, s[42:43]
	s_cbranch_vccnz .LBB0_195
	v_mov_b64_e32 v[2:3], s[0:1]
	s_load_dwordx2 s[98:99], s[0:1], 0x70
	s_waitcnt vmcnt(0) lgkmcnt(0)
	v_mov_b32_e32 v2, s98
	v_mov_b32_e32 v3, s99
	s_add_i32 s4, s18, 0xef80
	s_and_b32 s8, s4, 0xffff
	s_mul_i32 s8, s8, 0xaaab
	s_lshr_b32 s12, s8, 16
	s_lshr_b32 s8, s8, 22
	s_mulk_i32 s8, 0x60
	s_sub_i32 s4, s4, s8
	s_add_u32 s8, s38, 0x1080000
	s_addc_u32 s9, s39, 0
	s_lshl_b32 s4, s4, 5
	s_and_b32 s36, s4, 0xffe0
	s_mov_b64 s[10:11], 0x400
	s_movk_i32 s13, 0xb28
	s_and_b32 s12, s12, 0xffc0
	s_mov_b32 s4, s36
	s_waitcnt lgkmcnt(0)
	v_mad_i64_i32 v[34:35], s[42:43], s40, v112, v[2:3]

.LBB0_196:
	s_andn2_b64 vcc, exec, s[42:43]
	s_cbranch_vccnz .LBB0_198
	v_mov_b64_e32 v[2:3], s[0:1]
	s_load_dwordx2 s[98:99], s[0:1], 0x68
	s_waitcnt vmcnt(0) lgkmcnt(0)
	v_mov_b32_e32 v2, s98
	v_mov_b32_e32 v3, s99
	s_add_u32 s8, s38, 0xb00000
	s_addc_u32 s9, s39, 0
	s_lshl_b32 s4, s18, 5
	s_lshl_b32 s12, s18, 1
	s_and_b32 s36, s4, 0x3e0
	s_and_b32 s4, s12, 0x3fc0
	s_mov_b64 s[10:11], 0xb00
	s_movk_i32 s13, 0x400
	s_add_i32 s12, s4, 0xffffea00
	s_mov_b32 s4, s36
	s_waitcnt lgkmcnt(0)
	v_mad_i64_i32 v[34:35], s[42:43], s40, v110, v[2:3]

.LBB0_199:
	s_andn2_b64 vcc, exec, s[42:43]
	s_cbranch_vccnz .LBB0_205
	v_mov_b64_e32 v[2:3], s[0:1]
	s_load_dwordx2 s[98:99], s[0:1], 0x60
	s_waitcnt vmcnt(0) lgkmcnt(0)
	v_mov_b32_e32 v2, s98
	v_mov_b32_e32 v3, s99
	s_mul_i32 s4, s18, 0xba3
	s_lshr_b32 s8, s4, 31
	s_ashr_i32 s10, s4, 19
	s_add_i32 s10, s10, s8
	s_mul_i32 s4, s10, 0xb0
	s_sub_i32 s4, s18, s4
	s_sext_i32_i16 s11, s4
	s_lshl_b32 s36, s11, 5
	s_cmpk_gt_i32 s11, 0x57
	s_mov_b64 s[8:9], -1
	s_cbranch_scc0 .LBB0_202
	s_lshl_b32 s4, s11, 6
	s_add_i32 s4, s4, 0x7fffea00
	s_and_b32 s4, s4, 0x7fffff00
	s_and_b32 s8, s36, 0x60
	s_or_b32 s4, s8, s4
	s_bitset1_b32 s4, 7
	s_mov_b64 s[8:9], 0

.LBB0_206:
	s_andn2_b64 vcc, exec, s[38:39]
	s_cbranch_vccnz .LBB0_208
	v_mov_b64_e32 v[2:3], s[0:1]
	s_load_dwordx2 s[98:99], s[0:1], 0x80
	s_waitcnt vmcnt(0) lgkmcnt(0)
	v_mov_b32_e32 v2, s98
	v_mov_b32_e32 v3, s99
	s_add_i32 s4, s27, 0xffffae00
	s_bfe_u32 s12, s27, 0x10006
	s_lshr_b32 s18, s4, 7
	s_lshl_b32 s10, s12, 19
	s_lshl_b64 s[38:39], s[18:19], 20
	s_lshl_b64 s[8:9], s[18:19], 19
	s_add_u32 s8, s28, s8
	s_addc_u32 s9, s29, s9
	s_lshl_b32 s4, s12, 7
	s_lshl_b32 s12, s27, 5
	s_mov_b32 s11, s19
	s_lshl_b32 s18, s27, 4
	s_and_b32 s36, s12, 0x60
	s_movk_i32 s13, 0x80
	s_and_b32 s12, s18, 0x3c0
	s_or_b32 s4, s4, s36
	s_waitcnt lgkmcnt(0)
	v_lshl_add_u64 v[2:3], v[2:3], 0, s[38:39]
	v_lshl_add_u64 v[34:35], v[2:3], 0, s[10:11]
	s_mov_b64 s[10:11], 0x400

.LBB0_279:
	s_add_i32 s4, s6, 0xffffff80
	s_cmp_ge_i32 s2, s4
	s_cbranch_scc0 .LBB0_283
	s_waitcnt vmcnt(0)
	v_mov_b64_e32 v[2:3], s[0:1]
	s_load_dwordx2 s[98:99], s[0:1], 0x78
	s_waitcnt vmcnt(0) lgkmcnt(0)
	v_mov_b32_e32 v4, s98
	v_mov_b32_e32 v5, s99
	s_load_dwordx2 s[98:99], s[0:1], 0x80
	s_waitcnt vmcnt(0) lgkmcnt(0)
	v_mov_b32_e32 v6, s98
	v_mov_b32_e32 v7, s99
	s_sub_i32 s4, s2, s4
	s_mov_b32 s7, 0
	s_lshr_b32 s6, s4, 5
	s_and_b32 s4, s4, 31
	s_lshl_b64 s[22:23], s[6:7], 20
	s_mov_b32 s19, s7
	s_lshl_b64 s[20:21], s[6:7], 13
	s_lshl_b32 s18, s4, 15
	v_mov_b32_e32 v3, 0
	v_lshlrev_b32_e32 v2, 2, v98
	s_mov_b32 s13, s7
	s_lshl_b32 s12, s4, 8
	s_mov_b64 s[8:9], 0
	s_movk_i32 s2, 0x1000
	s_mov_b64 s[10:11], 0x2000
	s_waitcnt lgkmcnt(0)
	v_lshl_add_u64 v[4:5], v[4:5], 0, s[20:21]
	v_lshl_add_u64 v[6:7], v[6:7], 0, s[22:23]
	v_lshl_add_u64 v[6:7], v[6:7], 0, s[18:19]
	v_lshl_add_u64 v[4:5], v[4:5], 0, s[12:13]
	v_lshl_add_u64 v[6:7], v[6:7], 0, v[2:3]
	v_mov_b32_e32 v2, v3

.LBB0_283:
	s_waitcnt vmcnt(0)
	v_mov_b64_e32 v[2:3], s[0:1]
	s_load_dwordx2 s[98:99], s[0:1], 0x10
	s_waitcnt vmcnt(0) lgkmcnt(0)
	v_mov_b32_e32 v4, s98
	v_mov_b32_e32 v5, s99
	s_load_dwordx2 s[98:99], s[0:1], 0x18
	s_waitcnt vmcnt(0) lgkmcnt(0)
	v_mov_b32_e32 v6, s98
	v_mov_b32_e32 v7, s99
	s_load_dwordx2 s[98:99], s[0:1], 0x48
	s_waitcnt vmcnt(0) lgkmcnt(0)
	v_mov_b32_e32 v8, s98
	v_mov_b32_e32 v9, s99
	s_and_b32 s4, s60, 0x7f
	s_mul_i32 s4, s4, 9
	s_lshr_b32 s8, s4, 1
	s_add_i32 s4, s4, 9
	s_ashr_i32 s2, s60, 7
	v_min_i32_e32 v16, 0xff, v0
	s_lshr_b32 s4, s4, 1
	s_add_i32 s3, s3, s8
	v_lshrrev_b32_e32 v22, 4, v16
	s_cmp_lt_u32 s3, s4
	s_movk_i32 s5, 0x200
	v_or_b32_e32 v22, 0x80, v22
	s_cselect_b64 s[12:13], -1, 0
	v_mov_b32_e32 v19, 0
	v_lshrrev_b32_e32 v27, 4, v0
	v_or_b32_e32 v13, 0x200, v0
	v_or_b32_e32 v14, 0x600, v0
	v_lshlrev_b32_e32 v16, 2, v16
	v_cmp_gt_u32_e32 vcc, s5, v0
	v_min_u32_e32 v22, 0x81, v22
	s_and_b64 s[4:5], s[12:13], exec
	v_mov_b32_e32 v24, 0x2400000
	v_lshlrev_b32_e32 v12, 4, v0
	v_lshlrev_b32_e32 v10, 12, v27
	v_lshrrev_b32_e32 v28, 4, v13
	v_lshrrev_b32_e32 v73, 4, v14
	v_mov_b32_e32 v23, v19
	v_and_b32_e32 v26, 60, v16
	v_lshlrev_b32_e32 v22, 12, v22
	s_cselect_b32 s3, s3, s8
	v_and_b32_e32 v72, 15, v0
	s_mov_b32 s19, 0
	v_mov_b32_e32 v11, v19
	v_and_b32_e32 v20, 0xf0, v12
	v_mov_b32_e32 v13, v19
	v_mov_b32_e32 v15, v19
	v_mov_b32_e32 v59, v19
	v_lshlrev_b32_e32 v12, 12, v28
	v_or_b32_e32 v14, 0x40000, v10
	v_or_b32_e32 v25, 0xffffff80, v73
	v_lshlrev_b32_e32 v58, 2, v26
	s_lshl_b32 s18, s3, 4
	v_lshrrev_b32_e32 v1, 4, v98
	s_mov_b32 s6, 0xfff80000
	v_lshlrev_b32_e32 v2, 2, v72
	v_mov_b32_e32 v3, v19
	v_cndmask_b32_e32 v16, v25, v73, vcc
	v_mul_u32_u24_e32 v18, 0x48000, v1
	s_mov_b32 s7, 0x9000
	s_mov_b32 s3, 0x12000
	v_mov_b32_e32 v21, v19
	v_mov_b32_e32 v17, v19
	v_lshlrev_b64 v[16:17], 12, v[16:17]
	s_waitcnt lgkmcnt(0)
	s_barrier
	v_and_b32_e32 v74, 0x78, v99
	v_lshl_add_u64 v[60:61], v[4:5], 0, v[22:23]
	v_lshl_add_u64 v[10:11], v[6:7], 0, v[10:11]
	v_mad_i64_i32 v[8:9], s[4:5], s2, v24, v[8:9]
	v_lshl_add_u64 v[12:13], v[6:7], 0, v[12:13]
	v_lshl_add_u64 v[14:15], v[6:7], 0, v[14:15]
	v_cndmask_b32_e32 v7, v5, v7, vcc
	v_cndmask_b32_e32 v6, v4, v6, vcc
	v_lshl_add_u64 v[4:5], s[18:19], 2, v[8:9]
	v_lshl_add_u64 v[24:25], v[60:61], 0, v[58:59]
	v_lshl_add_u64 v[30:31], v[4:5], 0, v[2:3]
	v_add_co_u32_e32 v2, vcc, s6, v24
	v_lshl_add_u64 v[70:71], v[30:31], 0, v[18:19]
	s_nop 0
	v_addc_co_u32_e32 v3, vcc, -1, v25, vcc
	v_add_co_u32_e32 v30, vcc, s7, v70
	v_lshl_add_u64 v[66:67], v[10:11], 0, v[20:21]
	s_nop 0
	v_addc_co_u32_e32 v31, vcc, 0, v71, vcc
	v_add_co_u32_e32 v32, vcc, s3, v70
	s_mov_b32 s3, 0x1b000
	s_nop 0
	v_addc_co_u32_e32 v33, vcc, 0, v71, vcc
	v_add_co_u32_e32 v34, vcc, s3, v70
	s_mov_b32 s3, 0x24000
	s_nop 0
	v_addc_co_u32_e32 v35, vcc, 0, v71, vcc
	v_lshl_add_u64 v[62:63], v[12:13], 0, v[20:21]
	v_lshl_add_u64 v[64:65], v[14:15], 0, v[20:21]
	v_lshl_add_u64 v[22:23], v[6:7], 0, v[16:17]
	global_load_dwordx4 v[14:17], v[66:67], off
	global_load_dwordx4 v[10:13], v[62:63], off
	global_load_dwordx4 v[6:9], v[64:65], off
	v_add_co_u32_e32 v36, vcc, s3, v70
	s_mov_b32 s3, 0x2d000
	s_nop 0
	v_addc_co_u32_e32 v37, vcc, 0, v71, vcc
	v_add_co_u32_e32 v38, vcc, s3, v70
	s_mov_b32 s3, 0x36000
	s_nop 0
	v_addc_co_u32_e32 v39, vcc, 0, v71, vcc
	v_add_co_u32_e32 v40, vcc, s3, v70
	s_mov_b32 s3, 0x3f000
	s_nop 0
	v_addc_co_u32_e32 v41, vcc, 0, v71, vcc
	v_add_co_u32_e32 v42, vcc, s3, v70
	s_mov_b32 s3, 0x120000
	s_nop 0
	v_addc_co_u32_e32 v43, vcc, 0, v71, vcc
	v_add_co_u32_e32 v44, vcc, s3, v70
	s_mov_b32 s3, 0x129000
	s_nop 0
	v_addc_co_u32_e32 v45, vcc, 0, v71, vcc
	v_lshl_add_u64 v[68:69], v[22:23], 0, v[20:21]
	global_load_dwordx4 v[2:5], v[2:3], off
	s_waitcnt vmcnt(3)
	v_mul_f32_e32 v29, 0xbfb8aa3b, v14
	global_load_dword v20, v[70:71], off nt
	global_load_dword v26, v[30:31], off nt
	global_load_dword v25, v[32:33], off nt
	global_load_dword v24, v[34:35], off nt
	global_load_dword v23, v[36:37], off nt
	global_load_dword v22, v[38:39], off nt
	global_load_dword v21, v[40:41], off nt
	global_load_dword v18, v[42:43], off nt
	global_load_dword v117, v[44:45], off nt
	v_add_co_u32_e32 v30, vcc, s3, v70
	s_mov_b32 s3, 0x132000
	s_nop 0
	v_addc_co_u32_e32 v31, vcc, 0, v71, vcc
	v_add_co_u32_e32 v32, vcc, s3, v70
	s_mov_b32 s3, 0x13b000
	s_nop 0
	v_addc_co_u32_e32 v33, vcc, 0, v71, vcc
	v_add_co_u32_e32 v34, vcc, s3, v70
	s_mov_b32 s3, 0x144000
	s_nop 0
	v_addc_co_u32_e32 v35, vcc, 0, v71, vcc
	v_add_co_u32_e32 v36, vcc, s3, v70
	s_mov_b32 s3, 0x14d000
	s_nop 0
	v_addc_co_u32_e32 v37, vcc, 0, v71, vcc
	v_add_co_u32_e32 v38, vcc, s3, v70
	s_mov_b32 s3, 0x156000
	s_nop 0
	v_addc_co_u32_e32 v39, vcc, 0, v71, vcc
	v_add_co_u32_e32 v40, vcc, s3, v70
	s_mov_b32 s3, 0x15f000
	s_nop 0
	v_addc_co_u32_e32 v41, vcc, 0, v71, vcc
	v_add_co_u32_e32 v42, vcc, s3, v70
	s_mov_b32 s3, 0x240000
	s_nop 0
	v_addc_co_u32_e32 v43, vcc, 0, v71, vcc
	v_add_co_u32_e32 v44, vcc, s3, v70
	s_mov_b32 s3, 0x249000
	s_nop 0
	v_addc_co_u32_e32 v45, vcc, 0, v71, vcc
	global_load_dword v135, v[30:31], off nt
	global_load_dword v132, v[32:33], off nt
	global_load_dword v129, v[34:35], off nt
	global_load_dword v126, v[36:37], off nt
	global_load_dword v123, v[38:39], off nt
	global_load_dword v120, v[40:41], off nt
	global_load_dword v113, v[42:43], off nt
	global_load_dword v85, v[44:45], off nt
	v_add_co_u32_e32 v30, vcc, s3, v70
	s_mov_b32 s3, 0x252000
	s_nop 0
	v_addc_co_u32_e32 v31, vcc, 0, v71, vcc
	v_add_co_u32_e32 v32, vcc, s3, v70
	s_mov_b32 s3, 0x25b000
	s_nop 0
	v_addc_co_u32_e32 v33, vcc, 0, v71, vcc
	v_add_co_u32_e32 v34, vcc, s3, v70
	s_mov_b32 s3, 0x264000
	s_nop 0
	v_addc_co_u32_e32 v35, vcc, 0, v71, vcc
	v_add_co_u32_e32 v36, vcc, s3, v70
	s_mov_b32 s3, 0x26d000
	s_nop 0
	v_addc_co_u32_e32 v37, vcc, 0, v71, vcc
	v_add_co_u32_e32 v38, vcc, s3, v70
	s_mov_b32 s3, 0x276000
	s_nop 0
	v_addc_co_u32_e32 v39, vcc, 0, v71, vcc
	v_add_co_u32_e32 v40, vcc, s3, v70
	s_mov_b32 s3, 0x27f000
	s_nop 0
	v_addc_co_u32_e32 v41, vcc, 0, v71, vcc
	v_add_co_u32_e32 v42, vcc, s3, v70
	s_mov_b32 s3, 0x360000
	s_nop 0
	v_addc_co_u32_e32 v43, vcc, 0, v71, vcc
	v_add_co_u32_e32 v44, vcc, s3, v70
	s_mov_b32 s3, 0x369000
	s_nop 0
	v_addc_co_u32_e32 v45, vcc, 0, v71, vcc
	global_load_dword v110, v[30:31], off nt
	global_load_dword v106, v[32:33], off nt
	global_load_dword v102, v[34:35], off nt
	global_load_dword v97, v[36:37], off nt
	global_load_dword v92, v[38:39], off nt
	global_load_dword v89, v[40:41], off nt
	global_load_dword v80, v[42:43], off nt
	global_load_dword v121, v[44:45], off nt
	v_add_co_u32_e32 v30, vcc, s3, v70
	s_mov_b32 s3, 0x372000
	s_nop 0
	v_addc_co_u32_e32 v31, vcc, 0, v71, vcc
	v_add_co_u32_e32 v32, vcc, s3, v70
	s_mov_b32 s3, 0x37b000
	s_nop 0
	v_addc_co_u32_e32 v33, vcc, 0, v71, vcc
	v_add_co_u32_e32 v34, vcc, s3, v70
	s_mov_b32 s3, 0x384000
	s_nop 0
	v_addc_co_u32_e32 v35, vcc, 0, v71, vcc
	v_add_co_u32_e32 v36, vcc, s3, v70
	s_mov_b32 s3, 0x38d000
	s_nop 0
	v_addc_co_u32_e32 v37, vcc, 0, v71, vcc
	v_add_co_u32_e32 v38, vcc, s3, v70
	s_mov_b32 s3, 0x396000
	s_nop 0
	v_addc_co_u32_e32 v39, vcc, 0, v71, vcc
	v_add_co_u32_e32 v40, vcc, s3, v70
	s_mov_b32 s3, 0x39f000
	s_nop 0
	v_addc_co_u32_e32 v41, vcc, 0, v71, vcc
	v_add_co_u32_e32 v42, vcc, s3, v70
	s_mov_b32 s3, 0x480000
	s_nop 0
	v_addc_co_u32_e32 v43, vcc, 0, v71, vcc
	v_add_co_u32_e32 v44, vcc, s3, v70
	s_mov_b32 s3, 0x489000
	s_nop 0
	v_addc_co_u32_e32 v45, vcc, 0, v71, vcc
	global_load_dword v137, v[30:31], off nt
	global_load_dword v136, v[32:33], off nt
	global_load_dword v133, v[34:35], off nt
	global_load_dword v130, v[36:37], off nt
	global_load_dword v127, v[38:39], off nt
	global_load_dword v125, v[40:41], off nt
	global_load_dword v118, v[42:43], off nt
	global_load_dword v86, v[44:45], off nt
	v_add_co_u32_e32 v30, vcc, s3, v70
	s_mov_b32 s3, 0x492000
	s_nop 0
	v_addc_co_u32_e32 v31, vcc, 0, v71, vcc
	v_add_co_u32_e32 v32, vcc, s3, v70
	s_mov_b32 s3, 0x49b000
	s_nop 0
	v_addc_co_u32_e32 v33, vcc, 0, v71, vcc
	v_add_co_u32_e32 v34, vcc, s3, v70
	s_mov_b32 s3, 0x4a4000
	s_nop 0
	v_addc_co_u32_e32 v35, vcc, 0, v71, vcc
	v_add_co_u32_e32 v36, vcc, s3, v70
	s_mov_b32 s3, 0x4ad000
	s_nop 0
	v_addc_co_u32_e32 v37, vcc, 0, v71, vcc
	v_add_co_u32_e32 v38, vcc, s3, v70
	s_mov_b32 s3, 0x4b6000
	s_nop 0
	v_addc_co_u32_e32 v39, vcc, 0, v71, vcc
	v_add_co_u32_e32 v40, vcc, s3, v70
	s_mov_b32 s3, 0x4bf000
	s_nop 0
	v_addc_co_u32_e32 v41, vcc, 0, v71, vcc
	v_add_co_u32_e32 v42, vcc, s3, v70
	s_mov_b32 s3, 0x5a0000
	s_nop 0
	v_addc_co_u32_e32 v43, vcc, 0, v71, vcc
	v_add_co_u32_e32 v44, vcc, s3, v70
	s_mov_b32 s3, 0x5a9000
	s_nop 0
	v_addc_co_u32_e32 v45, vcc, 0, v71, vcc
	global_load_dword v115, v[30:31], off nt
	global_load_dword v111, v[32:33], off nt
	global_load_dword v107, v[34:35], off nt
	global_load_dword v103, v[36:37], off nt
	global_load_dword v95, v[38:39], off nt
	global_load_dword v90, v[40:41], off nt
	global_load_dword v83, v[42:43], off nt
	global_load_dword v87, v[44:45], off nt
	v_add_co_u32_e32 v30, vcc, s3, v70
	s_mov_b32 s3, 0x5b2000
	s_nop 0
	v_addc_co_u32_e32 v31, vcc, 0, v71, vcc
	v_add_co_u32_e32 v32, vcc, s3, v70
	s_mov_b32 s3, 0x5bb000
	s_nop 0
	v_addc_co_u32_e32 v33, vcc, 0, v71, vcc
	v_add_co_u32_e32 v34, vcc, s3, v70
	s_mov_b32 s3, 0x5c4000
	s_nop 0
	v_addc_co_u32_e32 v35, vcc, 0, v71, vcc
	v_exp_f32_e32 v29, v29
	v_add_co_u32_e32 v36, vcc, s3, v70
	s_mov_b32 s3, 0x5cd000
	s_nop 0
	v_addc_co_u32_e32 v37, vcc, 0, v71, vcc
	v_add_co_u32_e32 v38, vcc, s3, v70
	s_mov_b32 s3, 0x5d6000
	s_nop 0
	v_addc_co_u32_e32 v39, vcc, 0, v71, vcc
	v_add_f32_e32 v29, 1.0, v29
	v_add_co_u32_e32 v40, vcc, s3, v70
	s_nop 0
	v_addc_co_u32_e32 v41, vcc, 0, v71, vcc
	s_mov_b32 s3, 0x5df000
	v_add_co_u32_e32 v42, vcc, s3, v70
	s_movk_i32 s3, 0x90
	s_nop 0
	v_addc_co_u32_e32 v43, vcc, 0, v71, vcc
	global_load_dword v112, v[30:31], off nt
	global_load_dword v108, v[32:33], off nt
	global_load_dword v104, v[34:35], off nt
	global_load_dword v100, v[36:37], off nt
	global_load_dword v93, v[38:39], off nt
	global_load_dword v91, v[40:41], off nt
	global_load_dword v81, v[42:43], off nt
	v_mul_f32_e32 v32, 0xbfb8aa3b, v15
	v_exp_f32_e32 v32, v32
	s_nop 0
	v_add_f32_e32 v32, 1.0, v32
	v_mul_f32_e32 v31, 0xbfb8aa3b, v16
	v_rcp_f32_e32 v30, v29
	s_nop 0
	v_mul_f32_e32 v29, v14, v30
	v_exp_f32_e32 v31, v31
	s_nop 0
	v_add_f32_e32 v31, 1.0, v31
	v_rcp_f32_e32 v14, v32
	s_nop 0
	v_mul_f32_e32 v30, v15, v14
	v_mul_f32_e32 v32, 0xbfb8aa3b, v17
	v_exp_f32_e32 v32, v32
	s_nop 0
	v_add_f32_e32 v32, 1.0, v32
	v_rcp_f32_e32 v14, v31
	s_nop 0
	v_mul_f32_e32 v31, v16, v14
	v_rcp_f32_e32 v14, v32
	s_nop 0
	v_mul_f32_e32 v17, v17, v14
	v_cvt_pk_bf16_f32 v14, v29, v30
	v_cvt_pk_bf16_f32 v15, v31, v17
	s_nop 0
	v_lshlrev_b32_e32 v16, 16, v14
	v_sub_f32_e32 v16, v29, v16
	v_and_b32_e32 v29, 0xffff0000, v14
	v_sub_f32_e32 v29, v30, v29
	v_cvt_pk_bf16_f32 v16, v16, v29
	v_lshlrev_b32_e32 v29, 16, v15
	v_and_b32_e32 v30, 0xffff0000, v15
	v_sub_f32_e32 v29, v31, v29
	v_sub_f32_e32 v17, v17, v30
	v_cvt_pk_bf16_f32 v17, v29, v17
	s_waitcnt vmcnt(50)
	v_mul_f32_e32 v29, 0xbfb8aa3b, v10
	v_exp_f32_e32 v29, v29
	v_mad_u32_u24 v30, v27, s3, 0
	v_add_u32_e32 v76, v30, v74
	ds_write_b64 v76, v[14:15]
	ds_write_b64 v76, v[16:17] offset:20736
	v_add_f32_e32 v29, 1.0, v29
	v_mul_f32_e32 v16, 0xbfb8aa3b, v11
	v_exp_f32_e32 v16, v16
	s_nop 0
	v_add_f32_e32 v16, 1.0, v16
	v_rcp_f32_e32 v14, v29
	s_nop 0
	v_mul_f32_e32 v14, v10, v14
	v_mul_f32_e32 v29, 0xbfb8aa3b, v12
	v_exp_f32_e32 v29, v29
	s_nop 0
	v_add_f32_e32 v17, 1.0, v29
	v_rcp_f32_e32 v10, v16
	s_nop 0
	v_mul_f32_e32 v15, v11, v10
	v_mul_f32_e32 v16, 0xbfb8aa3b, v13
	v_exp_f32_e32 v16, v16
	s_nop 0
	v_add_f32_e32 v16, 1.0, v16
	v_rcp_f32_e32 v10, v17
	s_nop 0
	v_mul_f32_e32 v17, v12, v10
	v_rcp_f32_e32 v10, v16
	s_nop 0
	v_mul_f32_e32 v13, v13, v10
	s_waitcnt vmcnt(49)
	v_mul_f32_e32 v16, 0xbfb8aa3b, v6
	v_exp_f32_e32 v16, v16
	v_cvt_pk_bf16_f32 v10, v14, v15
	v_cvt_pk_bf16_f32 v11, v17, v13
	s_nop 0
	v_lshlrev_b32_e32 v12, 16, v10
	v_sub_f32_e32 v12, v14, v12
	v_and_b32_e32 v14, 0xffff0000, v10
	v_sub_f32_e32 v14, v15, v14
	v_and_b32_e32 v15, 0xffff0000, v11
	v_cvt_pk_bf16_f32 v12, v12, v14
	v_lshlrev_b32_e32 v14, 16, v11
	v_sub_f32_e32 v13, v13, v15
	v_add_f32_e32 v15, 1.0, v16
	v_sub_f32_e32 v14, v17, v14
	v_cvt_pk_bf16_f32 v13, v14, v13
	v_mad_u32_u24 v14, v28, s3, 0
	v_add_u32_e32 v79, v14, v74
	ds_write_b64 v79, v[10:11]
	ds_write_b64 v79, v[12:13] offset:20736
	v_mul_f32_e32 v12, 0xbfb8aa3b, v7
	v_exp_f32_e32 v12, v12
	s_nop 0
	v_add_f32_e32 v12, 1.0, v12
	v_rcp_f32_e32 v10, v15
	s_nop 0
	v_mul_f32_e32 v10, v6, v10
	v_mul_f32_e32 v15, 0xbfb8aa3b, v8
	v_exp_f32_e32 v15, v15
	s_nop 0
	v_add_f32_e32 v13, 1.0, v15
	v_rcp_f32_e32 v6, v12
	s_nop 0
	v_mul_f32_e32 v11, v7, v6
	v_mul_f32_e32 v12, 0xbfb8aa3b, v9
	v_exp_f32_e32 v12, v12
	s_nop 0
	v_add_f32_e32 v12, 1.0, v12
	v_rcp_f32_e32 v6, v13
	s_nop 0
	v_mul_f32_e32 v13, v8, v6
	s_movk_i32 s3, 0x300
	v_rcp_f32_e32 v6, v12
	s_nop 0
	v_mul_f32_e32 v9, v9, v6
	v_cvt_pk_bf16_f32 v6, v10, v11
	v_cvt_pk_bf16_f32 v7, v13, v9
	v_cmp_gt_u32_e64 s[8:9], s3, v0
	v_lshlrev_b32_e32 v8, 16, v6
	v_sub_f32_e32 v8, v10, v8
	v_and_b32_e32 v10, 0xffff0000, v6
	v_sub_f32_e32 v10, v11, v10
	v_cvt_pk_bf16_f32 v8, v8, v10
	v_lshlrev_b32_e32 v10, 16, v7
	v_and_b32_e32 v11, 0xffff0000, v7
	v_sub_f32_e32 v10, v13, v10
	v_sub_f32_e32 v9, v9, v11
	v_cvt_pk_bf16_f32 v9, v10, v9
	v_add_u32_e32 v10, 0x2400, v30
	v_add_u32_e32 v78, v10, v74
	ds_write_b64 v78, v[6:7]
	ds_write_b64 v78, v[8:9] offset:20736
	s_and_saveexec_b64 s[10:11], s[8:9]
	s_cbranch_execz .LBB0_291
	global_load_dwordx4 v[6:9], v[68:69], off
	s_movk_i32 s3, 0x220
	v_cmp_gt_u32_e64 s[6:7], s3, v0
	s_and_saveexec_b64 s[20:21], s[6:7]
	s_cbranch_execz .LBB0_286
	s_waitcnt vmcnt(0)
	v_mul_f32_e32 v10, 0xbfb8aa3b, v6
	v_exp_f32_e32 v10, v10
	s_nop 0
	v_add_f32_e32 v10, 1.0, v10
	v_rcp_f32_e32 v11, v10
	s_nop 0
	v_mul_f32_e32 v19, v6, v11

.LBB0_668:
	s_and_b64 vcc, exec, s[6:7]
	s_barrier
	s_cbranch_vccnz .LBB0_672
	s_nop 4
	v_mov_b64_e32 v[4:5], s[0:1]
	s_waitcnt vmcnt(0)
	s_load_dwordx2 s[98:99], s[0:1], 0x50
	s_waitcnt vmcnt(0) lgkmcnt(0)
	v_mov_b32_e32 v38, s98
	v_mov_b32_e32 v39, s99
	s_mul_i32 s4, s2, 0x492000
	s_mul_hi_i32 s3, s2, 0x492000
	v_or_b32_e32 v40, s18, v72
	v_mov_b32_e32 v41, 0
	v_mov_b32_e32 v44, 0x9000
	s_add_u32 s4, s94, s4
	v_lshlrev_b64 v[42:43], 2, v[40:41]
	s_addc_u32 s5, s95, s3
	v_mul_u32_u24_e32 v40, 0x24000, v1
	s_mov_b64 s[6:7], 0x5800000
	v_lshl_add_u64 v[4:5], s[4:5], 0, v[42:43]
	v_lshl_add_u64 v[4:5], v[4:5], 0, s[6:7]
	s_mov_b32 s9, 0x12000
	v_lshl_add_u64 v[40:41], v[4:5], 0, v[40:41]
	s_mov_b32 s10, 0x1b000
	s_mov_b32 s8, 0x24000
	s_mov_b32 s11, 0x2d000
	s_mov_b32 s12, 0xa2000
	s_mov_b32 s13, 0xab000
	s_mov_b32 s18, 0xb4000
	s_mov_b32 s19, 0xbd000
	s_mov_b32 s20, 0x132000
	s_mov_b32 s21, 0x13b000
	s_mov_b32 s22, 0x144000
	s_mov_b32 s23, 0x14d000
	s_mov_b32 s24, 0x1c2000
	s_mov_b32 s25, 0x1cb000
	s_mov_b32 s26, 0x1d4000
	s_mov_b32 s27, 0x1dd000
	s_mov_b32 s28, 0x252000
	s_mov_b32 s29, 0x25b000
	s_mov_b32 s30, 0x264000
	s_mov_b32 s31, 0x26d000
	s_mov_b32 s33, 0x2e2000
	s_waitcnt lgkmcnt(0)
	v_mad_i64_i32 v[38:39], s[2:3], s2, v44, v[38:39]
	v_lshl_add_u64 v[38:39], v[38:39], 0, v[42:43]
	global_load_dword v1, v[38:39], off nt
	v_add_co_u32_e32 v38, vcc, s9, v40
	s_mov_b32 s2, 0x2eb000
	s_nop 0
	v_addc_co_u32_e32 v39, vcc, 0, v41, vcc
	v_add_co_u32_e32 v42, vcc, s10, v40
	s_waitcnt vmcnt(0)
	v_add_f32_e32 v30, v30, v1
	v_addc_co_u32_e32 v43, vcc, 0, v41, vcc
	v_add_co_u32_e32 v44, vcc, s8, v40
	v_add_f32_e32 v14, v14, v1
	s_nop 0
	v_addc_co_u32_e32 v45, vcc, 0, v41, vcc
	v_add_co_u32_e32 v46, vcc, s11, v40
	v_add_f32_e32 v31, v31, v1
	s_nop 0
	v_addc_co_u32_e32 v47, vcc, 0, v41, vcc
	v_add_co_u32_e32 v48, vcc, s12, v40
	v_add_f32_e32 v32, v32, v1
	s_nop 0
	v_addc_co_u32_e32 v49, vcc, 0, v41, vcc
	v_add_co_u32_e32 v50, vcc, s13, v40
	v_add_f32_e32 v33, v33, v1
	s_nop 0
	v_addc_co_u32_e32 v51, vcc, 0, v41, vcc
	v_add_co_u32_e32 v52, vcc, s18, v40
	v_add_f32_e32 v15, v15, v1
	s_nop 0
	v_addc_co_u32_e32 v53, vcc, 0, v41, vcc
	v_add_co_u32_e32 v54, vcc, s19, v40
	v_add_f32_e32 v16, v16, v1
	s_nop 0
	v_addc_co_u32_e32 v55, vcc, 0, v41, vcc
	v_add_co_u32_e32 v56, vcc, s20, v40
	v_add_f32_e32 v17, v17, v1
	s_nop 0
	v_addc_co_u32_e32 v57, vcc, 0, v41, vcc
	v_add_co_u32_e32 v58, vcc, s21, v40
	v_add_f32_e32 v34, v34, v1
	s_nop 0
	v_addc_co_u32_e32 v59, vcc, 0, v41, vcc
	v_add_co_u32_e32 v60, vcc, s22, v40
	v_add_f32_e32 v35, v35, v1
	s_nop 0
	v_addc_co_u32_e32 v61, vcc, 0, v41, vcc
	v_add_co_u32_e32 v62, vcc, s23, v40
	v_add_f32_e32 v36, v36, v1
	s_nop 0
	v_addc_co_u32_e32 v63, vcc, 0, v41, vcc
	v_add_co_u32_e32 v64, vcc, s24, v40
	v_add_f32_e32 v37, v37, v1
	s_nop 0
	v_addc_co_u32_e32 v65, vcc, 0, v41, vcc
	v_add_co_u32_e32 v66, vcc, s25, v40
	v_add_f32_e32 v22, v22, v1
	s_nop 0
	v_addc_co_u32_e32 v67, vcc, 0, v41, vcc
	v_add_co_u32_e32 v68, vcc, s26, v40
	v_add_f32_e32 v23, v23, v1
	s_nop 0
	v_addc_co_u32_e32 v69, vcc, 0, v41, vcc
	v_add_co_u32_e32 v70, vcc, s27, v40
	v_add_f32_e32 v24, v24, v1
	s_nop 0
	v_addc_co_u32_e32 v71, vcc, 0, v41, vcc
	v_add_co_u32_e32 v72, vcc, s28, v40
	v_add_f32_e32 v25, v25, v1
	s_nop 0
	v_addc_co_u32_e32 v73, vcc, 0, v41, vcc
	v_add_co_u32_e32 v74, vcc, s29, v40
	v_add_f32_e32 v26, v26, v1
	s_nop 0
	v_addc_co_u32_e32 v75, vcc, 0, v41, vcc
	v_add_co_u32_e32 v76, vcc, s30, v40
	v_add_f32_e32 v27, v27, v1
	s_nop 0
	v_addc_co_u32_e32 v77, vcc, 0, v41, vcc
	v_add_co_u32_e32 v78, vcc, s31, v40
	v_add_f32_e32 v28, v28, v1
	s_nop 0
	v_addc_co_u32_e32 v79, vcc, 0, v41, vcc
	v_add_f32_e32 v29, v29, v1
	global_store_dword v[38:39], v30, off
	global_store_dword v[42:43], v31, off
	global_store_dword v[44:45], v32, off
	global_store_dword v[46:47], v33, off
	global_store_dword v[48:49], v14, off
	global_store_dword v[50:51], v15, off
	global_store_dword v[52:53], v16, off
	global_store_dword v[54:55], v17, off
	global_store_dword v[56:57], v34, off
	global_store_dword v[58:59], v35, off
	global_store_dword v[60:61], v36, off
	global_store_dword v[62:63], v37, off
	global_store_dword v[64:65], v22, off
	global_store_dword v[66:67], v23, off
	global_store_dword v[68:69], v24, off
	global_store_dword v[70:71], v25, off
	global_store_dword v[72:73], v26, off
	global_store_dword v[74:75], v27, off
	global_store_dword v[76:77], v28, off
	global_store_dword v[78:79], v29, off
	v_add_co_u32_e32 v14, vcc, s33, v40
	v_add_f32_e32 v10, v10, v1
	s_nop 0
	v_addc_co_u32_e32 v15, vcc, 0, v41, vcc
	global_store_dword v[14:15], v10, off
	v_add_co_u32_e32 v10, vcc, s2, v40
	v_add_f32_e32 v14, v11, v1
	s_nop 0
	v_addc_co_u32_e32 v11, vcc, 0, v41, vcc
	s_mov_b32 s2, 0x2f4000
	global_store_dword v[10:11], v14, off
	v_add_co_u32_e32 v10, vcc, s2, v40
	v_add_f32_e32 v12, v12, v1
	s_nop 0
	v_addc_co_u32_e32 v11, vcc, 0, v41, vcc
	s_mov_b32 s2, 0x2fd000
	global_store_dword v[10:11], v12, off
	v_add_co_u32_e32 v10, vcc, s2, v40
	v_add_f32_e32 v12, v13, v1
	s_nop 0
	v_addc_co_u32_e32 v11, vcc, 0, v41, vcc
	s_mov_b32 s2, 0x372000
	global_store_dword v[10:11], v12, off
	v_add_co_u32_e32 v10, vcc, s2, v40
	v_add_f32_e32 v12, v18, v1
	s_nop 0
	v_addc_co_u32_e32 v11, vcc, 0, v41, vcc
	s_mov_b32 s2, 0x37b000
	global_store_dword v[10:11], v12, off
	v_add_co_u32_e32 v10, vcc, s2, v40
	v_add_f32_e32 v12, v19, v1
	s_nop 0
	v_addc_co_u32_e32 v11, vcc, 0, v41, vcc
	s_mov_b32 s2, 0x384000
	global_store_dword v[10:11], v12, off
	v_add_co_u32_e32 v10, vcc, s2, v40
	v_add_f32_e32 v12, v20, v1
	s_nop 0
	v_addc_co_u32_e32 v11, vcc, 0, v41, vcc
	s_mov_b32 s2, 0x38d000
	global_store_dword v[10:11], v12, off
	v_add_co_u32_e32 v10, vcc, s2, v40
	v_add_f32_e32 v12, v21, v1
	s_nop 0
	v_addc_co_u32_e32 v11, vcc, 0, v41, vcc
	s_mov_b32 s2, 0x402000
	global_store_dword v[10:11], v12, off
	v_add_co_u32_e32 v10, vcc, s2, v40
	v_add_f32_e32 v6, v6, v1
	s_nop 0
	v_addc_co_u32_e32 v11, vcc, 0, v41, vcc
	s_mov_b32 s2, 0x40b000
	global_store_dword v[10:11], v6, off
	v_add_co_u32_e32 v6, vcc, s2, v40
	v_add_f32_e32 v10, v7, v1
	s_nop 0
	v_addc_co_u32_e32 v7, vcc, 0, v41, vcc
	s_mov_b32 s2, 0x414000
	global_store_dword v[6:7], v10, off
	v_add_co_u32_e32 v6, vcc, s2, v40
	v_add_f32_e32 v8, v8, v1
	s_nop 0
	v_addc_co_u32_e32 v7, vcc, 0, v41, vcc
	global_store_dword v[6:7], v8, off
	v_add_co_u32_e32 v6, vcc, 0x41d000, v40
	v_add_f32_e32 v8, v9, v1
	s_nop 0
	v_addc_co_u32_e32 v7, vcc, 0, v41, vcc
	v_cmp_gt_u32_e32 vcc, 16, v98
	global_store_dword v[6:7], v8, off
	s_and_saveexec_b64 s[6:7], vcc
	s_cbranch_execz .LBB0_671
	v_add_f32_e32 v2, v2, v1
	global_store_dword v[4:5], v2, off
	v_add_co_u32_e32 v2, vcc, 0x9000, v4
	v_add_f32_e32 v1, v3, v1
	s_nop 0
	v_addc_co_u32_e32 v3, vcc, 0, v5, vcc
	global_store_dword v[2:3], v1, off

.LBB0_727:
	v_mov_b32_e32 v130, v0
	s_mov_b64 s[38:39], s[94:95]
	s_mov_b64 s[4:5], s[92:93]
	s_mov_b32 s40, s60
	v_readfirstlane_b32 s2, v130
	v_writelane_b32 v228, s4, 4
	s_ashr_i32 s3, s2, 6
	s_mov_b32 s2, s60
	v_writelane_b32 v228, s5, 5
	v_writelane_b32 v228, s2, 6
	s_mov_b32 s96, 0
	v_and_b32_e32 v132, 63, v130
	v_writelane_b32 v228, s3, 7
	s_lshl_b32 s2, s40, 3
	s_add_i32 s12, s2, s3
	s_add_u32 s4, s38, 0x4000
	v_writelane_b32 v228, s4, 8
	s_addc_u32 s4, s39, 0
	v_writelane_b32 v228, s4, 10
	s_add_i32 s4, s96, 0x20160
	s_add_u32 s42, s38, 0x5800000
	s_addc_u32 s43, s39, 0
	s_cmp_lt_i32 s90, 2
	v_writelane_b32 v228, s4, 12
	s_cselect_b64 s[4:5], -1, 0
	s_cmp_gt_i32 s91, 1
	s_cselect_b64 s[6:7], -1, 0
	s_and_b64 s[4:5], s[4:5], s[6:7]
	s_load_dword s37, s[0:1], 0xe8
	s_andn2_b64 vcc, exec, s[4:5]
	s_waitcnt lgkmcnt(0)
	s_cbranch_vccnz .LBB0_789
	v_mov_b64_e32 v[2:3], s[0:1]
	s_load_dwordx2 s[98:99], s[0:1], 0x58
	s_waitcnt vmcnt(0) lgkmcnt(0)
	v_mov_b32_e32 v2, s98
	v_mov_b32_e32 v3, s99
	s_cmpk_gt_i32 s12, 0x101f
	s_cbranch_scc1 .LBB0_735
	v_mov_b32_e32 v83, 0
	v_lshlrev_b32_e32 v4, 4, v132
	v_mov_b32_e32 v5, v83
	s_waitcnt lgkmcnt(0)
	v_lshl_add_u64 v[18:19], v[2:3], 0, v[4:5]
	global_load_dwordx4 v[2:5], v[18:19], off
	global_load_dwordx4 v[6:9], v[18:19], off offset:1024
	global_load_dwordx4 v[10:13], v[18:19], off offset:2048
	global_load_dwordx4 v[14:17], v[18:19], off offset:3072
	v_mbcnt_lo_u32_b32 v1, -1, 0
	v_mbcnt_hi_u32_b32 v18, -1, v1
	v_and_b32_e32 v1, 64, v18
	v_add_u32_e32 v19, 64, v1
	v_xor_b32_e32 v1, 1, v18
	v_cmp_lt_i32_e32 vcc, v1, v19
	v_xor_b32_e32 v20, 2, v18
	s_add_u32 s8, s0, 8
	v_cndmask_b32_e32 v1, v18, v1, vcc
	v_cmp_lt_i32_e32 vcc, v20, v19
	s_addc_u32 s9, s1, 0
	s_lshl_b32 s10, s12, 2
	v_cndmask_b32_e32 v20, v18, v20, vcc
	v_lshlrev_b32_e32 v97, 2, v20
	v_xor_b32_e32 v20, 4, v18
	v_cmp_lt_i32_e32 vcc, v20, v19
	s_lshl_b32 s16, s37, 5
	s_ashr_i32 s11, s10, 31
	v_cndmask_b32_e32 v20, v18, v20, vcc
	v_lshlrev_b32_e32 v98, 2, v20
	v_xor_b32_e32 v20, 8, v18
	v_cmp_lt_i32_e32 vcc, v20, v19
	v_lshlrev_b32_e32 v82, 3, v132
	s_ashr_i32 s17, s16, 31
	v_cndmask_b32_e32 v20, v18, v20, vcc
	v_lshlrev_b32_e32 v99, 2, v20
	v_xor_b32_e32 v20, 16, v18
	v_cmp_lt_i32_e32 vcc, v20, v19
	s_lshl_b64 s[6:7], s[10:11], 11
	s_mov_b64 s[4:5], 0xba00000
	v_cndmask_b32_e32 v20, v18, v20, vcc
	v_lshlrev_b32_e32 v100, 2, v20
	v_xor_b32_e32 v20, 32, v18
	v_cmp_lt_i32_e32 vcc, v20, v19
	s_add_u32 s6, s38, s6
	s_addc_u32 s7, s39, s7
	v_cndmask_b32_e32 v18, v18, v20, vcc
	v_lshlrev_b32_e32 v101, 2, v18
	v_lshl_add_u64 v[18:19], s[38:39], 0, v[82:83]
	v_lshl_add_u64 v[84:85], v[18:19], 0, s[4:5]
	v_lshlrev_b32_e32 v18, 2, v132
	v_or_b32_e32 v20, 0x100, v18
	v_or_b32_e32 v22, 0x200, v18
	v_or_b32_e32 v24, 0x300, v18
	v_lshl_add_u64 v[26:27], s[6:7], 0, v[82:83]
	s_lshl_b64 s[20:21], s[10:11], 12
	s_mov_b32 s15, 0
	v_lshlrev_b32_e32 v1, 2, v1
	v_lshl_add_u64 v[86:87], v[26:27], 0, s[4:5]
	s_lshl_b64 s[18:19], s[16:17], 11
	s_or_b32 s20, s20, 0x3000
	s_lshl_b64 s[22:23], s[16:17], 12
	v_lshlrev_b32_e32 v82, 4, v132
	v_mov_b32_e32 v102, 0x358637bd
	s_mov_b32 s4, 0xf800000
	v_mov_b32_e32 v103, 0x260
	v_lshlrev_b32_e32 v88, 2, v18
	s_movk_i32 s5, 0x7fff
	s_mov_b32 s13, 0xffff0000
	v_lshlrev_b32_e32 v90, 2, v20
	v_lshlrev_b32_e32 v92, 2, v22
	v_lshlrev_b32_e32 v94, 2, v24
	s_movk_i32 s26, 0x1000
	s_branch .LBB0_731

.LBB0_733:
	s_andn2_b64 vcc, exec, s[52:53]
	s_cbranch_vccnz .LBB0_730
	v_mov_b64_e32 v[22:23], s[0:1]
	s_load_dwordx2 s[98:99], s[0:1], 0x0
	s_waitcnt vmcnt(0) lgkmcnt(0)
	v_mov_b32_e32 v22, s98
	v_mov_b32_e32 v23, s99
	s_add_i32 s14, s10, 0xffffc003
	s_mov_b64 s[44:45], s[50:51]
	s_waitcnt lgkmcnt(0)
	v_lshl_add_u64 v[22:23], v[22:23], 0, s[20:21]
	s_branch .LBB0_730

.LBB0_789:
	s_waitcnt lgkmcnt(0)
	v_mov_b64_e32 v[2:3], s[0:1]
	s_load_dwordx2 s[98:99], s[0:1], 0x0
	s_waitcnt vmcnt(0) lgkmcnt(0)
	v_mov_b32_e32 v134, s98
	v_mov_b32_e32 v135, s99
	s_load_dwordx2 s[98:99], s[0:1], 0x8
	s_waitcnt vmcnt(0) lgkmcnt(0)
	v_mov_b32_e32 v136, s98
	v_mov_b32_e32 v137, s99
	s_cmp_lt_i32 s90, 3
	s_cselect_b64 s[4:5], -1, 0
	s_cmp_gt_i32 s91, 2
	s_cselect_b64 s[6:7], -1, 0
	s_and_b64 s[14:15], s[4:5], s[6:7]
	s_andn2_b64 vcc, exec, s[14:15]
	s_cbranch_vccnz .LBB0_882
	s_add_u32 s4, s38, 0x200000
	s_addc_u32 s5, s39, 0
	s_add_u32 s6, s38, 0x8000
	s_addc_u32 s7, s39, 0
	s_add_u32 s16, s38, 0x10000000
	s_addc_u32 s17, s39, 0
	s_cmp_gt_i32 s40, 21
	s_cbranch_scc1 .LBB0_801
	v_mov_b32_e32 v10, v0
	s_mov_b32 s8, 0x1fffe0
	v_ashrrev_i32_e32 v2, 31, v10
	v_lshrrev_b32_e32 v2, 26, v2
	v_add_u32_e32 v2, v10, v2
	v_ashrrev_i32_e32 v6, 6, v2
	v_bfe_i32 v2, v10, 27, 1
	v_lshlrev_b32_e32 v1, 4, v10
	v_lshrrev_b32_e32 v2, 22, v2
	v_add_u32_e32 v2, v1, v2
	v_and_b32_e32 v2, 0xfffffc00, v2
	v_sub_u32_e32 v2, v1, v2
	v_lshrrev_b32_e32 v3, 4, v2
	v_bitop3_b32 v2, v3, v2, 32 bitop3:0x6c
	v_ashrrev_i32_e32 v4, 31, v2
	v_lshrrev_b32_e32 v4, 26, v4
	v_add_u32_e32 v4, v2, v4
	v_lshlrev_b32_e32 v3, 3, v6
	v_ashrrev_i32_e32 v7, 6, v4
	v_and_b32_e32 v4, 0xc0, v4
	v_and_b32_e32 v3, -16, v3
	v_sub_u32_e32 v2, v2, v4
	v_mov_b32_e32 v4, 1
	v_add_u32_e32 v3, v7, v3
	v_ashrrev_i16_sdwa v2, v4, sext(v2) dst_sel:DWORD dst_unused:UNUSED_PAD src0_sel:DWORD src1_sel:BYTE_0
	v_lshlrev_b32_e32 v5, 5, v6
	v_bfe_i32 v8, v2, 0, 16
	v_lshlrev_b32_e32 v2, 1, v3
	v_lshrrev_b32_e32 v9, 2, v3
	v_and_b32_e32 v11, 3, v7
	v_and_b32_e32 v5, 32, v5
	v_and_b32_e32 v2, 24, v2
	v_and_b32_e32 v9, 4, v9
	v_and_or_b32 v11, v3, s8, v11
	v_or3_b32 v2, v11, v9, v2
	v_add_lshl_u32 v5, v5, v8, 1
	v_add_u32_e32 v1, 0x2000, v1
	v_lshl_add_u32 v140, v2, 11, v5
	v_ashrrev_i32_e32 v2, 31, v1
	v_lshrrev_b32_e32 v2, 22, v2
	v_add_u32_e32 v2, v1, v2
	v_ashrrev_i32_e32 v9, 10, v2
	v_mul_i32_i24_e32 v2, 0x400, v9
	v_sub_u32_e32 v1, v1, v2
	v_lshrrev_b32_e32 v2, 4, v1
	v_bitop3_b32 v1, v2, v1, 32 bitop3:0x6c
	v_lshl_add_u32 v138, v3, 11, v5
	v_ashrrev_i32_e32 v3, 31, v1
	v_lshrrev_b32_e32 v3, 26, v3
	v_add_u32_e32 v3, v1, v3
	v_readfirstlane_b32 s13, v10
	v_lshlrev_b32_e32 v2, 3, v9
	v_ashrrev_i32_e32 v11, 6, v3
	v_and_b32_e32 v3, 0xc0, v3
	v_and_b32_e32 v2, -16, v2
	v_sub_u32_e32 v1, v1, v3
	s_ashr_i32 s19, s13, 6
	s_ashr_i32 s41, s40, 31
	s_ashr_i32 s18, s13, 8
	v_add_u32_e32 v2, v11, v2
	v_ashrrev_i16_sdwa v1, v4, sext(v1) dst_sel:DWORD dst_unused:UNUSED_PAD src0_sel:DWORD src1_sel:BYTE_0
	v_and_b32_e32 v4, 3, v11
	s_lshl_b32 s24, s19, 10
	s_lshl_b64 s[20:21], s[40:41], 19
	v_and_or_b32 v4, v2, s8, v4
	s_add_u32 s8, s4, s20
	s_addc_u32 s9, s5, s21
	s_add_i32 s22, s96, 0x10000
	s_add_i32 s26, s22, s24
	v_lshlrev_b32_e32 v5, 5, v9
	v_bfe_i32 v12, v1, 0, 16
	v_lshlrev_b32_e32 v1, 1, v2
	v_lshrrev_b32_e32 v3, 2, v2
	s_add_i32 s27, s26, 0x2000
	v_and_b32_e32 v5, 32, v5
	v_and_b32_e32 v1, 24, v1
	v_and_b32_e32 v3, 4, v3
	s_add_u32 s10, s8, 0x40000
	v_or3_b32 v1, v4, v3, v1
	v_add_lshl_u32 v3, v5, v12, 1
	s_mov_b32 m0, s26
	s_addc_u32 s11, s9, 0
	s_add_i32 s23, s96, 0x14000
	v_lshl_add_u32 v144, v1, 11, v3
	global_load_lds_dwordx4 v140, s[8:9]
	s_mov_b32 m0, s27
	s_add_i32 s28, s23, s24
	global_load_lds_dwordx4 v144, s[8:9]
	s_mov_b32 m0, s28
	s_add_i32 s29, s28, 0x2000
	global_load_lds_dwordx4 v140, s[10:11]
	s_mov_b32 m0, s29
	v_lshl_add_u32 v142, v2, 11, v3
	global_load_lds_dwordx4 v144, s[10:11]
	s_add_u32 s10, s38, 0xda00000
	s_addc_u32 s11, s39, 0
	s_add_i32 s30, s96, s24
	s_add_i32 s31, s30, 0x2000
	s_mov_b32 m0, s30
	s_add_u32 s44, s38, 0xda40000
	global_load_lds_dwordx4 v138, s[10:11]
	s_mov_b32 m0, s31
	s_addc_u32 s45, s39, 0
	s_add_i32 s33, s30, 0x4000
	global_load_lds_dwordx4 v142, s[10:11]
	s_mov_b32 m0, s33
	s_add_i32 s34, s30, 0x6000
	global_load_lds_dwordx4 v138, s[44:45]
	s_mov_b32 m0, s34
	v_mov_b32_e32 v141, 0
	global_load_lds_dwordx4 v142, s[44:45]
	v_mov_b32_e32 v145, v141
	v_lshl_add_u64 v[4:5], s[8:9], 0, v[140:141]
	v_lshl_add_u64 v[2:3], s[8:9], 0, v[144:145]
	v_mov_b32_e32 v139, v141
	s_cmp_lg_u32 s18, 1
	v_mov_b32_e32 v143, v141
	s_cbranch_scc1 .LBB0_793
	s_barrier

.LBB0_840:
	s_or_b64 exec, exec, s[6:7]
	v_mov_b32_e32 v1, v0
	v_mov_b64_e32 v[2:3], s[0:1]
	s_barrier
	s_load_dwordx2 s[98:99], s[0:1], 0x58
	s_waitcnt vmcnt(0) lgkmcnt(0)
	v_mov_b32_e32 v2, s98
	v_mov_b32_e32 v3, s99
	v_readfirstlane_b32 s6, v1
	s_ashr_i32 s13, s6, 6
	s_cmp_gt_i32 s13, 7
	v_and_b32_e32 v131, 63, v1
	s_cbranch_scc1 .LBB0_843
	v_mov_b32_e32 v91, 0
	v_lshlrev_b32_e32 v90, 4, v131
	s_waitcnt lgkmcnt(0)
	v_lshl_add_u64 v[2:3], v[2:3], 0, v[90:91]
	s_movk_i32 s6, 0x1000
	v_add_co_u32_e32 v18, vcc, s6, v2
	s_lshl_b32 s6, s40, 5
	s_nop 0
	v_addc_co_u32_e32 v19, vcc, 0, v3, vcc
	global_load_dwordx4 v[2:5], v[18:19], off
	global_load_dwordx4 v[6:9], v[18:19], off offset:1024
	global_load_dwordx4 v[10:13], v[18:19], off offset:2048
	global_load_dwordx4 v[14:17], v[18:19], off offset:3072
	v_mbcnt_lo_u32_b32 v18, -1, 0
	v_mbcnt_hi_u32_b32 v18, -1, v18
	v_and_b32_e32 v19, 64, v18
	v_add_u32_e32 v19, 64, v19
	v_xor_b32_e32 v20, 1, v18
	v_cmp_lt_i32_e32 vcc, v20, v19
	s_lshl_b32 s7, s13, 2
	s_add_i32 s26, s6, 0x20a0
	v_cndmask_b32_e32 v20, v18, v20, vcc
	v_lshlrev_b32_e32 v133, 2, v20
	v_xor_b32_e32 v20, 2, v18
	v_cmp_lt_i32_e32 vcc, v20, v19
	s_add_i32 s6, s6, s7
	s_add_i32 s18, s6, 0x2080
	v_cndmask_b32_e32 v20, v18, v20, vcc
	v_lshlrev_b32_e32 v156, 2, v20
	v_xor_b32_e32 v20, 4, v18
	v_cmp_lt_i32_e32 vcc, v20, v19
	s_add_u32 s27, s38, 0x5803000
	s_addc_u32 s28, s39, 0
	v_cndmask_b32_e32 v20, v18, v20, vcc
	v_lshlrev_b32_e32 v157, 2, v20
	v_xor_b32_e32 v20, 8, v18
	v_cmp_lt_i32_e32 vcc, v20, v19
	s_ashr_i32 s19, s18, 31
	s_lshl_b64 s[6:7], s[18:19], 11
	v_cndmask_b32_e32 v20, v18, v20, vcc
	v_lshlrev_b32_e32 v158, 2, v20
	v_xor_b32_e32 v20, 16, v18
	v_cmp_lt_i32_e32 vcc, v20, v19
	v_lshl_or_b32 v92, v131, 3, s6
	v_mov_b32_e32 v93, s7
	v_cndmask_b32_e32 v20, v18, v20, vcc
	v_lshlrev_b32_e32 v159, 2, v20
	v_xor_b32_e32 v20, 32, v18
	v_cmp_lt_i32_e32 vcc, v20, v19
	s_lshl_b64 s[6:7], s[18:19], 12
	v_or_b32_e32 v94, s6, v90
	v_cndmask_b32_e32 v18, v18, v20, vcc
	v_lshlrev_b32_e32 v160, 2, v18
	v_lshlrev_b32_e32 v18, 2, v131
	v_or_b32_e32 v20, 0x100, v18
	v_or_b32_e32 v22, 0x200, v18
	v_or_b32_e32 v24, 0x300, v18
	v_mov_b32_e32 v95, s7
	v_mov_b32_e32 v161, 0x358637bd
	s_mov_b32 s19, 0xf800000
	v_mov_b32_e32 v162, 0x260
	v_lshlrev_b32_e32 v90, 2, v18
	s_movk_i32 s29, 0x7fff
	s_mov_b32 s30, 0xffff0000
	s_mov_b32 s31, 0xba00000
	v_lshlrev_b32_e32 v96, 2, v20
	v_mov_b32_e32 v97, v91
	v_lshlrev_b32_e32 v98, 2, v22
	v_mov_b32_e32 v99, v91
	v_lshlrev_b32_e32 v100, 2, v24
	v_mov_b32_e32 v101, v91
	s_mov_b32 s33, 0xba01000
	s_mov_b64 s[20:21], 0x10000
	s_mov_b64 s[22:23], 0x20000

.LBB0_1002:
	s_or_b64 exec, exec, s[10:11]
	v_mov_b32_e32 v130, v0
	v_mov_b64_e32 v[2:3], s[0:1]
	s_barrier
	s_load_dwordx2 s[98:99], s[0:1], 0x58
	s_waitcnt vmcnt(0) lgkmcnt(0)
	v_mov_b32_e32 v2, s98
	v_mov_b32_e32 v3, s99
	v_readfirstlane_b32 s3, v130
	s_ashr_i32 s3, s3, 6
	s_add_i32 s12, s3, s2
	s_cmp_gt_i32 s3, 15
	v_and_b32_e32 v132, 63, v130
	s_cbranch_scc1 .LBB0_1005
	v_mov_b32_e32 v91, 0
	v_lshlrev_b32_e32 v90, 4, v132
	s_waitcnt lgkmcnt(0)
	v_lshl_add_u64 v[2:3], v[2:3], 0, v[90:91]
	s_movk_i32 s2, 0x1000
	v_add_co_u32_e32 v18, vcc, s2, v2
	v_mbcnt_lo_u32_b32 v1, -1, 0
	s_nop 0
	v_addc_co_u32_e32 v19, vcc, 0, v3, vcc
	global_load_dwordx4 v[2:5], v[18:19], off
	global_load_dwordx4 v[6:9], v[18:19], off offset:1024
	global_load_dwordx4 v[10:13], v[18:19], off offset:2048
	global_load_dwordx4 v[14:17], v[18:19], off offset:3072
	v_mbcnt_hi_u32_b32 v18, -1, v1
	v_and_b32_e32 v1, 64, v18
	v_add_u32_e32 v19, 64, v1
	v_xor_b32_e32 v1, 1, v18
	v_cmp_lt_i32_e32 vcc, v1, v19
	v_xor_b32_e32 v20, 2, v18
	s_lshl_b32 s7, s27, 8
	v_cndmask_b32_e32 v1, v18, v1, vcc
	v_cmp_lt_i32_e32 vcc, v20, v19
	s_lshl_b32 s2, s26, 6
	s_add_i32 s8, s7, s2
	v_cndmask_b32_e32 v20, v18, v20, vcc
	v_lshlrev_b32_e32 v131, 2, v20
	v_xor_b32_e32 v20, 4, v18
	v_cmp_lt_i32_e32 vcc, v20, v19
	s_lshl_b32 s9, s3, 2
	s_add_i32 s6, s9, s8
	v_cndmask_b32_e32 v20, v18, v20, vcc
	v_lshlrev_b32_e32 v133, 2, v20
	v_xor_b32_e32 v20, 8, v18
	v_cmp_lt_i32_e32 vcc, v20, v19
	s_add_u32 s2, s38, 0x5803000
	s_addc_u32 s13, s39, 0
	v_cndmask_b32_e32 v20, v18, v20, vcc
	v_lshlrev_b32_e32 v152, 2, v20
	v_xor_b32_e32 v20, 16, v18
	v_cmp_lt_i32_e32 vcc, v20, v19
	s_lshl_b32 s5, s5, 6
	s_add_i32 s5, s7, s5
	v_cndmask_b32_e32 v20, v18, v20, vcc
	v_lshlrev_b32_e32 v153, 2, v20
	v_xor_b32_e32 v20, 32, v18
	v_cmp_lt_i32_e32 vcc, v20, v19
	s_add_i32 s5, s5, s9
	s_lshl_b32 s4, s4, 6
	v_cndmask_b32_e32 v18, v18, v20, vcc
	s_sub_i32 s4, s5, s4
	s_ashr_i32 s7, s6, 31
	v_lshlrev_b32_e32 v154, 2, v18
	s_or_b32 s22, s8, 32
	v_lshlrev_b32_e32 v18, 2, v132
	s_sub_i32 s8, s4, 32
	s_lshl_b64 s[4:5], s[6:7], 11
	v_or_b32_e32 v20, 0x100, v18
	v_or_b32_e32 v22, 0x200, v18
	v_or_b32_e32 v24, 0x300, v18
	v_lshl_or_b32 v92, v132, 3, s4
	v_mov_b32_e32 v93, s5
	s_lshl_b64 s[4:5], s[6:7], 12
	v_lshlrev_b32_e32 v1, 2, v1
	v_or_b32_e32 v94, s4, v90
	v_mov_b32_e32 v95, s5
	v_mov_b32_e32 v155, 0x358637bd
	s_mov_b32 s4, 0xf800000
	v_mov_b32_e32 v156, 0x260
	v_lshlrev_b32_e32 v90, 2, v18
	s_movk_i32 s5, 0x7fff
	s_mov_b32 s23, 0xffff0000
	s_mov_b32 s24, 0xba00000
	v_lshlrev_b32_e32 v96, 2, v20
	v_mov_b32_e32 v97, v91
	v_lshlrev_b32_e32 v98, 2, v22
	v_mov_b32_e32 v99, v91
	v_lshlrev_b32_e32 v100, 2, v24
	v_mov_b32_e32 v101, v91
	s_mov_b32 s25, 0xba01000
	s_mov_b64 s[16:17], 0x10000
	s_mov_b64 s[18:19], 0x20000

.LBB0_1591:
	v_mov_b32_e32 v180, v0
	s_mov_b64 s[6:7], -1
	v_readfirstlane_b32 s22, v180
	s_ashr_i32 s10, s22, 6
	v_and_b32_e32 v182, 63, v180
	s_cmp_lg_u32 s5, s33
	s_cbranch_scc0 .LBB0_1597
	s_waitcnt lgkmcnt(0)
	v_mov_b64_e32 v[2:3], s[0:1]
	s_load_dwordx2 s[98:99], s[0:1], 0x40
	s_waitcnt vmcnt(0) lgkmcnt(0)
	v_mov_b32_e32 v4, s98
	v_mov_b32_e32 v5, s99
	s_load_dwordx2 s[98:99], s[0:1], 0x20
	s_waitcnt vmcnt(0) lgkmcnt(0)
	v_mov_b32_e32 v8, s98
	v_mov_b32_e32 v9, s99
	v_ashrrev_i32_e32 v41, 5, v180
	v_lshlrev_b32_e32 v2, 14, v41
	v_and_b32_e32 v178, 0x1c000, v2
	s_mov_b32 s83, s57
	v_lshlrev_b32_e32 v40, 4, v180
	v_and_b32_e32 v6, 0xf0, v40
	v_mov_b32_e32 v7, v179
	s_lshl_b32 s5, s10, 5
	s_and_b32 s6, s5, 0xffffffc0
	s_lshl_b32 s5, s10, 7
	v_and_b32_e32 v203, 31, v180
	s_and_b32 s11, s5, 0x80
	s_mov_b32 s5, 0x20000
	v_lshrrev_b32_e32 v181, 5, v182
	s_mov_b64 s[8:9], 0
	s_waitcnt lgkmcnt(0)
	v_lshl_add_u64 v[26:27], s[54:55], 2, v[4:5]
	v_lshl_add_u64 v[2:3], v[8:9], 0, v[178:179]
	v_lshl_add_u64 v[4:5], v[2:3], 0, s[82:83]
	v_and_b32_e32 v2, 0x100, v40
	v_mov_b32_e32 v3, v179
	v_lshl_add_u64 v[10:11], v[4:5], 0, v[2:3]
	v_ashrrev_i32_e32 v4, 8, v180
	v_ashrrev_i32_e32 v5, 31, v4
	v_lshl_add_u64 v[4:5], v[4:5], 2, v[26:27]
	global_load_dword v4, v[4:5], off
	v_add_u32_e32 v3, 16, v41
	v_lshl_add_u64 v[8:9], v[8:9], 0, s[76:77]
	s_waitcnt vmcnt(0)
	v_ashrrev_i32_e32 v5, 31, v4
	v_lshlrev_b64 v[4:5], 17, v[4:5]
	v_lshl_add_u64 v[12:13], v[10:11], 0, v[4:5]
	v_lshl_add_u64 v[18:19], v[12:13], 0, v[6:7]
	v_ashrrev_i32_e32 v12, 3, v3
	v_ashrrev_i32_e32 v13, 31, v12
	v_lshl_add_u64 v[12:13], v[12:13], 2, v[26:27]
	global_load_dword v12, v[12:13], off
	v_add_u32_e32 v3, 32, v41
	v_or_b32_e32 v4, v4, v178
	v_or3_b32 v4, v4, v2, v6
	v_lshl_add_u64 v[200:201], v[8:9], 0, v[4:5]
	s_waitcnt vmcnt(0)
	v_ashrrev_i32_e32 v13, 31, v12
	v_lshlrev_b64 v[12:13], 17, v[12:13]
	v_lshl_add_u64 v[14:15], v[10:11], 0, v[12:13]
	v_lshl_add_u64 v[22:23], v[14:15], 0, v[6:7]
	v_ashrrev_i32_e32 v14, 3, v3
	v_ashrrev_i32_e32 v15, 31, v14
	v_lshl_add_u64 v[14:15], v[14:15], 2, v[26:27]
	global_load_dword v14, v[14:15], off
	v_add_u32_e32 v3, 48, v41
	v_or_b32_e32 v12, v12, v178
	v_or3_b32 v12, v12, v2, v6
	v_lshl_add_u64 v[198:199], v[8:9], 0, v[12:13]
	s_waitcnt vmcnt(0)
	v_ashrrev_i32_e32 v15, 31, v14
	v_lshlrev_b64 v[14:15], 17, v[14:15]
	v_lshl_add_u64 v[16:17], v[10:11], 0, v[14:15]
	v_lshl_add_u64 v[28:29], v[16:17], 0, v[6:7]
	v_ashrrev_i32_e32 v16, 3, v3
	v_ashrrev_i32_e32 v17, 31, v16
	v_lshl_add_u64 v[16:17], v[16:17], 2, v[26:27]
	global_load_dword v16, v[16:17], off
	v_add_u32_e32 v3, 64, v41
	v_or_b32_e32 v14, v14, v178
	v_or3_b32 v14, v14, v2, v6
	v_lshl_add_u64 v[196:197], v[8:9], 0, v[14:15]
	s_waitcnt vmcnt(0)
	v_ashrrev_i32_e32 v17, 31, v16
	v_lshlrev_b64 v[16:17], 17, v[16:17]
	v_lshl_add_u64 v[20:21], v[10:11], 0, v[16:17]
	v_lshl_add_u64 v[32:33], v[20:21], 0, v[6:7]
	v_ashrrev_i32_e32 v20, 3, v3
	v_ashrrev_i32_e32 v21, 31, v20
	v_lshl_add_u64 v[20:21], v[20:21], 2, v[26:27]
	global_load_dword v20, v[20:21], off
	v_add_u32_e32 v3, 0x50, v41
	v_or_b32_e32 v16, v16, v178
	v_or3_b32 v16, v16, v2, v6
	v_lshl_add_u64 v[194:195], v[8:9], 0, v[16:17]
	s_waitcnt vmcnt(0)
	v_ashrrev_i32_e32 v21, 31, v20
	v_lshlrev_b64 v[20:21], 17, v[20:21]
	v_lshl_add_u64 v[24:25], v[10:11], 0, v[20:21]
	v_lshl_add_u64 v[34:35], v[24:25], 0, v[6:7]
	v_ashrrev_i32_e32 v24, 3, v3
	v_ashrrev_i32_e32 v25, 31, v24
	v_lshl_add_u64 v[24:25], v[24:25], 2, v[26:27]
	global_load_dword v24, v[24:25], off
	v_add_u32_e32 v3, 0x60, v41
	v_or_b32_e32 v20, v20, v178
	v_or3_b32 v20, v20, v2, v6
	v_lshl_add_u64 v[192:193], v[8:9], 0, v[20:21]
	s_waitcnt vmcnt(0)
	v_ashrrev_i32_e32 v25, 31, v24
	v_lshlrev_b64 v[24:25], 17, v[24:25]
	v_lshl_add_u64 v[30:31], v[10:11], 0, v[24:25]
	v_lshl_add_u64 v[36:37], v[30:31], 0, v[6:7]
	v_ashrrev_i32_e32 v30, 3, v3
	v_add_u32_e32 v3, 0x70, v41
	v_ashrrev_i32_e32 v42, 3, v3
	v_ashrrev_i32_e32 v31, 31, v30
	v_ashrrev_i32_e32 v43, 31, v42
	v_lshl_add_u64 v[30:31], v[30:31], 2, v[26:27]
	v_lshl_add_u64 v[26:27], v[42:43], 2, v[26:27]
	global_load_dword v30, v[30:31], off
	v_lshrrev_b32_e32 v3, 4, v180
	global_load_dword v26, v[26:27], off
	v_mul_lo_u32 v41, v3, s48
	v_lshlrev_b32_e32 v3, 3, v180
	v_and_b32_e32 v48, 0x78, v3
	v_or_b32_e32 v3, s6, v203
	s_waitcnt vmcnt(1)
	v_ashrrev_i32_e32 v31, 31, v30
	v_lshlrev_b64 v[30:31], 17, v[30:31]
	s_waitcnt vmcnt(0)
	v_ashrrev_i32_e32 v27, 31, v26
	v_lshlrev_b64 v[26:27], 17, v[26:27]
	v_lshl_add_u64 v[38:39], v[10:11], 0, v[30:31]
	v_lshl_add_u64 v[10:11], v[10:11], 0, v[26:27]
	v_lshl_add_u64 v[42:43], v[10:11], 0, v[6:7]
	v_ashrrev_i32_e32 v10, 3, v180
	v_ashrrev_i32_e32 v11, 31, v10
	v_lshl_add_u64 v[38:39], v[38:39], 0, v[6:7]
	v_lshlrev_b64 v[44:45], 11, v[10:11]
	v_or_b32_e32 v7, s11, v203
	v_mov_b32_e32 v11, s96
	v_lshl_add_u64 v[46:47], s[58:59], 0, v[44:45]
	v_mul_lo_u32 v49, v10, s48
	v_and_b32_e32 v10, 0x70, v40
	v_mad_u32_u24 v7, v7, s48, v11
	v_mov_b32_e32 v11, v179
	global_load_dwordx4 v[130:133], v[18:19], off nt
	global_load_dwordx4 v[134:137], v[22:23], off nt
	global_load_dwordx4 v[138:141], v[28:29], off nt
	global_load_dwordx4 v[142:145], v[32:33], off nt
	global_load_dwordx4 v[146:149], v[34:35], off nt
	global_load_dwordx4 v[150:153], v[36:37], off nt
	global_load_dwordx4 v[154:157], v[38:39], off nt
	global_load_dwordx4 v[158:161], v[42:43], off nt
	v_lshl_add_u64 v[22:23], v[46:47], 0, v[10:11]
	v_add_co_u32_e32 v28, vcc, s5, v22
	s_mov_b32 s5, 0x40000
	s_nop 0
	v_addc_co_u32_e32 v29, vcc, 0, v23, vcc
	global_load_dwordx4 v[162:165], v[22:23], off
	global_load_dwordx4 v[166:169], v[28:29], off
	v_add_co_u32_e32 v28, vcc, s5, v22
	s_mov_b32 s5, 0x60000
	s_nop 0
	v_addc_co_u32_e32 v29, vcc, 0, v23, vcc
	v_add_co_u32_e32 v22, vcc, s5, v22
	global_load_dwordx4 v[170:173], v[28:29], off
	s_nop 0
	v_addc_co_u32_e32 v23, vcc, 0, v23, vcc
	global_load_dwordx4 v[174:177], v[22:23], off
	v_or_b32_e32 v22, v26, v178
	v_or3_b32 v26, v22, v2, v6
	v_or_b32_e32 v22, v30, v178
	v_mul_lo_u32 v40, v3, s48
	v_or3_b32 v30, v22, v2, v6
	v_or_b32_e32 v22, v24, v178
	v_lshlrev_b32_e32 v3, 4, v181
	v_add_u32_e32 v19, s96, v41
	v_add_u32_e32 v11, s96, v49
	v_add_u32_e32 v18, s96, v40
	v_or_b32_e32 v44, v44, v10
	v_or3_b32 v24, v22, v2, v6
	v_mov_b32_e32 v2, 0
	v_lshl_add_u64 v[184:185], s[74:75], 0, v[44:45]
	v_lshl_add_u64 v[186:187], v[8:9], 0, v[26:27]
	v_lshl_add_u64 v[188:189], v[8:9], 0, v[30:31]
	v_lshl_add_u64 v[190:191], v[8:9], 0, v[24:25]
	v_add_u32_e32 v178, v19, v48
	v_add_u32_e32 v204, v11, v10
	v_add_u32_e32 v205, v18, v3
	v_add_u32_e32 v206, v7, v3
	v_mov_b32_e32 v3, v2
	v_mov_b32_e32 v4, v2
	v_mov_b32_e32 v5, v2
	v_mov_b32_e32 v6, v2
	v_mov_b32_e32 v7, v2
	v_mov_b32_e32 v8, v2
	v_mov_b32_e32 v9, v2
	v_mov_b32_e32 v10, v2
	v_mov_b32_e32 v11, v2
	v_mov_b32_e32 v12, v2
	v_mov_b32_e32 v13, v2
	v_mov_b32_e32 v14, v2
	v_mov_b32_e32 v15, v2
	v_mov_b32_e32 v16, v2
	v_mov_b32_e32 v17, v2
	v_mov_b32_e32 v18, v2
	v_mov_b32_e32 v19, v2
	v_mov_b32_e32 v20, v2
	v_mov_b32_e32 v21, v2
	v_mov_b32_e32 v22, v2
	v_mov_b32_e32 v23, v2
	v_mov_b32_e32 v24, v2
	v_mov_b32_e32 v25, v2
	v_mov_b32_e32 v26, v2
	v_mov_b32_e32 v27, v2
	v_mov_b32_e32 v28, v2
	v_mov_b32_e32 v29, v2
	v_mov_b32_e32 v30, v2
	v_mov_b32_e32 v31, v2
	v_mov_b32_e32 v32, v2
	v_mov_b32_e32 v33, v2
	v_mov_b32_e32 v34, v2
	v_mov_b32_e32 v35, v2
	v_mov_b32_e32 v36, v2
	v_mov_b32_e32 v37, v2
	v_mov_b32_e32 v38, v2
	v_mov_b32_e32 v39, v2
	v_mov_b32_e32 v40, v2
	v_mov_b32_e32 v41, v2
	v_mov_b32_e32 v42, v2
	v_mov_b32_e32 v43, v2
	v_mov_b32_e32 v44, v2
	v_mov_b32_e32 v45, v2
	v_mov_b32_e32 v46, v2
	v_mov_b32_e32 v47, v2
	v_mov_b32_e32 v48, v2
	v_mov_b32_e32 v49, v2
	v_mov_b32_e32 v50, v2
	v_mov_b32_e32 v51, v2
	v_mov_b32_e32 v52, v2
	v_mov_b32_e32 v53, v2
	v_mov_b32_e32 v54, v2
	v_mov_b32_e32 v55, v2
	v_mov_b32_e32 v56, v2
	v_mov_b32_e32 v57, v2
	v_mov_b32_e32 v58, v2
	v_mov_b32_e32 v59, v2
	v_mov_b32_e32 v60, v2
	v_mov_b32_e32 v61, v2
	v_mov_b32_e32 v62, v2
	v_mov_b32_e32 v63, v2
	v_mov_b32_e32 v64, v2
	v_mov_b32_e32 v65, v2
	v_mov_b32_e32 v66, v2
	v_mov_b32_e32 v67, v2
	v_mov_b32_e32 v68, v2
	v_mov_b32_e32 v69, v2
	v_mov_b32_e32 v70, v2
	v_mov_b32_e32 v71, v2
	v_mov_b32_e32 v72, v2
	v_mov_b32_e32 v73, v2
	v_mov_b32_e32 v74, v2
	v_mov_b32_e32 v75, v2
	v_mov_b32_e32 v76, v2
	v_mov_b32_e32 v77, v2
	v_mov_b32_e32 v78, v2
	v_mov_b32_e32 v79, v2
	v_mov_b32_e32 v80, v2
	v_mov_b32_e32 v81, v2
	v_mov_b32_e32 v82, v2
	v_mov_b32_e32 v83, v2
	v_mov_b32_e32 v84, v2
	v_mov_b32_e32 v85, v2
	v_mov_b32_e32 v86, v2
	v_mov_b32_e32 v87, v2
	v_mov_b32_e32 v88, v2
	v_mov_b32_e32 v89, v2
	v_mov_b32_e32 v90, v2
	v_mov_b32_e32 v91, v2
	v_mov_b32_e32 v92, v2
	v_mov_b32_e32 v93, v2
	v_mov_b32_e32 v94, v2
	v_mov_b32_e32 v95, v2
	v_mov_b32_e32 v96, v2
	v_mov_b32_e32 v97, v2
	v_mov_b32_e32 v98, v2
	v_mov_b32_e32 v99, v2
	v_mov_b32_e32 v100, v2
	v_mov_b32_e32 v101, v2
	v_mov_b32_e32 v102, v2
	v_mov_b32_e32 v103, v2
	v_mov_b32_e32 v104, v2
	v_mov_b32_e32 v105, v2
	v_mov_b32_e32 v106, v2
	v_mov_b32_e32 v107, v2
	v_mov_b32_e32 v108, v2
	v_mov_b32_e32 v109, v2
	v_mov_b32_e32 v110, v2
	v_mov_b32_e32 v111, v2
	v_mov_b32_e32 v112, v2
	v_mov_b32_e32 v113, v2
	v_mov_b32_e32 v114, v2
	v_mov_b32_e32 v115, v2
	v_mov_b32_e32 v116, v2
	v_mov_b32_e32 v117, v2
	v_mov_b32_e32 v118, v2
	v_mov_b32_e32 v119, v2
	v_mov_b32_e32 v120, v2
	v_mov_b32_e32 v121, v2
	v_mov_b32_e32 v122, v2
	v_mov_b32_e32 v123, v2
	v_mov_b32_e32 v124, v2
	v_mov_b32_e32 v125, v2
	v_mov_b32_e32 v126, v2
	v_mov_b32_e32 v127, v2
	v_mov_b32_e32 v128, v2
	v_mov_b32_e32 v129, v2
	s_branch .LBB0_1594

.LBB0_1627:
	s_load_dwordx2 s[98:99], s[0:1], 0x98
	s_waitcnt vmcnt(0) lgkmcnt(0)
	v_mov_b32_e32 v44, s98
	v_mov_b32_e32 v45, s99
	v_and_b32_e32 v46, 0xffffff00, v43
	v_ashrrev_i32_e32 v47, 31, v46
	v_add_u32_e32 v21, 0x200, v21
	v_cmp_lt_i32_e32 vcc, s13, v21
	s_or_b64 s[8:9], vcc, s[8:9]
	s_waitcnt lgkmcnt(0)
	v_lshl_add_u64 v[44:45], v[46:47], 2, v[44:45]
	v_lshl_add_u64 v[44:45], v[44:45], 0, s[10:11]
	v_lshl_add_u64 v[44:45], v[44:45], 0, v[22:23]
	global_load_dword v44, v[44:45], off
	v_add_u32_e32 v45, s4, v43
	v_add_u32_e32 v43, 0x800, v43
	s_waitcnt vmcnt(0)
	ds_write_b32 v45, v44
	s_andn2_b64 exec, exec, s[8:9]
	s_cbranch_execnz .LBB0_1627

.LBB0_1630:
	s_load_dwordx2 s[98:99], s[0:1], 0xa0
	s_waitcnt vmcnt(0) lgkmcnt(0)
	v_mov_b32_e32 v44, s98
	v_mov_b32_e32 v45, s99
	v_ashrrev_i32_e32 v60, 6, v43
	v_add_u32_e32 v46, s3, v60
	v_ashrrev_i32_e32 v47, 31, v46
	v_add_u32_e32 v79, 0x200, v43
	v_cmp_lt_i32_e32 vcc, s14, v43
	v_lshl_add_u32 v43, v60, 2, s4
	s_or_b64 s[8:9], vcc, s[8:9]
	v_mad_u64_u32 v[60:61], s[18:19], v60, s13, v[22:23]
	s_waitcnt lgkmcnt(0)
	v_lshl_add_u64 v[44:45], v[46:47], 2, v[44:45]
	global_load_dword v78, v[44:45], off
	ds_read2st64_b32 v[44:45], v21 offset1:1
	ds_read2st64_b32 v[46:47], v21 offset0:2 offset1:3
	ds_read2st64_b32 v[48:49], v21 offset0:4 offset1:5
	ds_read2st64_b32 v[50:51], v21 offset0:6 offset1:7
	ds_read2st64_b32 v[52:53], v21 offset0:8 offset1:9
	ds_read2st64_b32 v[54:55], v21 offset0:10 offset1:11
	ds_read2st64_b32 v[56:57], v21 offset0:12 offset1:13
	ds_read2st64_b32 v[58:59], v21 offset0:14 offset1:15
	ds_read2st64_b32 v[62:63], v43 offset1:1
	ds_read2st64_b32 v[64:65], v43 offset0:2 offset1:3
	ds_read2st64_b32 v[66:67], v43 offset0:4 offset1:5
	ds_read2st64_b32 v[68:69], v43 offset0:6 offset1:7
	ds_read2st64_b32 v[70:71], v43 offset0:8 offset1:9
	ds_read2st64_b32 v[72:73], v43 offset0:10 offset1:11
	ds_read2st64_b32 v[74:75], v43 offset0:12 offset1:13
	ds_read2st64_b32 v[76:77], v43 offset0:14 offset1:15
	s_waitcnt lgkmcnt(4)
	v_pk_mul_f32 v[50:51], v[50:51], v[68:69]
	s_waitcnt lgkmcnt(3)
	v_pk_mul_f32 v[52:53], v[52:53], v[70:71]
	s_waitcnt lgkmcnt(2)
	v_pk_mul_f32 v[54:55], v[54:55], v[72:73]
	s_waitcnt lgkmcnt(1)
	v_pk_mul_f32 v[56:57], v[56:57], v[74:75]
	s_waitcnt lgkmcnt(0)
	v_pk_mul_f32 v[58:59], v[58:59], v[76:77]
	s_waitcnt vmcnt(0)
	v_fmac_f32_e32 v78, v44, v62
	v_fmac_f32_e32 v78, v45, v63
	v_fmac_f32_e32 v78, v46, v64
	v_fmac_f32_e32 v78, v47, v65
	v_fmac_f32_e32 v78, v48, v66
	v_fmac_f32_e32 v78, v49, v67
	v_add_f32_e32 v43, v78, v50
	v_add_f32_e32 v43, v43, v51
	v_add_f32_e32 v43, v43, v52
	v_add_f32_e32 v43, v43, v53
	v_add_f32_e32 v43, v43, v54
	v_add_f32_e32 v43, v43, v55
	v_add_f32_e32 v43, v43, v56
	v_add_f32_e32 v43, v43, v57
	v_add_f32_e32 v43, v43, v58
	v_add_f32_e32 v44, v43, v59
	v_mul_f32_e64 v43, |v44|, s5
	v_exp_f32_e32 v45, v43
	v_min_f32_e32 v44, 0, v44
	v_mov_b32_e32 v43, v79
	v_add_f32_e32 v45, 1.0, v45
	v_cmp_gt_f32_e32 vcc, s10, v45
	s_nop 1
	v_cndmask_b32_e64 v46, 0, 32, vcc
	v_ldexp_f32 v45, v45, v46
	v_log_f32_e32 v45, v45
	v_cndmask_b32_e32 v46, 0, v23, vcc
	v_mul_f32_e32 v47, 0x3f317217, v45
	v_fma_f32 v47, v45, s11, -v47
	v_fmac_f32_e32 v47, 0x3377d1cf, v45
	v_fmac_f32_e32 v47, 0x3f317217, v45
	v_cmp_lt_f32_e64 vcc, |v45|, s12
	s_nop 1
	v_cndmask_b32_e32 v45, v45, v47, vcc
	v_sub_f32_e32 v45, v45, v46
	v_sub_f32_e32 v44, v44, v45
	v_mul_f32_e32 v44, 0x3d800000, v44
	ds_write_b32 v60, v44
	s_andn2_b64 exec, exec, s[8:9]
	s_cbranch_execnz .LBB0_1630

.LBB0_1714:
	v_mov_b64_e32 v[8:9], s[0:1]
	s_load_dwordx2 s[98:99], s[0:1], 0x90
	s_waitcnt vmcnt(0) lgkmcnt(0)
	v_mov_b32_e32 v8, s98
	v_mov_b32_e32 v9, s99
	v_add_u32_e32 v5, 0x200, v5
	v_cmp_lt_i32_e32 vcc, s7, v5
	s_or_b64 s[72:73], vcc, s[72:73]
	s_waitcnt lgkmcnt(0)
	v_lshl_add_u64 v[8:9], v[8:9], 0, v[2:3]
	global_load_dword v7, v[8:9], off nt
	v_lshl_add_u64 v[2:3], v[2:3], 0, s[14:15]
	s_waitcnt vmcnt(0)
	ds_write_b32 v6, v7
	v_add_u32_e32 v6, 0x800, v6
	s_andn2_b64 exec, exec, s[72:73]
	s_cbranch_execnz .LBB0_1714
.LBB0_1715:
	s_or_b64 exec, exec, s[68:69]
	s_movk_i32 s7, 0x7f
	v_cmp_lt_i32_e32 vcc, s7, v130
	s_and_saveexec_b64 s[14:15], vcc
	s_xor_b64 s[14:15], exec, s[14:15]
	s_lshl_b32 s7, s5, 7
	s_or_saveexec_b64 s[14:15], s[14:15]
	v_mov_b32_e32 v58, s7
	s_xor_b64 exec, exec, s[14:15]
	s_cbranch_execz .LBB0_1721
	v_mov_b64_e32 v[2:3], s[0:1]
	s_load_dwordx2 s[98:99], s[0:1], 0x88
	s_waitcnt vmcnt(0) lgkmcnt(0)
	v_mov_b32_e32 v6, s98
	v_mov_b32_e32 v7, s99
	s_lshl_b32 s7, s5, 7
	v_add_u32_e32 v2, s7, v130
	v_ashrrev_i32_e32 v3, 31, v2
	s_add_u32 s68, s38, 0x6200000
	s_addc_u32 s69, s39, 0
	s_mov_b32 s9, 0
	s_waitcnt lgkmcnt(0)
	v_lshl_add_u64 v[6:7], v[2:3], 2, v[6:7]
	global_load_dword v3, v[6:7], off nt

.LBB0_2725:
	v_mov_b64_e32 v[4:5], s[0:1]
	s_waitcnt lgkmcnt(0)
	s_barrier
	s_load_dwordx2 s[98:99], s[0:1], 0x28
	s_waitcnt vmcnt(0) lgkmcnt(0)
	v_mov_b32_e32 v2, s98
	v_mov_b32_e32 v3, s99
	s_load_dwordx2 s[98:99], s[0:1], 0x30
	s_waitcnt vmcnt(0) lgkmcnt(0)
	v_mov_b32_e32 v10, s98
	v_mov_b32_e32 v11, s99
	s_load_dwordx2 s[98:99], s[0:1], 0x40
	s_waitcnt vmcnt(0) lgkmcnt(0)
	v_mov_b32_e32 v4, s98
	v_mov_b32_e32 v5, s99
	s_lshl_b32 s6, s5, 2
	s_add_i32 s6, s36, s6
	v_mov_b32_e32 v6, s6
	v_add_u32_e32 v6, 0xc00, v6
	ds_read2_b32 v[6:7], v6 offset1:8
	s_mov_b64 s[8:9], -1
	s_waitcnt lgkmcnt(0)
	v_cmp_lt_i32_e32 vcc, 31, v6
	v_readfirstlane_b32 s10, v6
	v_readfirstlane_b32 s11, v7
	s_cbranch_vccz .LBB0_2745
	s_add_u32 s6, s18, 0xc00
	s_addc_u32 s7, s19, 0
	v_lshl_add_u64 v[4:5], s[58:59], 2, v[4:5]
	v_mov_b64_e32 v[6:7], s[6:7]
	s_cbranch_execz .LBB0_2746

.LBB0_2935:
	s_or_b64 exec, exec, s[6:7]
	v_mov_b32_e32 v1, v0
	v_mov_b64_e32 v[2:3], s[0:1]
	s_barrier
	s_load_dwordx2 s[98:99], s[0:1], 0x58
	s_waitcnt vmcnt(0) lgkmcnt(0)
	v_mov_b32_e32 v2, s98
	v_mov_b32_e32 v3, s99
	v_readfirstlane_b32 s2, v1
	s_ashr_i32 s2, s2, 4
	s_and_b32 s3, s2, -4
	s_cmp_gt_i32 s3, 31
	s_cbranch_scc1 .LBB0_2938
	v_and_b32_e32 v21, 63, v1
	v_mov_b32_e32 v91, 0
	v_lshlrev_b32_e32 v90, 4, v21
	s_waitcnt lgkmcnt(0)
	v_lshl_add_u64 v[2:3], v[2:3], 0, v[90:91]
	s_movk_i32 s2, 0x2000
	v_add_co_u32_e32 v18, vcc, s2, v2
	v_and_b32_e32 v1, 64, v166
	s_nop 0
	v_addc_co_u32_e32 v19, vcc, 0, v3, vcc
	global_load_dwordx4 v[2:5], v[18:19], off
	global_load_dwordx4 v[6:9], v[18:19], off offset:1024
	global_load_dwordx4 v[10:13], v[18:19], off offset:2048
	global_load_dwordx4 v[14:17], v[18:19], off offset:3072
	v_add_u32_e32 v18, 64, v1
	v_xor_b32_e32 v1, 1, v166
	v_cmp_lt_i32_e32 vcc, v1, v18
	v_xor_b32_e32 v19, 2, v166
	s_lshl_b32 s4, s40, 5
	v_cndmask_b32_e32 v1, v166, v1, vcc
	v_cmp_lt_i32_e32 vcc, v19, v18
	s_add_i32 s3, s4, s3
	s_add_i32 s2, s4, 0x20a0
	v_cndmask_b32_e32 v19, v166, v19, vcc
	v_lshlrev_b32_e32 v167, 2, v19
	v_xor_b32_e32 v19, 4, v166
	v_cmp_lt_i32_e32 vcc, v19, v18
	s_add_i32 s12, s3, 0x2080
	s_add_u32 s3, s68, 0x5800000
	v_cndmask_b32_e32 v19, v166, v19, vcc
	v_lshlrev_b32_e32 v168, 2, v19
	v_xor_b32_e32 v19, 8, v166
	v_cmp_lt_i32_e32 vcc, v19, v18
	s_addc_u32 s4, s69, 0
	s_ashr_i32 s13, s12, 31
	v_cndmask_b32_e32 v19, v166, v19, vcc
	v_lshlrev_b32_e32 v169, 2, v19
	v_xor_b32_e32 v19, 16, v166
	v_cmp_lt_i32_e32 vcc, v19, v18
	s_lshl_b64 s[6:7], s[12:13], 11
	v_lshl_or_b32 v92, v21, 3, s6
	v_cndmask_b32_e32 v19, v166, v19, vcc
	v_lshlrev_b32_e32 v170, 2, v19
	v_xor_b32_e32 v19, 32, v166
	v_cmp_lt_i32_e32 vcc, v19, v18
	v_mov_b32_e32 v93, s7
	s_lshl_b64 s[6:7], s[12:13], 12
	v_cndmask_b32_e32 v18, v166, v19, vcc
	v_lshlrev_b32_e32 v171, 2, v18
	v_lshlrev_b32_e32 v18, 2, v21
	v_or_b32_e32 v20, 0x100, v18
	v_or_b32_e32 v22, 0x200, v18
	v_or_b32_e32 v24, 0x300, v18
	v_lshlrev_b32_e32 v1, 2, v1
	v_or_b32_e32 v94, s6, v90
	v_mov_b32_e32 v95, s7
	v_mov_b32_e32 v172, 0x358637bd
	s_mov_b32 s13, 0xf800000
	v_mov_b32_e32 v173, 0x260
	v_lshlrev_b32_e32 v90, 2, v18
	s_movk_i32 s22, 0x7fff
	s_mov_b32 s23, 0xffff0000
	s_mov_b32 s24, 0xba00000
	v_lshlrev_b32_e32 v96, 2, v20
	v_lshlrev_b32_e32 v98, 2, v22
	v_mov_b32_e32 v99, v91
	v_lshlrev_b32_e32 v100, 2, v24
	v_mov_b32_e32 v101, v91
	s_mov_b32 s25, 0xba01000
	s_mov_b64 s[14:15], 0x10000
	s_mov_b64 s[16:17], 0x20000
	v_mov_b32_e32 v97, v91

.LBB0_2965:
	ds_read2_b32 v[20:21], v18 offset1:2
	ds_read2st64_b32 v[22:23], v19 offset1:4
	s_add_i32 s8, s8, -8
	s_cmp_eq_u32 s8, 0
	s_waitcnt lgkmcnt(0)
	v_mfma_f32_32x32x2_f32 v[2:17], v20, v22, v[2:17]
	v_mfma_f32_32x32x2_f32 v[2:17], v21, v23, v[2:17]
	ds_read2_b32 v[20:21], v18 offset0:4 offset1:6
	ds_read2st64_b32 v[22:23], v19 offset0:8 offset1:12
	s_waitcnt lgkmcnt(0)
	v_mfma_f32_32x32x2_f32 v[2:17], v20, v22, v[2:17]
	v_mfma_f32_32x32x2_f32 v[2:17], v21, v23, v[2:17]
	ds_read2_b32 v[20:21], v18 offset0:8 offset1:10
	ds_read2st64_b32 v[22:23], v19 offset0:16 offset1:20
	s_waitcnt lgkmcnt(0)
	v_mfma_f32_32x32x2_f32 v[2:17], v20, v22, v[2:17]
	v_mfma_f32_32x32x2_f32 v[2:17], v21, v23, v[2:17]
	ds_read2_b32 v[20:21], v18 offset0:12 offset1:14
	ds_read2st64_b32 v[22:23], v19 offset0:24 offset1:28
	v_add_u32_e32 v19, 0x2000, v19
	v_add_u32_e32 v18, 64, v18
	s_waitcnt lgkmcnt(0)
	v_mfma_f32_32x32x2_f32 v[2:17], v20, v22, v[2:17]
	v_mfma_f32_32x32x2_f32 v[2:17], v21, v23, v[2:17]
	s_cbranch_scc0 .LBB0_2965
	v_add_u32_e32 v18, 0xc200, v103
	s_barrier
	s_nop 14
	ds_write2_b32 v18, v2, v3 offset0:64 offset1:196
	v_add_u32_e32 v2, 0xc600, v103
	ds_write2_b32 v2, v4, v5 offset0:72 offset1:204
	v_add_u32_e32 v2, 0xd200, v103
	ds_write2_b32 v2, v6, v7 offset0:96 offset1:228
	v_add_u32_e32 v2, 0xd600, v103
	ds_write2_b32 v2, v8, v9 offset0:104 offset1:236
	v_add_u32_e32 v2, 0xe400, v103
	ds_write2_b32 v2, v10, v11 offset1:132
	v_add_u32_e32 v2, 0xe800, v103
	ds_write2_b32 v2, v12, v13 offset0:8 offset1:140
	v_add_u32_e32 v2, 0xf400, v103
	ds_write2_b32 v2, v14, v15 offset0:32 offset1:164
	v_add_u32_e32 v2, 0xf800, v103
	v_mov_b64_e32 v[18:19], s[0:1]
	ds_write2_b32 v2, v16, v17 offset0:40 offset1:172
	s_waitcnt lgkmcnt(0)
	s_barrier
	ds_read_b128 v[14:17], v95 offset:49920
	ds_read_b128 v[10:13], v95 offset:49936
	ds_read_b128 v[6:9], v95 offset:49952
	ds_read_b128 v[2:5], v95 offset:49968
	s_load_dwordx2 s[98:99], s[0:1], 0xa8
	s_waitcnt vmcnt(0) lgkmcnt(0)
	v_mov_b32_e32 v22, s98
	v_mov_b32_e32 v23, s99
	v_mov_b32_e32 v1, v229
	v_add_u32_e32 v60, s36, v94
	v_mov_b64_e32 v[18:19], s[12:13]
	v_and_b32_e32 v21, 64, v166
	s_lshl_b32 s70, s35, 2
	v_mad_i64_i32 v[18:19], s[8:9], v60, s29, v[18:19]
	v_xor_b32_e32 v20, 1, v166
	v_lshlrev_b32_e32 v42, 2, v54
	v_add_u32_e32 v59, 64, v21
	v_lshl_add_u64 v[18:19], v[18:19], 0, s[70:71]
	v_cmp_lt_i32_e32 vcc, v20, v59
	v_lshl_add_u64 v[30:31], v[18:19], 0, v[42:43]
	s_waitcnt lgkmcnt(0)
	v_mov_b32_e32 v26, v15
	v_cndmask_b32_e32 v20, v166, v20, vcc
	v_add_co_u32_e32 v18, vcc, s4, v30
	v_lshlrev_b32_e32 v61, 2, v20
	s_nop 0
	v_addc_co_u32_e32 v19, vcc, 0, v31, vcc
	global_load_dwordx4 v[18:21], v[18:19], off offset:1184
	v_mov_b32_e32 v27, v11
	v_mov_b32_e32 v24, v14
	v_mov_b32_e32 v25, v10
	v_mov_b32_e32 v36, v7
	v_mov_b32_e32 v37, v3
	v_pk_mul_f32 v[26:27], v[26:27], v[26:27]
	v_mov_b32_e32 v28, v16
	v_mov_b32_e32 v29, v12
	v_mov_b32_e32 v34, v6
	v_mov_b32_e32 v35, v2
	v_pk_mul_f32 v[36:37], v[36:37], v[36:37]
	v_pk_fma_f32 v[24:25], v[24:25], v[24:25], v[26:27]
	v_mov_b32_e32 v32, v17
	v_mov_b32_e32 v33, v13
	v_mov_b32_e32 v38, v8
	v_mov_b32_e32 v39, v4
	v_pk_fma_f32 v[26:27], v[34:35], v[34:35], v[36:37]
	v_pk_fma_f32 v[24:25], v[28:29], v[28:29], v[24:25]
	v_mov_b32_e32 v40, v9
	v_mov_b32_e32 v41, v5
	v_pk_fma_f32 v[26:27], v[38:39], v[38:39], v[26:27]
	v_pk_fma_f32 v[24:25], v[32:33], v[32:33], v[24:25]
	v_pk_fma_f32 v[26:27], v[40:41], v[40:41], v[26:27]
	v_add_f32_e32 v24, v24, v25
	v_add_f32_e32 v24, v24, v26
	v_add_f32_e32 v24, v24, v27
	ds_bpermute_b32 v25, v61, v24
	v_xor_b32_e32 v26, 2, v166
	v_cmp_lt_i32_e32 vcc, v26, v59
	v_lshl_add_u64 v[62:63], v[30:31], 0, s[72:73]
	v_mov_b32_e32 v38, v14
	v_cndmask_b32_e32 v26, v166, v26, vcc
	v_lshlrev_b32_e32 v26, 2, v26
	s_waitcnt lgkmcnt(0)
	v_add_f32_e32 v24, v24, v25
	ds_bpermute_b32 v25, v26, v24
	v_ashrrev_i32_e32 v61, 31, v60
	s_lshl_b32 s70, s35, 1
	s_mov_b64 s[76:77], 0
	s_waitcnt lgkmcnt(0)
	v_add_f32_e32 v32, v24, v25
	v_lshl_add_u64 v[64:65], v[22:23], 0, v[42:43]
	global_load_dwordx4 v[26:29], v[64:65], off
	v_xor_b32_e32 v22, 4, v166
	v_cmp_lt_i32_e32 vcc, v22, v59
	s_nop 1
	v_cndmask_b32_e32 v22, v166, v22, vcc
	v_lshlrev_b32_e32 v22, 2, v22
	ds_bpermute_b32 v33, v22, v32
	global_load_dwordx4 v[22:25], v[64:65], off offset:16
	s_waitcnt lgkmcnt(0)
	v_add_f32_e32 v30, v32, v33
	v_fmamk_f32 v30, v30, 0x3c000000, v104
	v_mul_f32_e32 v31, 0x4f800000, v30
	v_cmp_gt_f32_e32 vcc, s31, v30
	s_nop 1
	v_cndmask_b32_e32 v39, v30, v31, vcc
	v_sqrt_f32_e32 v40, v39
	global_load_dwordx4 v[30:33], v[62:63], off offset:16
	global_load_dwordx4 v[34:37], v[62:63], off offset:48
	v_add_u32_e32 v14, -1, v40
	v_add_u32_e32 v41, 1, v40
	v_fma_f32 v42, -v14, v40, v39
	v_fma_f32 v59, -v41, v40, v39
	v_cmp_ge_f32_e64 s[8:9], 0, v42
	s_nop 1
	v_cndmask_b32_e64 v14, v40, v14, s[8:9]
	v_cmp_lt_f32_e64 s[8:9], 0, v59
	s_nop 1
	v_cndmask_b32_e64 v14, v14, v41, s[8:9]
	v_mul_f32_e32 v40, 0x37800000, v14
	v_cndmask_b32_e32 v14, v14, v40, vcc
	v_cmp_class_f32_e32 vcc, v39, v105
	s_nop 1
	v_cndmask_b32_e32 v14, v14, v39, vcc
	v_div_scale_f32 v40, s[8:9], v14, v14, 1.0
	v_rcp_f32_e32 v41, v40
	v_mov_b32_e32 v39, v16
	v_div_scale_f32 v16, vcc, 1.0, v14, 1.0
	v_fma_f32 v42, -v40, v41, 1.0
	v_fmac_f32_e32 v41, v42, v41
	v_mul_f32_e32 v42, v16, v41
	v_fma_f32 v59, -v40, v42, v16
	v_fmac_f32_e32 v42, v59, v41
	v_fma_f32 v16, -v40, v42, v16
	v_div_fmas_f32 v16, v16, v41, v42
	v_div_fixup_f32 v14, v16, v14, 1.0
	v_pk_mul_f32 v[110:111], v[38:39], v[14:15] op_sel_hi:[1,0]
	s_waitcnt vmcnt(0)
	v_mul_f32_e32 v16, 0xbfb8aa3b, v18
	v_mul_f32_e32 v38, 0xbfb8aa3b, v20
	v_exp_f32_e32 v112, v16
	v_exp_f32_e32 v113, v38
	v_mul_f32_e32 v16, 0xbfb8aa3b, v19
	global_load_dwordx4 v[38:41], v[64:65], off offset:48
	global_load_dwordx4 v[106:109], v[64:65], off offset:32
	v_exp_f32_e32 v64, v16
	v_pk_add_f32 v[112:113], v[112:113], 1.0 op_sel_hi:[1,0]
	s_nop 0
	v_div_scale_f32 v16, s[8:9], v113, v113, v20
	v_rcp_f32_e32 v65, v16
	v_div_scale_f32 v59, s[8:9], v112, v112, v18
	v_rcp_f32_e32 v116, v59
	v_fma_f32 v114, -v16, v65, 1.0
	v_div_scale_f32 v42, vcc, v20, v113, v20
	v_fmac_f32_e32 v65, v114, v65
	v_fma_f32 v115, -v59, v116, 1.0
	v_mul_f32_e32 v114, v42, v65
	v_fmac_f32_e32 v116, v115, v116
	v_fma_f32 v115, -v16, v114, v42
	v_fmac_f32_e32 v114, v115, v65
	v_fma_f32 v16, -v16, v114, v42
	v_div_fmas_f32 v16, v16, v65, v114
	v_div_scale_f32 v117, s[8:9], v18, v112, v18
	v_div_fixup_f32 v113, v16, v113, v20
	v_mul_f32_e32 v20, 0xbfb8aa3b, v21
	v_mul_f32_e32 v118, v117, v116
	v_exp_f32_e32 v65, v20
	v_fma_f32 v119, -v59, v118, v117
	v_fmac_f32_e32 v118, v119, v116
	v_fma_f32 v16, -v59, v118, v117
	s_mov_b64 vcc, s[8:9]
	v_div_fmas_f32 v16, v16, v116, v118
	v_pk_add_f32 v[64:65], v[64:65], 1.0 op_sel_hi:[1,0]
	v_div_fixup_f32 v112, v16, v112, v18
	v_mov_b32_e32 v16, v15
	v_div_scale_f32 v15, s[8:9], v65, v65, v21
	v_rcp_f32_e32 v18, v15
	v_mov_b32_e32 v114, v26
	v_mov_b32_e32 v115, v28
	v_mov_b32_e32 v28, v27
	v_fma_f32 v20, -v15, v18, 1.0
	v_fmac_f32_e32 v18, v20, v18
	v_div_scale_f32 v20, vcc, v21, v65, v21
	v_mul_f32_e32 v26, v20, v18
	v_fma_f32 v27, -v15, v26, v20
	v_fmac_f32_e32 v26, v27, v18
	v_pk_mul_f32 v[16:17], v[16:17], v[14:15] op_sel_hi:[1,0]
	v_fma_f32 v15, -v15, v26, v20
	v_div_scale_f32 v20, s[8:9], v64, v64, v19
	v_rcp_f32_e32 v27, v20
	v_div_fmas_f32 v15, v15, v18, v26
	v_div_fixup_f32 v21, v15, v65, v21
	v_pk_mul_f32 v[16:17], v[28:29], v[16:17]
	v_fma_f32 v15, -v20, v27, 1.0
	v_fmac_f32_e32 v27, v15, v27
	v_div_scale_f32 v15, vcc, v19, v64, v19
	v_mul_f32_e32 v18, v15, v27
	v_fma_f32 v26, -v20, v18, v15
	v_fmac_f32_e32 v18, v26, v27
	v_fma_f32 v15, -v20, v18, v15
	v_div_fmas_f32 v15, v15, v27, v18
	v_div_fixup_f32 v20, v15, v64, v19
	v_pk_mul_f32 v[20:21], v[20:21], v[16:17]
	global_load_dwordx4 v[16:19], v[62:63], off offset:32
	s_waitcnt lgkmcnt(0)
	v_mul_f32_e32 v15, 0xbfb8aa3b, v30
	v_exp_f32_e32 v26, v15
	v_mul_f32_e32 v15, 0xbfb8aa3b, v31
	v_exp_f32_e32 v28, v15
	v_mul_f32_e32 v15, 0xbfb8aa3b, v32
	v_exp_f32_e32 v27, v15
	v_mov_b32_e32 v62, v10
	v_mov_b32_e32 v63, v12
	v_pk_mul_f32 v[62:63], v[62:63], v[14:15] op_sel_hi:[1,0]
	v_pk_add_f32 v[26:27], v[26:27], 1.0 op_sel_hi:[1,0]
	v_mov_b32_e32 v64, v22
	v_div_scale_f32 v10, s[8:9], v27, v27, v32
	v_rcp_f32_e32 v12, v10
	v_mov_b32_e32 v65, v24
	v_pk_mul_f32 v[110:111], v[114:115], v[110:111]
	v_pk_mul_f32 v[62:63], v[62:63], v[64:65]
	v_fma_f32 v15, -v10, v12, 1.0
	v_fmac_f32_e32 v12, v15, v12
	v_div_scale_f32 v15, vcc, v32, v27, v32
	v_mul_f32_e32 v22, v15, v12
	v_fma_f32 v24, -v10, v22, v15
	v_fmac_f32_e32 v22, v24, v12
	v_fma_f32 v10, -v10, v22, v15
	v_div_scale_f32 v15, s[8:9], v26, v26, v30
	v_rcp_f32_e32 v24, v15
	v_div_fmas_f32 v10, v10, v12, v22
	v_div_fixup_f32 v27, v10, v27, v32
	v_pk_mul_f32 v[110:111], v[112:113], v[110:111]
	v_fma_f32 v10, -v15, v24, 1.0
	v_fmac_f32_e32 v24, v10, v24
	v_div_scale_f32 v10, vcc, v30, v26, v30
	v_mul_f32_e32 v12, v10, v24
	v_fma_f32 v22, -v15, v12, v10
	v_fmac_f32_e32 v12, v22, v24
	v_fma_f32 v10, -v15, v12, v10
	v_div_fmas_f32 v10, v10, v24, v12
	v_mul_f32_e32 v12, 0xbfb8aa3b, v33
	v_exp_f32_e32 v29, v12
	v_div_fixup_f32 v26, v10, v26, v30
	v_mov_b32_e32 v12, v11
	v_mov_b32_e32 v24, v23
	v_pk_add_f32 v[10:11], v[28:29], 1.0 op_sel_hi:[1,0]
	v_pk_mul_f32 v[26:27], v[62:63], v[26:27]
	v_div_scale_f32 v15, s[8:9], v11, v11, v33
	v_rcp_f32_e32 v22, v15
	v_pk_mul_f32 v[12:13], v[12:13], v[14:15] op_sel_hi:[1,0]
	v_lshlrev_b32_e32 v42, 1, v54
	v_pk_mul_f32 v[12:13], v[12:13], v[24:25]
	v_fma_f32 v23, -v15, v22, 1.0
	v_fmac_f32_e32 v22, v23, v22
	v_div_scale_f32 v23, vcc, v33, v11, v33
	v_mul_f32_e32 v24, v23, v22
	v_fma_f32 v25, -v15, v24, v23
	v_fmac_f32_e32 v24, v25, v22
	v_fma_f32 v15, -v15, v24, v23
	v_div_scale_f32 v23, s[8:9], v10, v10, v31
	v_rcp_f32_e32 v25, v23
	v_div_fmas_f32 v15, v15, v22, v24
	v_div_fixup_f32 v11, v15, v11, v33
	v_fma_f32 v15, -v23, v25, 1.0
	v_fmac_f32_e32 v25, v15, v25
	v_div_scale_f32 v15, vcc, v31, v10, v31
	v_mul_f32_e32 v22, v15, v25
	v_fma_f32 v24, -v23, v22, v15
	v_fmac_f32_e32 v22, v24, v25
	v_fma_f32 v15, -v23, v22, v15
	v_div_fmas_f32 v15, v15, v25, v22
	v_div_fixup_f32 v10, v15, v10, v31
	v_pk_mul_f32 v[10:11], v[12:13], v[10:11]
	v_cvt_pk_bf16_f32 v13, v27, v11
	v_cvt_pk_bf16_f32 v11, v111, v21
	s_waitcnt vmcnt(0)
	v_mul_f32_e32 v15, 0xbfb8aa3b, v16
	v_cvt_pk_bf16_f32 v12, v26, v10
	v_cvt_pk_bf16_f32 v10, v110, v20
	v_exp_f32_e32 v20, v15
	v_mul_f32_e32 v15, 0xbfb8aa3b, v17
	v_exp_f32_e32 v22, v15
	v_mul_f32_e32 v15, 0xbfb8aa3b, v18
	v_exp_f32_e32 v21, v15
	v_mov_b32_e32 v24, v6
	v_mov_b32_e32 v25, v8
	v_pk_mul_f32 v[24:25], v[24:25], v[14:15] op_sel_hi:[1,0]
	v_pk_add_f32 v[20:21], v[20:21], 1.0 op_sel_hi:[1,0]
	v_mov_b32_e32 v26, v106
	v_div_scale_f32 v6, s[8:9], v21, v21, v18
	v_rcp_f32_e32 v8, v6
	v_mov_b32_e32 v27, v108
	v_pk_mul_f32 v[24:25], v[24:25], v[26:27]
	v_mov_b32_e32 v108, v107
	v_fma_f32 v15, -v6, v8, 1.0
	v_fmac_f32_e32 v8, v15, v8
	v_div_scale_f32 v15, vcc, v18, v21, v18
	v_mul_f32_e32 v23, v15, v8
	v_fma_f32 v26, -v6, v23, v15
	v_fmac_f32_e32 v23, v26, v8
	v_fma_f32 v6, -v6, v23, v15
	v_div_scale_f32 v15, s[8:9], v20, v20, v16
	v_rcp_f32_e32 v26, v15
	v_div_fmas_f32 v6, v6, v8, v23
	v_div_fixup_f32 v21, v6, v21, v18
	v_fma_f32 v6, -v15, v26, 1.0
	v_fmac_f32_e32 v26, v6, v26
	v_div_scale_f32 v6, vcc, v16, v20, v16
	v_mul_f32_e32 v8, v6, v26
	v_fma_f32 v18, -v15, v8, v6
	v_fmac_f32_e32 v8, v18, v26
	v_fma_f32 v6, -v15, v8, v6
	v_div_fmas_f32 v6, v6, v26, v8
	v_mul_f32_e32 v8, 0xbfb8aa3b, v19
	v_exp_f32_e32 v23, v8
	v_div_fixup_f32 v20, v6, v20, v16
	v_mov_b32_e32 v8, v7
	v_pk_mul_f32 v[20:21], v[24:25], v[20:21]
	v_pk_add_f32 v[6:7], v[22:23], 1.0 op_sel_hi:[1,0]
	s_nop 0
	v_div_scale_f32 v15, s[8:9], v7, v7, v19
	v_rcp_f32_e32 v16, v15
	v_pk_mul_f32 v[8:9], v[8:9], v[14:15] op_sel_hi:[1,0]
	v_fma_f32 v18, -v15, v16, 1.0
	v_fmac_f32_e32 v16, v18, v16
	v_div_scale_f32 v18, vcc, v19, v7, v19
	v_mul_f32_e32 v22, v18, v16
	v_fma_f32 v23, -v15, v22, v18
	v_fmac_f32_e32 v22, v23, v16
	v_fma_f32 v15, -v15, v22, v18
	v_div_scale_f32 v18, s[8:9], v6, v6, v17
	v_rcp_f32_e32 v23, v18
	v_div_fmas_f32 v15, v15, v16, v22
	v_div_fixup_f32 v7, v15, v7, v19
	v_pk_mul_f32 v[8:9], v[8:9], v[108:109]
	v_fma_f32 v15, -v18, v23, 1.0
	v_fmac_f32_e32 v23, v15, v23
	v_div_scale_f32 v15, vcc, v17, v6, v17
	v_mul_f32_e32 v16, v15, v23
	v_fma_f32 v19, -v18, v16, v15
	v_fmac_f32_e32 v16, v19, v23
	v_fma_f32 v15, -v18, v16, v15
	v_div_fmas_f32 v15, v15, v23, v16
	v_div_fixup_f32 v6, v15, v6, v17
	v_pk_mul_f32 v[6:7], v[8:9], v[6:7]
	v_mul_f32_e32 v9, 0xbfb8aa3b, v35
	v_mul_f32_e32 v8, 0xbfb8aa3b, v34
	v_exp_f32_e32 v16, v9
	v_mul_f32_e32 v9, 0xbfb8aa3b, v36
	v_exp_f32_e32 v8, v8
	v_exp_f32_e32 v9, v9
	v_mov_b32_e32 v18, v2
	v_mov_b32_e32 v19, v4
	v_pk_mul_f32 v[18:19], v[18:19], v[14:15] op_sel_hi:[1,0]
	v_pk_add_f32 v[8:9], v[8:9], 1.0 op_sel_hi:[1,0]
	v_mov_b32_e32 v22, v38
	v_div_scale_f32 v2, s[8:9], v9, v9, v36
	v_rcp_f32_e32 v4, v2
	v_mov_b32_e32 v23, v40
	v_pk_mul_f32 v[18:19], v[18:19], v[22:23]
	v_mov_b32_e32 v40, v39
	v_fma_f32 v15, -v2, v4, 1.0
	v_fmac_f32_e32 v4, v15, v4
	v_div_scale_f32 v15, vcc, v36, v9, v36
	v_mul_f32_e32 v17, v15, v4
	v_fma_f32 v22, -v2, v17, v15
	v_fmac_f32_e32 v17, v22, v4
	v_fma_f32 v2, -v2, v17, v15
	v_div_scale_f32 v15, s[8:9], v8, v8, v34
	v_rcp_f32_e32 v22, v15
	v_div_fmas_f32 v2, v2, v4, v17
	v_div_fixup_f32 v9, v2, v9, v36
	v_fma_f32 v2, -v15, v22, 1.0
	v_fmac_f32_e32 v22, v2, v22
	v_div_scale_f32 v2, vcc, v34, v8, v34
	v_mul_f32_e32 v4, v2, v22
	v_fma_f32 v17, -v15, v4, v2
	v_fmac_f32_e32 v4, v17, v22
	v_fma_f32 v2, -v15, v4, v2
	v_div_fmas_f32 v2, v2, v22, v4
	v_mul_f32_e32 v4, 0xbfb8aa3b, v37
	v_exp_f32_e32 v17, v4
	v_div_fixup_f32 v8, v2, v8, v34
	v_mov_b32_e32 v4, v3
	v_pk_mul_f32 v[8:9], v[18:19], v[8:9]
	v_pk_add_f32 v[2:3], v[16:17], 1.0 op_sel_hi:[1,0]
	s_nop 0
	v_div_scale_f32 v15, s[8:9], v3, v3, v37
	v_rcp_f32_e32 v16, v15
	v_pk_mul_f32 v[4:5], v[4:5], v[14:15] op_sel_hi:[1,0]
	v_fma_f32 v14, -v15, v16, 1.0
	v_fmac_f32_e32 v16, v14, v16
	v_div_scale_f32 v14, vcc, v37, v3, v37
	v_mul_f32_e32 v17, v14, v16
	v_fma_f32 v18, -v15, v17, v14
	v_fmac_f32_e32 v17, v18, v16
	v_fma_f32 v14, -v15, v17, v14
	v_div_scale_f32 v15, s[8:9], v2, v2, v35
	v_rcp_f32_e32 v18, v15
	v_div_fmas_f32 v14, v14, v16, v17
	v_div_fixup_f32 v3, v14, v3, v37
	v_pk_mul_f32 v[4:5], v[4:5], v[40:41]
	v_fma_f32 v14, -v15, v18, 1.0
	v_fmac_f32_e32 v18, v14, v18
	v_div_scale_f32 v14, vcc, v35, v2, v35
	v_mul_f32_e32 v16, v14, v18
	v_fma_f32 v17, -v15, v16, v14
	v_fmac_f32_e32 v16, v17, v18
	v_fma_f32 v14, -v15, v16, v14
	v_div_fmas_f32 v14, v14, v18, v16
	v_div_fixup_f32 v2, v14, v2, v35
	v_pk_mul_f32 v[2:3], v[4:5], v[2:3]
	v_bfe_u32 v5, v2, 16, 1
	v_add3_u32 v2, v2, v5, s33
	v_bfe_u32 v14, v8, 16, 1
	v_add3_u32 v8, v8, v14, s33
	v_lshrrev_b32_e32 v4, 16, v8
	v_cvt_pk_bf16_f32 v5, v9, v3
	v_and_or_b32 v4, v2, s34, v4
	v_cvt_pk_bf16_f32 v3, v21, v7
	v_cvt_pk_bf16_f32 v2, v20, v6
	v_lshlrev_b64 v[6:7], 11, v[60:61]
	v_lshl_add_u64 v[6:7], s[68:69], 0, v[6:7]
	v_lshl_add_u64 v[6:7], v[6:7], 0, s[70:71]
	v_lshl_add_u64 v[6:7], v[6:7], 0, v[42:43]
	v_lshl_add_u64 v[8:9], v[6:7], 0, s[74:75]
	v_add_co_u32_e32 v6, vcc, 0xdc00000, v6
	s_nop 1
	v_addc_co_u32_e32 v7, vcc, 0, v7, vcc
	global_store_dwordx4 v[6:7], v[10:13], off offset:1024
	global_store_dwordx4 v[8:9], v[2:5], off offset:16
	s_branch .LBB0_2949

.LBB0_3084:
	s_or_b64 exec, exec, s[10:11]
	v_mov_b32_e32 v1, v0
	v_mov_b64_e32 v[2:3], s[0:1]
	s_barrier
	s_load_dwordx2 s[98:99], s[0:1], 0x58
	s_waitcnt vmcnt(0) lgkmcnt(0)
	v_mov_b32_e32 v2, s98
	v_mov_b32_e32 v3, s99
	v_readfirstlane_b32 s5, v1
	s_ashr_i32 s5, s5, 4
	s_and_b32 s6, s5, -4
	s_cmp_gt_i32 s6, 63
	s_cbranch_scc1 .LBB0_3087
	v_and_b32_e32 v21, 63, v1
	v_mov_b32_e32 v91, 0
	v_lshlrev_b32_e32 v90, 4, v21
	s_waitcnt lgkmcnt(0)
	v_lshl_add_u64 v[2:3], v[2:3], 0, v[90:91]
	s_movk_i32 s5, 0x2000
	v_add_co_u32_e32 v18, vcc, s5, v2
	v_mbcnt_lo_u32_b32 v1, -1, 0
	s_nop 0
	v_addc_co_u32_e32 v19, vcc, 0, v3, vcc
	global_load_dwordx4 v[2:5], v[18:19], off
	global_load_dwordx4 v[6:9], v[18:19], off offset:1024
	global_load_dwordx4 v[10:13], v[18:19], off offset:2048
	global_load_dwordx4 v[14:17], v[18:19], off offset:3072
	v_mbcnt_hi_u32_b32 v18, -1, v1
	v_and_b32_e32 v1, 64, v18
	v_add_u32_e32 v19, 64, v1
	v_xor_b32_e32 v1, 1, v18
	v_cmp_lt_i32_e32 vcc, v1, v19
	v_xor_b32_e32 v20, 2, v18
	s_lshl_b32 s7, s28, 8
	v_cndmask_b32_e32 v1, v18, v1, vcc
	v_cmp_lt_i32_e32 vcc, v20, v19
	s_lshl_b32 s4, s4, 6
	s_add_i32 s8, s7, s4
	v_cndmask_b32_e32 v20, v18, v20, vcc
	v_lshlrev_b32_e32 v166, 2, v20
	v_xor_b32_e32 v20, 4, v18
	v_cmp_lt_i32_e32 vcc, v20, v19
	s_add_i32 s10, s6, s8
	s_add_u32 s4, s68, 0x5800000
	v_cndmask_b32_e32 v20, v18, v20, vcc
	v_lshlrev_b32_e32 v167, 2, v20
	v_xor_b32_e32 v20, 8, v18
	v_cmp_lt_i32_e32 vcc, v20, v19
	s_addc_u32 s5, s69, 0
	s_lshl_b32 s3, s3, 6
	v_cndmask_b32_e32 v20, v18, v20, vcc
	v_lshlrev_b32_e32 v168, 2, v20
	v_xor_b32_e32 v20, 16, v18
	v_cmp_lt_i32_e32 vcc, v20, v19
	s_add_i32 s3, s7, s3
	s_add_i32 s3, s3, s6
	v_cndmask_b32_e32 v20, v18, v20, vcc
	v_lshlrev_b32_e32 v169, 2, v20
	v_xor_b32_e32 v20, 32, v18
	v_cmp_lt_i32_e32 vcc, v20, v19
	s_lshl_b32 s2, s2, 6
	s_sub_i32 s2, s3, s2
	v_cndmask_b32_e32 v18, v18, v20, vcc
	s_ashr_i32 s11, s10, 31
	v_lshlrev_b32_e32 v170, 2, v18
	v_lshlrev_b32_e32 v18, 2, v21
	s_or_b32 s20, s8, 32
	s_sub_i32 s8, s2, 32
	s_lshl_b64 s[2:3], s[10:11], 11
	v_or_b32_e32 v20, 0x100, v18
	v_or_b32_e32 v22, 0x200, v18
	v_or_b32_e32 v24, 0x300, v18
	v_lshl_or_b32 v92, v21, 3, s2
	v_mov_b32_e32 v93, s3
	s_lshl_b64 s[2:3], s[10:11], 12
	v_lshlrev_b32_e32 v1, 2, v1
	v_or_b32_e32 v94, s2, v90
	v_mov_b32_e32 v95, s3
	v_mov_b32_e32 v171, 0x358637bd
	s_mov_b32 s2, 0xf800000
	v_mov_b32_e32 v172, 0x260
	v_lshlrev_b32_e32 v90, 2, v18
	s_movk_i32 s3, 0x7fff
	s_mov_b32 s21, 0xffff0000
	s_mov_b32 s22, 0xba00000
	v_lshlrev_b32_e32 v96, 2, v20
	v_lshlrev_b32_e32 v98, 2, v22
	v_mov_b32_e32 v99, v91
	v_lshlrev_b32_e32 v100, 2, v24
	v_mov_b32_e32 v101, v91
	s_mov_b32 s23, 0xba01000
	s_mov_b64 s[12:13], 0x10000
	s_mov_b64 s[14:15], 0x20000
	v_mov_b32_e32 v97, v91

.LBB0_3192:
	s_or_b64 exec, exec, s[6:7]
	v_mov_b32_e32 v1, v0
	v_mov_b64_e32 v[2:3], s[0:1]
	s_barrier
	s_load_dwordx2 s[98:99], s[0:1], 0x58
	s_waitcnt vmcnt(0) lgkmcnt(0)
	v_mov_b32_e32 v2, s98
	v_mov_b32_e32 v3, s99
	v_readfirstlane_b32 s5, v1
	s_ashr_i32 s6, s5, 6
	s_cmp_gt_i32 s6, 7
	s_cbranch_scc1 .LBB0_3195
	v_and_b32_e32 v21, 63, v1
	v_mov_b32_e32 v91, 0
	v_lshlrev_b32_e32 v90, 4, v21
	s_waitcnt lgkmcnt(0)
	v_lshl_add_u64 v[2:3], v[2:3], 0, v[90:91]
	s_movk_i32 s5, 0x3000
	v_add_co_u32_e32 v18, vcc, s5, v2
	v_mbcnt_lo_u32_b32 v1, -1, 0
	s_nop 0
	v_addc_co_u32_e32 v19, vcc, 0, v3, vcc
	global_load_dwordx4 v[2:5], v[18:19], off
	global_load_dwordx4 v[6:9], v[18:19], off offset:1024
	global_load_dwordx4 v[10:13], v[18:19], off offset:2048
	global_load_dwordx4 v[14:17], v[18:19], off offset:3072
	v_mbcnt_hi_u32_b32 v18, -1, v1
	v_and_b32_e32 v1, 64, v18
	v_add_u32_e32 v19, 64, v1
	v_xor_b32_e32 v1, 1, v18
	v_cmp_lt_i32_e32 vcc, v1, v19
	v_xor_b32_e32 v20, 2, v18
	s_lshl_b32 s7, s16, 5
	v_cndmask_b32_e32 v1, v18, v1, vcc
	v_cmp_lt_i32_e32 vcc, v20, v19
	s_lshl_b32 s6, s6, 2
	s_add_i32 s6, s7, s6
	v_cndmask_b32_e32 v20, v18, v20, vcc
	v_lshlrev_b32_e32 v148, 2, v20
	v_xor_b32_e32 v20, 4, v18
	v_cmp_lt_i32_e32 vcc, v20, v19
	s_add_i32 s24, s6, 0x2080
	s_ashr_i32 s25, s24, 31
	v_cndmask_b32_e32 v20, v18, v20, vcc
	v_lshlrev_b32_e32 v149, 2, v20
	v_xor_b32_e32 v20, 8, v18
	v_cmp_lt_i32_e32 vcc, v20, v19
	s_add_i32 s5, s7, 0x20a0
	s_lshl_b64 s[6:7], s[24:25], 11
	v_cndmask_b32_e32 v20, v18, v20, vcc
	v_lshlrev_b32_e32 v150, 2, v20
	v_xor_b32_e32 v20, 16, v18
	v_cmp_lt_i32_e32 vcc, v20, v19
	v_lshl_or_b32 v92, v21, 3, s6
	v_mov_b32_e32 v93, s7
	v_cndmask_b32_e32 v20, v18, v20, vcc
	v_lshlrev_b32_e32 v151, 2, v20
	v_xor_b32_e32 v20, 32, v18
	v_cmp_lt_i32_e32 vcc, v20, v19
	s_lshl_b64 s[6:7], s[24:25], 12
	v_lshlrev_b32_e32 v1, 2, v1
	v_cndmask_b32_e32 v18, v18, v20, vcc
	v_lshlrev_b32_e32 v152, 2, v18
	v_lshlrev_b32_e32 v18, 2, v21
	v_or_b32_e32 v20, 0x100, v18
	v_or_b32_e32 v22, 0x200, v18
	v_or_b32_e32 v24, 0x300, v18
	v_or_b32_e32 v94, s6, v90
	v_mov_b32_e32 v95, s7
	v_mov_b32_e32 v153, 0x358637bd
	s_mov_b32 s17, 0xf800000
	v_mov_b32_e32 v154, 0x260
	v_lshlrev_b32_e32 v90, 2, v18
	s_movk_i32 s25, 0x7fff
	s_mov_b32 s28, 0xffff0000
	s_mov_b32 s29, 0xba00000
	v_lshlrev_b32_e32 v96, 2, v20
	v_lshlrev_b32_e32 v98, 2, v22
	v_mov_b32_e32 v99, v91
	v_lshlrev_b32_e32 v100, 2, v24
	v_mov_b32_e32 v101, v91
	s_mov_b32 s30, 0xba01000
	s_mov_b64 s[26:27], 0x10000
	s_mov_b64 s[38:39], 0x20000
	v_mov_b32_e32 v97, v91

.LBB0_3339:
	s_or_b64 exec, exec, s[10:11]
	v_mov_b32_e32 v1, v0
	v_mov_b64_e32 v[2:3], s[0:1]
	s_barrier
	s_load_dwordx2 s[98:99], s[0:1], 0x58
	s_waitcnt vmcnt(0) lgkmcnt(0)
	v_mov_b32_e32 v2, s98
	v_mov_b32_e32 v3, s99
	v_readfirstlane_b32 s6, v1
	s_ashr_i32 s6, s6, 6
	s_cmp_gt_i32 s6, 15
	s_cbranch_scc1 .LBB0_3342
	v_and_b32_e32 v21, 63, v1
	v_mov_b32_e32 v91, 0
	v_lshlrev_b32_e32 v90, 4, v21
	s_waitcnt lgkmcnt(0)
	v_lshl_add_u64 v[2:3], v[2:3], 0, v[90:91]
	s_movk_i32 s7, 0x3000
	v_add_co_u32_e32 v18, vcc, s7, v2
	v_mbcnt_lo_u32_b32 v1, -1, 0
	s_nop 0
	v_addc_co_u32_e32 v19, vcc, 0, v3, vcc
	global_load_dwordx4 v[2:5], v[18:19], off
	global_load_dwordx4 v[6:9], v[18:19], off offset:1024
	global_load_dwordx4 v[10:13], v[18:19], off offset:2048
	global_load_dwordx4 v[14:17], v[18:19], off offset:3072
	v_mbcnt_hi_u32_b32 v18, -1, v1
	v_and_b32_e32 v1, 64, v18
	v_add_u32_e32 v19, 64, v1
	v_xor_b32_e32 v1, 1, v18
	v_cmp_lt_i32_e32 vcc, v1, v19
	v_xor_b32_e32 v20, 2, v18
	s_lshl_b32 s7, s31, 8
	v_cndmask_b32_e32 v1, v18, v1, vcc
	v_cmp_lt_i32_e32 vcc, v20, v19
	s_lshl_b32 s8, s30, 6
	s_add_i32 s8, s7, s8
	v_cndmask_b32_e32 v20, v18, v20, vcc
	v_lshlrev_b32_e32 v148, 2, v20
	v_xor_b32_e32 v20, 4, v18
	v_cmp_lt_i32_e32 vcc, v20, v19
	s_lshl_b32 s9, s6, 2
	s_add_i32 s6, s9, s8
	v_cndmask_b32_e32 v20, v18, v20, vcc
	v_lshlrev_b32_e32 v149, 2, v20
	v_xor_b32_e32 v20, 8, v18
	v_cmp_lt_i32_e32 vcc, v20, v19
	s_or_b32 s24, s8, 32
	s_lshl_b32 s8, s29, 6
	v_cndmask_b32_e32 v20, v18, v20, vcc
	v_lshlrev_b32_e32 v150, 2, v20
	v_xor_b32_e32 v20, 16, v18
	v_cmp_lt_i32_e32 vcc, v20, v19
	s_add_i32 s7, s7, s8
	s_add_i32 s7, s7, s9
	v_cndmask_b32_e32 v20, v18, v20, vcc
	v_lshlrev_b32_e32 v151, 2, v20
	v_xor_b32_e32 v20, 32, v18
	v_cmp_lt_i32_e32 vcc, v20, v19
	s_lshl_b32 s8, s28, 6
	s_sub_i32 s7, s7, s8
	v_cndmask_b32_e32 v18, v18, v20, vcc
	v_lshlrev_b32_e32 v152, 2, v18
	v_lshlrev_b32_e32 v18, 2, v21
	s_sub_i32 s8, s7, 32
	s_ashr_i32 s7, s6, 31
	v_or_b32_e32 v20, 0x100, v18
	v_or_b32_e32 v22, 0x200, v18
	v_or_b32_e32 v24, 0x300, v18
	s_lshl_b64 s[10:11], s[6:7], 11
	s_lshl_b64 s[6:7], s[6:7], 12
	v_lshlrev_b32_e32 v1, 2, v1
	v_lshl_or_b32 v92, v21, 3, s10
	v_mov_b32_e32 v93, s11
	v_or_b32_e32 v94, s6, v90
	v_mov_b32_e32 v95, s7
	v_mov_b32_e32 v153, 0x358637bd
	s_mov_b32 s25, 0xf800000
	v_mov_b32_e32 v154, 0x260
	v_lshlrev_b32_e32 v90, 2, v18
	s_movk_i32 s26, 0x7fff
	s_mov_b32 s27, 0xffff0000
	s_mov_b32 s28, 0xba00000
	v_lshlrev_b32_e32 v96, 2, v20
	v_lshlrev_b32_e32 v98, 2, v22
	v_mov_b32_e32 v99, v91
	v_lshlrev_b32_e32 v100, 2, v24
	v_mov_b32_e32 v101, v91
	s_mov_b32 s29, 0xba01000
	s_mov_b64 s[16:17], 0x10000
	s_mov_b64 s[18:19], 0x20000
	v_mov_b32_e32 v97, v91

.LBB0_3447:
	s_or_b64 exec, exec, s[6:7]
	v_mov_b32_e32 v1, v0
	v_mov_b64_e32 v[2:3], s[0:1]
	s_barrier
	s_load_dwordx2 s[98:99], s[0:1], 0x58
	s_waitcnt vmcnt(0) lgkmcnt(0)
	v_mov_b32_e32 v2, s98
	v_mov_b32_e32 v3, s99
	v_readfirstlane_b32 s5, v1
	s_ashr_i32 s5, s5, 6
	s_cmp_gt_i32 s5, 7
	v_and_b32_e32 v131, 63, v1
	s_cbranch_scc1 .LBB0_3450
	v_mov_b32_e32 v91, 0
	v_lshlrev_b32_e32 v90, 4, v131
	s_waitcnt lgkmcnt(0)
	v_lshl_add_u64 v[2:3], v[2:3], 0, v[90:91]
	s_movk_i32 s6, 0x4000
	v_add_co_u32_e32 v18, vcc, s6, v2
	s_lshl_b32 s6, s40, 5
	s_nop 0
	v_addc_co_u32_e32 v19, vcc, 0, v3, vcc
	global_load_dwordx4 v[2:5], v[18:19], off
	global_load_dwordx4 v[6:9], v[18:19], off offset:1024
	global_load_dwordx4 v[10:13], v[18:19], off offset:2048
	global_load_dwordx4 v[14:17], v[18:19], off offset:3072
	v_mbcnt_lo_u32_b32 v18, -1, 0
	v_mbcnt_hi_u32_b32 v18, -1, v18
	v_and_b32_e32 v19, 64, v18
	v_add_u32_e32 v19, 64, v19
	v_xor_b32_e32 v20, 1, v18
	v_cmp_lt_i32_e32 vcc, v20, v19
	s_lshl_b32 s7, s5, 2
	s_add_i32 s13, s6, 0x20a0
	v_cndmask_b32_e32 v20, v18, v20, vcc
	v_lshlrev_b32_e32 v133, 2, v20
	v_xor_b32_e32 v20, 2, v18
	v_cmp_lt_i32_e32 vcc, v20, v19
	s_add_i32 s6, s6, s7
	s_add_i32 s20, s6, 0x2080
	v_cndmask_b32_e32 v20, v18, v20, vcc
	v_lshlrev_b32_e32 v152, 2, v20
	v_xor_b32_e32 v20, 4, v18
	v_cmp_lt_i32_e32 vcc, v20, v19
	s_add_u32 s26, s38, 0x5803000
	s_addc_u32 s27, s39, 0
	v_cndmask_b32_e32 v20, v18, v20, vcc
	v_lshlrev_b32_e32 v153, 2, v20
	v_xor_b32_e32 v20, 8, v18
	v_cmp_lt_i32_e32 vcc, v20, v19
	s_ashr_i32 s21, s20, 31
	s_lshl_b64 s[6:7], s[20:21], 11
	v_cndmask_b32_e32 v20, v18, v20, vcc
	v_lshlrev_b32_e32 v154, 2, v20
	v_xor_b32_e32 v20, 16, v18
	v_cmp_lt_i32_e32 vcc, v20, v19
	v_lshl_or_b32 v92, v131, 3, s6
	v_mov_b32_e32 v93, s7
	v_cndmask_b32_e32 v20, v18, v20, vcc
	v_lshlrev_b32_e32 v155, 2, v20
	v_xor_b32_e32 v20, 32, v18
	v_cmp_lt_i32_e32 vcc, v20, v19
	s_lshl_b64 s[6:7], s[20:21], 12
	v_or_b32_e32 v94, s6, v90
	v_cndmask_b32_e32 v18, v18, v20, vcc
	v_lshlrev_b32_e32 v156, 2, v18
	v_lshlrev_b32_e32 v18, 2, v131
	v_or_b32_e32 v20, 0x100, v18
	v_or_b32_e32 v22, 0x200, v18
	v_or_b32_e32 v24, 0x300, v18
	v_mov_b32_e32 v95, s7
	v_mov_b32_e32 v157, 0x358637bd
	s_mov_b32 s21, 0xf800000
	v_mov_b32_e32 v158, 0x260
	v_lshlrev_b32_e32 v90, 2, v18
	s_movk_i32 s28, 0x7fff
	s_mov_b32 s29, 0xffff0000
	s_mov_b32 s30, 0xba00000
	v_lshlrev_b32_e32 v96, 2, v20
	v_mov_b32_e32 v97, v91
	v_lshlrev_b32_e32 v98, 2, v22
	v_mov_b32_e32 v99, v91
	v_lshlrev_b32_e32 v100, 2, v24
	v_mov_b32_e32 v101, v91
	s_mov_b32 s31, 0xba01000
	s_mov_b64 s[22:23], 0x10000
	s_mov_b64 s[24:25], 0x20000

.LBB0_3609:
	s_or_b64 exec, exec, s[10:11]
	v_mov_b32_e32 v130, v0
	v_mov_b64_e32 v[2:3], s[0:1]
	s_barrier
	s_load_dwordx2 s[98:99], s[0:1], 0x58
	s_waitcnt vmcnt(0) lgkmcnt(0)
	v_mov_b32_e32 v2, s98
	v_mov_b32_e32 v3, s99
	v_readfirstlane_b32 s6, v130
	s_ashr_i32 s96, s6, 6
	s_add_i32 s12, s96, s2
	s_cmp_gt_i32 s96, 15
	v_and_b32_e32 v132, 63, v130
	s_cbranch_scc1 .LBB0_3612
	v_mov_b32_e32 v91, 0
	v_lshlrev_b32_e32 v90, 4, v132
	s_waitcnt lgkmcnt(0)
	v_lshl_add_u64 v[2:3], v[2:3], 0, v[90:91]
	s_movk_i32 s2, 0x4000
	v_add_co_u32_e32 v18, vcc, s2, v2
	v_mbcnt_lo_u32_b32 v1, -1, 0
	s_nop 0
	v_addc_co_u32_e32 v19, vcc, 0, v3, vcc
	global_load_dwordx4 v[2:5], v[18:19], off
	global_load_dwordx4 v[6:9], v[18:19], off offset:1024
	global_load_dwordx4 v[10:13], v[18:19], off offset:2048
	global_load_dwordx4 v[14:17], v[18:19], off offset:3072
	v_mbcnt_hi_u32_b32 v18, -1, v1
	v_and_b32_e32 v1, 64, v18
	v_add_u32_e32 v19, 64, v1
	v_xor_b32_e32 v1, 1, v18
	v_cmp_lt_i32_e32 vcc, v1, v19
	v_xor_b32_e32 v20, 2, v18
	s_lshl_b32 s7, s26, 8
	v_cndmask_b32_e32 v1, v18, v1, vcc
	v_cmp_lt_i32_e32 vcc, v20, v19
	s_lshl_b32 s2, s5, 6
	s_add_i32 s8, s7, s2
	v_cndmask_b32_e32 v20, v18, v20, vcc
	v_lshlrev_b32_e32 v131, 2, v20
	v_xor_b32_e32 v20, 4, v18
	v_cmp_lt_i32_e32 vcc, v20, v19
	s_lshl_b32 s9, s96, 2
	s_add_i32 s6, s9, s8
	v_cndmask_b32_e32 v20, v18, v20, vcc
	v_lshlrev_b32_e32 v133, 2, v20
	v_xor_b32_e32 v20, 8, v18
	v_cmp_lt_i32_e32 vcc, v20, v19
	s_add_u32 s2, s38, 0x5803000
	s_addc_u32 s5, s39, 0
	v_cndmask_b32_e32 v20, v18, v20, vcc
	v_lshlrev_b32_e32 v152, 2, v20
	v_xor_b32_e32 v20, 16, v18
	v_cmp_lt_i32_e32 vcc, v20, v19
	s_lshl_b32 s4, s4, 6
	s_add_i32 s4, s7, s4
	v_cndmask_b32_e32 v20, v18, v20, vcc
	v_lshlrev_b32_e32 v153, 2, v20
	v_xor_b32_e32 v20, 32, v18
	v_cmp_lt_i32_e32 vcc, v20, v19
	s_add_i32 s4, s4, s9
	s_lshl_b32 s3, s3, 6
	v_cndmask_b32_e32 v18, v18, v20, vcc
	v_lshlrev_b32_e32 v154, 2, v18
	v_lshlrev_b32_e32 v18, 2, v132
	s_ashr_i32 s7, s6, 31
	v_or_b32_e32 v20, 0x100, v18
	v_or_b32_e32 v22, 0x200, v18
	v_or_b32_e32 v24, 0x300, v18
	s_sub_i32 s3, s4, s3
	s_lshl_b64 s[10:11], s[6:7], 11
	s_lshl_b64 s[6:7], s[6:7], 12
	v_lshlrev_b32_e32 v1, 2, v1
	s_or_b32 s13, s8, 32
	s_sub_i32 s8, s3, 32
	v_lshl_or_b32 v92, v132, 3, s10
	v_mov_b32_e32 v93, s11
	v_or_b32_e32 v94, s6, v90
	v_mov_b32_e32 v95, s7
	v_mov_b32_e32 v155, 0x358637bd
	s_mov_b32 s3, 0xf800000
	v_mov_b32_e32 v156, 0x260
	v_lshlrev_b32_e32 v90, 2, v18
	s_movk_i32 s4, 0x7fff
	s_mov_b32 s22, 0xffff0000
	s_mov_b32 s23, 0xba00000
	v_lshlrev_b32_e32 v96, 2, v20
	v_mov_b32_e32 v97, v91
	v_lshlrev_b32_e32 v98, 2, v22
	v_mov_b32_e32 v99, v91
	v_lshlrev_b32_e32 v100, 2, v24
	v_mov_b32_e32 v101, v91
	s_mov_b32 s24, 0xba01000
	s_mov_b64 s[14:15], 0x10000
	s_mov_b64 s[18:19], 0x20000

.LBB0_4198:
	v_mov_b32_e32 v180, v0
	s_mov_b64 s[6:7], -1
	v_readfirstlane_b32 s22, v180
	s_ashr_i32 s10, s22, 6
	v_and_b32_e32 v182, 63, v180
	s_cmp_eq_u32 s2, s33
	s_cbranch_scc1 .LBB0_4204
	s_waitcnt lgkmcnt(0)
	v_mov_b64_e32 v[2:3], s[0:1]
	s_load_dwordx2 s[98:99], s[0:1], 0x40
	s_waitcnt vmcnt(0) lgkmcnt(0)
	v_mov_b32_e32 v4, s98
	v_mov_b32_e32 v5, s99
	s_load_dwordx2 s[98:99], s[0:1], 0x20
	s_waitcnt vmcnt(0) lgkmcnt(0)
	v_mov_b32_e32 v8, s98
	v_mov_b32_e32 v9, s99
	v_ashrrev_i32_e32 v41, 5, v180
	v_lshlrev_b32_e32 v2, 14, v41
	v_and_b32_e32 v178, 0x1c000, v2
	s_mov_b32 s81, s57
	v_lshlrev_b32_e32 v40, 4, v180
	s_mov_b64 s[6:7], 0x14000000
	v_and_b32_e32 v6, 0xf0, v40
	v_mov_b32_e32 v7, v179
	s_lshl_b32 s2, s10, 5
	v_and_b32_e32 v203, 31, v180
	v_lshrrev_b32_e32 v181, 5, v182
	s_mov_b64 s[8:9], 0
	s_waitcnt lgkmcnt(0)
	v_lshl_add_u64 v[24:25], s[54:55], 2, v[4:5]
	v_lshl_add_u64 v[2:3], v[8:9], 0, v[178:179]
	v_lshl_add_u64 v[4:5], v[2:3], 0, s[80:81]
	v_and_b32_e32 v2, 0x100, v40
	v_mov_b32_e32 v3, v179
	v_lshl_add_u64 v[4:5], v[4:5], 0, v[2:3]
	v_lshl_add_u64 v[10:11], v[4:5], 0, s[6:7]
	v_ashrrev_i32_e32 v4, 8, v180
	v_ashrrev_i32_e32 v5, 31, v4
	v_lshl_add_u64 v[4:5], v[4:5], 2, v[24:25]
	global_load_dword v4, v[4:5], off
	v_add_u32_e32 v3, 16, v41
	s_and_b32 s6, s2, 0xffffffc0
	s_lshl_b32 s2, s10, 7
	s_and_b32 s11, s2, 0x80
	s_mov_b32 s2, 0x20000
	v_lshl_add_u64 v[8:9], v[8:9], 0, s[76:77]
	s_waitcnt vmcnt(0)
	v_ashrrev_i32_e32 v5, 31, v4
	v_lshlrev_b64 v[4:5], 17, v[4:5]
	v_lshl_add_u64 v[12:13], v[10:11], 0, v[4:5]
	v_lshl_add_u64 v[18:19], v[12:13], 0, v[6:7]
	v_ashrrev_i32_e32 v12, 3, v3
	v_ashrrev_i32_e32 v13, 31, v12
	v_lshl_add_u64 v[12:13], v[12:13], 2, v[24:25]
	global_load_dword v12, v[12:13], off
	v_add_u32_e32 v3, 32, v41
	v_or_b32_e32 v4, v4, v178
	v_or3_b32 v4, v4, v2, v6
	v_lshl_add_u64 v[200:201], v[8:9], 0, v[4:5]
	s_waitcnt vmcnt(0)
	v_ashrrev_i32_e32 v13, 31, v12
	v_lshlrev_b64 v[12:13], 17, v[12:13]
	v_lshl_add_u64 v[14:15], v[10:11], 0, v[12:13]
	v_lshl_add_u64 v[22:23], v[14:15], 0, v[6:7]
	v_ashrrev_i32_e32 v14, 3, v3
	v_ashrrev_i32_e32 v15, 31, v14
	v_lshl_add_u64 v[14:15], v[14:15], 2, v[24:25]
	global_load_dword v14, v[14:15], off
	v_add_u32_e32 v3, 48, v41
	v_or_b32_e32 v12, v12, v178
	v_or3_b32 v12, v12, v2, v6
	v_lshl_add_u64 v[198:199], v[8:9], 0, v[12:13]
	s_waitcnt vmcnt(0)
	v_ashrrev_i32_e32 v15, 31, v14
	v_lshlrev_b64 v[14:15], 17, v[14:15]
	v_lshl_add_u64 v[16:17], v[10:11], 0, v[14:15]
	v_lshl_add_u64 v[28:29], v[16:17], 0, v[6:7]
	v_ashrrev_i32_e32 v16, 3, v3
	v_ashrrev_i32_e32 v17, 31, v16
	v_lshl_add_u64 v[16:17], v[16:17], 2, v[24:25]
	global_load_dword v16, v[16:17], off
	v_add_u32_e32 v3, 64, v41
	v_or_b32_e32 v14, v14, v178
	v_or3_b32 v14, v14, v2, v6
	v_lshl_add_u64 v[196:197], v[8:9], 0, v[14:15]
	s_waitcnt vmcnt(0)
	v_ashrrev_i32_e32 v17, 31, v16
	v_lshlrev_b64 v[16:17], 17, v[16:17]
	v_lshl_add_u64 v[20:21], v[10:11], 0, v[16:17]
	v_lshl_add_u64 v[32:33], v[20:21], 0, v[6:7]
	v_ashrrev_i32_e32 v20, 3, v3
	v_ashrrev_i32_e32 v21, 31, v20
	v_lshl_add_u64 v[20:21], v[20:21], 2, v[24:25]
	global_load_dword v20, v[20:21], off
	v_add_u32_e32 v3, 0x50, v41
	v_or_b32_e32 v16, v16, v178
	v_or3_b32 v16, v16, v2, v6
	v_lshl_add_u64 v[194:195], v[8:9], 0, v[16:17]
	s_waitcnt vmcnt(0)
	v_ashrrev_i32_e32 v21, 31, v20
	v_lshlrev_b64 v[20:21], 17, v[20:21]
	v_lshl_add_u64 v[26:27], v[10:11], 0, v[20:21]
	v_lshl_add_u64 v[34:35], v[26:27], 0, v[6:7]
	v_ashrrev_i32_e32 v26, 3, v3
	v_ashrrev_i32_e32 v27, 31, v26
	v_lshl_add_u64 v[26:27], v[26:27], 2, v[24:25]
	global_load_dword v26, v[26:27], off
	v_add_u32_e32 v3, 0x60, v41
	v_or_b32_e32 v20, v20, v178
	v_or3_b32 v20, v20, v2, v6
	v_lshl_add_u64 v[192:193], v[8:9], 0, v[20:21]
	s_waitcnt vmcnt(0)
	v_ashrrev_i32_e32 v27, 31, v26
	v_lshlrev_b64 v[26:27], 17, v[26:27]
	v_lshl_add_u64 v[30:31], v[10:11], 0, v[26:27]
	v_lshl_add_u64 v[36:37], v[30:31], 0, v[6:7]
	v_ashrrev_i32_e32 v30, 3, v3
	v_add_u32_e32 v3, 0x70, v41
	v_ashrrev_i32_e32 v42, 3, v3
	v_ashrrev_i32_e32 v31, 31, v30
	v_ashrrev_i32_e32 v43, 31, v42
	v_lshl_add_u64 v[30:31], v[30:31], 2, v[24:25]
	v_lshl_add_u64 v[24:25], v[42:43], 2, v[24:25]
	global_load_dword v30, v[30:31], off
	v_lshrrev_b32_e32 v3, 4, v180
	global_load_dword v24, v[24:25], off
	v_mul_lo_u32 v41, v3, s48
	v_lshlrev_b32_e32 v3, 3, v180
	v_and_b32_e32 v3, 0x78, v3
	s_waitcnt vmcnt(1)
	v_ashrrev_i32_e32 v31, 31, v30
	v_lshlrev_b64 v[30:31], 17, v[30:31]
	s_waitcnt vmcnt(0)
	v_ashrrev_i32_e32 v25, 31, v24
	v_lshlrev_b64 v[24:25], 17, v[24:25]
	v_lshl_add_u64 v[38:39], v[10:11], 0, v[30:31]
	v_lshl_add_u64 v[10:11], v[10:11], 0, v[24:25]
	v_lshl_add_u64 v[42:43], v[10:11], 0, v[6:7]
	v_ashrrev_i32_e32 v10, 3, v180
	v_ashrrev_i32_e32 v11, 31, v10
	v_lshlrev_b64 v[44:45], 11, v[10:11]
	v_mul_lo_u32 v48, v10, s48
	v_and_b32_e32 v10, 0x70, v40
	v_or_b32_e32 v11, s11, v203
	v_mov_b32_e32 v40, s94
	v_lshl_add_u64 v[46:47], s[58:59], 0, v[44:45]
	v_mad_u32_u24 v40, v11, s48, v40
	v_mov_b32_e32 v11, v179
	v_lshl_add_u64 v[38:39], v[38:39], 0, v[6:7]
	global_load_dwordx4 v[130:133], v[18:19], off nt
	global_load_dwordx4 v[134:137], v[22:23], off nt
	global_load_dwordx4 v[138:141], v[28:29], off nt
	global_load_dwordx4 v[142:145], v[32:33], off nt
	global_load_dwordx4 v[146:149], v[34:35], off nt
	global_load_dwordx4 v[150:153], v[36:37], off nt
	global_load_dwordx4 v[154:157], v[38:39], off nt
	global_load_dwordx4 v[158:161], v[42:43], off nt
	v_lshl_add_u64 v[22:23], v[46:47], 0, v[10:11]
	v_add_co_u32_e32 v28, vcc, s2, v22
	s_mov_b32 s2, 0x40000
	s_nop 0
	v_addc_co_u32_e32 v29, vcc, 0, v23, vcc
	global_load_dwordx4 v[162:165], v[22:23], off
	global_load_dwordx4 v[166:169], v[28:29], off
	v_add_co_u32_e32 v28, vcc, s2, v22
	s_mov_b32 s2, 0x60000
	s_nop 0
	v_addc_co_u32_e32 v29, vcc, 0, v23, vcc
	v_add_co_u32_e32 v22, vcc, s2, v22
	global_load_dwordx4 v[170:173], v[28:29], off
	s_nop 0
	v_addc_co_u32_e32 v23, vcc, 0, v23, vcc
	global_load_dwordx4 v[174:177], v[22:23], off
	v_or_b32_e32 v22, v24, v178
	v_or_b32_e32 v7, s6, v203
	v_or3_b32 v24, v22, v2, v6
	v_or_b32_e32 v22, v30, v178
	v_mul_lo_u32 v49, v7, s48
	v_or3_b32 v30, v22, v2, v6
	v_or_b32_e32 v22, v26, v178
	v_lshlrev_b32_e32 v7, 4, v181
	v_add_u32_e32 v11, s94, v41
	v_add_u32_e32 v18, s94, v48
	v_add_u32_e32 v19, s94, v49
	v_or_b32_e32 v44, v44, v10
	v_or3_b32 v26, v22, v2, v6
	v_mov_b32_e32 v2, 0
	v_lshl_add_u64 v[184:185], s[74:75], 0, v[44:45]
	v_lshl_add_u64 v[186:187], v[8:9], 0, v[24:25]
	v_lshl_add_u64 v[188:189], v[8:9], 0, v[30:31]
	v_lshl_add_u64 v[190:191], v[8:9], 0, v[26:27]
	v_add_u32_e32 v178, v11, v3
	v_add_u32_e32 v204, v18, v10
	v_add_u32_e32 v205, v19, v7
	v_add_u32_e32 v206, v40, v7
	v_mov_b32_e32 v3, v2
	v_mov_b32_e32 v4, v2
	v_mov_b32_e32 v5, v2
	v_mov_b32_e32 v6, v2
	v_mov_b32_e32 v7, v2
	v_mov_b32_e32 v8, v2
	v_mov_b32_e32 v9, v2
	v_mov_b32_e32 v10, v2
	v_mov_b32_e32 v11, v2
	v_mov_b32_e32 v12, v2
	v_mov_b32_e32 v13, v2
	v_mov_b32_e32 v14, v2
	v_mov_b32_e32 v15, v2
	v_mov_b32_e32 v16, v2
	v_mov_b32_e32 v17, v2
	v_mov_b32_e32 v18, v2
	v_mov_b32_e32 v19, v2
	v_mov_b32_e32 v20, v2
	v_mov_b32_e32 v21, v2
	v_mov_b32_e32 v22, v2
	v_mov_b32_e32 v23, v2
	v_mov_b32_e32 v24, v2
	v_mov_b32_e32 v25, v2
	v_mov_b32_e32 v26, v2
	v_mov_b32_e32 v27, v2
	v_mov_b32_e32 v28, v2
	v_mov_b32_e32 v29, v2
	v_mov_b32_e32 v30, v2
	v_mov_b32_e32 v31, v2
	v_mov_b32_e32 v32, v2
	v_mov_b32_e32 v33, v2
	v_mov_b32_e32 v34, v2
	v_mov_b32_e32 v35, v2
	v_mov_b32_e32 v36, v2
	v_mov_b32_e32 v37, v2
	v_mov_b32_e32 v38, v2
	v_mov_b32_e32 v39, v2
	v_mov_b32_e32 v40, v2
	v_mov_b32_e32 v41, v2
	v_mov_b32_e32 v42, v2
	v_mov_b32_e32 v43, v2
	v_mov_b32_e32 v44, v2
	v_mov_b32_e32 v45, v2
	v_mov_b32_e32 v46, v2
	v_mov_b32_e32 v47, v2
	v_mov_b32_e32 v48, v2
	v_mov_b32_e32 v49, v2
	v_mov_b32_e32 v50, v2
	v_mov_b32_e32 v51, v2
	v_mov_b32_e32 v52, v2
	v_mov_b32_e32 v53, v2
	v_mov_b32_e32 v54, v2
	v_mov_b32_e32 v55, v2
	v_mov_b32_e32 v56, v2
	v_mov_b32_e32 v57, v2
	v_mov_b32_e32 v58, v2
	v_mov_b32_e32 v59, v2
	v_mov_b32_e32 v60, v2
	v_mov_b32_e32 v61, v2
	v_mov_b32_e32 v62, v2
	v_mov_b32_e32 v63, v2
	v_mov_b32_e32 v64, v2
	v_mov_b32_e32 v65, v2
	v_mov_b32_e32 v66, v2
	v_mov_b32_e32 v67, v2
	v_mov_b32_e32 v68, v2
	v_mov_b32_e32 v69, v2
	v_mov_b32_e32 v70, v2
	v_mov_b32_e32 v71, v2
	v_mov_b32_e32 v72, v2
	v_mov_b32_e32 v73, v2
	v_mov_b32_e32 v74, v2
	v_mov_b32_e32 v75, v2
	v_mov_b32_e32 v76, v2
	v_mov_b32_e32 v77, v2
	v_mov_b32_e32 v78, v2
	v_mov_b32_e32 v79, v2
	v_mov_b32_e32 v80, v2
	v_mov_b32_e32 v81, v2
	v_mov_b32_e32 v82, v2
	v_mov_b32_e32 v83, v2
	v_mov_b32_e32 v84, v2
	v_mov_b32_e32 v85, v2
	v_mov_b32_e32 v86, v2
	v_mov_b32_e32 v87, v2
	v_mov_b32_e32 v88, v2
	v_mov_b32_e32 v89, v2
	v_mov_b32_e32 v90, v2
	v_mov_b32_e32 v91, v2
	v_mov_b32_e32 v92, v2
	v_mov_b32_e32 v93, v2
	v_mov_b32_e32 v94, v2
	v_mov_b32_e32 v95, v2
	v_mov_b32_e32 v96, v2
	v_mov_b32_e32 v97, v2
	v_mov_b32_e32 v98, v2
	v_mov_b32_e32 v99, v2
	v_mov_b32_e32 v100, v2
	v_mov_b32_e32 v101, v2
	v_mov_b32_e32 v102, v2
	v_mov_b32_e32 v103, v2
	v_mov_b32_e32 v104, v2
	v_mov_b32_e32 v105, v2
	v_mov_b32_e32 v106, v2
	v_mov_b32_e32 v107, v2
	v_mov_b32_e32 v108, v2
	v_mov_b32_e32 v109, v2
	v_mov_b32_e32 v110, v2
	v_mov_b32_e32 v111, v2
	v_mov_b32_e32 v112, v2
	v_mov_b32_e32 v113, v2
	v_mov_b32_e32 v114, v2
	v_mov_b32_e32 v115, v2
	v_mov_b32_e32 v116, v2
	v_mov_b32_e32 v117, v2
	v_mov_b32_e32 v118, v2
	v_mov_b32_e32 v119, v2
	v_mov_b32_e32 v120, v2
	v_mov_b32_e32 v121, v2
	v_mov_b32_e32 v122, v2
	v_mov_b32_e32 v123, v2
	v_mov_b32_e32 v124, v2
	v_mov_b32_e32 v125, v2
	v_mov_b32_e32 v126, v2
	v_mov_b32_e32 v127, v2
	v_mov_b32_e32 v128, v2
	v_mov_b32_e32 v129, v2
	s_branch .LBB0_4201

.LBB0_4234:
	s_load_dwordx2 s[98:99], s[0:1], 0x98
	s_waitcnt vmcnt(0) lgkmcnt(0)
	v_mov_b32_e32 v44, s98
	v_mov_b32_e32 v45, s99
	v_and_b32_e32 v46, 0xffffff00, v43
	v_ashrrev_i32_e32 v47, 31, v46
	v_add_u32_e32 v21, 0x200, v21
	s_waitcnt lgkmcnt(0)
	v_lshl_add_u64 v[44:45], v[46:47], 2, v[44:45]
	v_lshl_add_u64 v[44:45], v[44:45], 0, s[12:13]
	v_lshl_add_u64 v[44:45], v[44:45], 0, v[22:23]
	v_add_co_u32_e32 v44, vcc, 0x4000, v44
	s_nop 1
	v_addc_co_u32_e32 v45, vcc, 0, v45, vcc
	global_load_dword v44, v[44:45], off
	v_cmp_lt_i32_e32 vcc, s14, v21
	v_add_u32_e32 v45, s4, v43
	v_add_u32_e32 v43, 0x800, v43
	s_or_b64 s[10:11], vcc, s[10:11]
	s_waitcnt vmcnt(0)
	ds_write_b32 v45, v44
	s_andn2_b64 exec, exec, s[10:11]
	s_cbranch_execnz .LBB0_4234

.LBB0_4237:
	s_load_dwordx2 s[98:99], s[0:1], 0xa0
	s_waitcnt vmcnt(0) lgkmcnt(0)
	v_mov_b32_e32 v44, s98
	v_mov_b32_e32 v45, s99
	v_ashrrev_i32_e32 v46, 6, v43
	v_ashrrev_i32_e32 v47, 31, v46
	v_lshl_add_u64 v[48:49], s[6:7], 0, v[46:47]
	v_add_u32_e32 v79, 0x200, v43
	v_cmp_lt_i32_e32 vcc, s15, v43
	v_lshl_add_u32 v43, v46, 2, s4
	v_mad_u64_u32 v[46:47], s[18:19], v46, s14, v[22:23]
	s_or_b64 s[10:11], vcc, s[10:11]
	s_waitcnt lgkmcnt(0)
	v_lshl_add_u64 v[44:45], v[48:49], 2, v[44:45]
	global_load_dword v78, v[44:45], off offset:1024
	ds_read2st64_b32 v[44:45], v21 offset1:1
	ds_read2st64_b32 v[48:49], v21 offset0:2 offset1:3
	ds_read2st64_b32 v[50:51], v21 offset0:4 offset1:5
	ds_read2st64_b32 v[52:53], v21 offset0:6 offset1:7
	ds_read2st64_b32 v[54:55], v21 offset0:8 offset1:9
	ds_read2st64_b32 v[56:57], v21 offset0:10 offset1:11
	ds_read2st64_b32 v[58:59], v21 offset0:12 offset1:13
	ds_read2st64_b32 v[60:61], v21 offset0:14 offset1:15
	ds_read2st64_b32 v[62:63], v43 offset1:1
	ds_read2st64_b32 v[64:65], v43 offset0:2 offset1:3
	ds_read2st64_b32 v[66:67], v43 offset0:4 offset1:5
	ds_read2st64_b32 v[68:69], v43 offset0:6 offset1:7
	ds_read2st64_b32 v[70:71], v43 offset0:8 offset1:9
	ds_read2st64_b32 v[72:73], v43 offset0:10 offset1:11
	ds_read2st64_b32 v[74:75], v43 offset0:12 offset1:13
	ds_read2st64_b32 v[76:77], v43 offset0:14 offset1:15
	s_waitcnt lgkmcnt(4)
	v_pk_mul_f32 v[52:53], v[52:53], v[68:69]
	s_waitcnt lgkmcnt(3)
	v_pk_mul_f32 v[54:55], v[54:55], v[70:71]
	s_waitcnt lgkmcnt(2)
	v_pk_mul_f32 v[56:57], v[56:57], v[72:73]
	s_waitcnt lgkmcnt(1)
	v_pk_mul_f32 v[58:59], v[58:59], v[74:75]
	s_waitcnt lgkmcnt(0)
	v_pk_mul_f32 v[60:61], v[60:61], v[76:77]
	s_waitcnt vmcnt(0)
	v_fmac_f32_e32 v78, v44, v62
	v_fmac_f32_e32 v78, v45, v63
	v_fmac_f32_e32 v78, v48, v64
	v_fmac_f32_e32 v78, v49, v65
	v_fmac_f32_e32 v78, v50, v66
	v_fmac_f32_e32 v78, v51, v67
	v_add_f32_e32 v43, v78, v52
	v_add_f32_e32 v43, v43, v53
	v_add_f32_e32 v43, v43, v54
	v_add_f32_e32 v43, v43, v55
	v_add_f32_e32 v43, v43, v56
	v_add_f32_e32 v43, v43, v57
	v_add_f32_e32 v43, v43, v58
	v_add_f32_e32 v43, v43, v59
	v_add_f32_e32 v43, v43, v60
	v_add_f32_e32 v44, v43, v61
	v_mul_f32_e64 v43, |v44|, s3
	v_exp_f32_e32 v45, v43
	v_min_f32_e32 v44, 0, v44
	v_mov_b32_e32 v43, v79
	v_add_f32_e32 v45, 1.0, v45
	v_cmp_gt_f32_e32 vcc, s5, v45
	s_nop 1
	v_cndmask_b32_e64 v47, 0, 32, vcc
	v_ldexp_f32 v45, v45, v47
	v_log_f32_e32 v45, v45
	v_cndmask_b32_e32 v47, 0, v23, vcc
	v_mul_f32_e32 v48, 0x3f317217, v45
	v_fma_f32 v48, v45, s12, -v48
	v_fmac_f32_e32 v48, 0x3377d1cf, v45
	v_fmac_f32_e32 v48, 0x3f317217, v45
	v_cmp_lt_f32_e64 vcc, |v45|, s13
	s_nop 1
	v_cndmask_b32_e32 v45, v45, v48, vcc
	v_sub_f32_e32 v45, v45, v47
	v_sub_f32_e32 v44, v44, v45
	v_mul_f32_e32 v44, 0x3d800000, v44
	ds_write_b32 v46, v44
	s_andn2_b64 exec, exec, s[10:11]
	s_cbranch_execnz .LBB0_4237

.LBB0_4321:
	v_mov_b64_e32 v[8:9], s[0:1]
	s_load_dwordx2 s[98:99], s[0:1], 0x90
	s_waitcnt vmcnt(0) lgkmcnt(0)
	v_mov_b32_e32 v8, s98
	v_mov_b32_e32 v9, s99
	v_add_u32_e32 v5, 0x200, v5
	v_cmp_lt_i32_e32 vcc, s4, v5
	s_or_b64 s[90:91], vcc, s[90:91]
	s_waitcnt lgkmcnt(0)
	v_lshl_add_u64 v[8:9], v[8:9], 0, v[2:3]
	global_load_dword v7, v[8:9], off nt
	v_lshl_add_u64 v[2:3], v[2:3], 0, s[14:15]
	s_waitcnt vmcnt(0)
	ds_write_b32 v6, v7
	v_add_u32_e32 v6, 0x800, v6
	s_andn2_b64 exec, exec, s[90:91]
	s_cbranch_execnz .LBB0_4321
.LBB0_4322:
	s_or_b64 exec, exec, s[72:73]
	s_movk_i32 s4, 0x7f
	s_and_b32 s26, s40, 1
	v_cmp_lt_i32_e32 vcc, s4, v130
	s_and_saveexec_b64 s[14:15], vcc
	s_xor_b64 s[14:15], exec, s[14:15]
	s_lshl_b32 s4, s26, 7
	s_or_saveexec_b64 s[14:15], s[14:15]
	v_mov_b32_e32 v59, s4
	s_xor_b64 exec, exec, s[14:15]
	s_cbranch_execz .LBB0_4328
	v_mov_b64_e32 v[2:3], s[0:1]
	s_load_dwordx2 s[98:99], s[0:1], 0x88
	s_waitcnt vmcnt(0) lgkmcnt(0)
	v_mov_b32_e32 v6, s98
	v_mov_b32_e32 v7, s99
	s_lshl_b32 s4, s26, 7
	v_add_u32_e32 v2, s4, v130
	v_add_u32_e32 v8, 0x100, v2
	v_ashrrev_i32_e32 v9, 31, v8
	s_add_u32 s72, s38, 0x6200000
	s_addc_u32 s73, s39, 0
	s_mov_b32 s5, 0
	s_waitcnt lgkmcnt(0)
	v_lshl_add_u64 v[6:7], v[8:9], 2, v[6:7]
	global_load_dword v3, v[6:7], off nt

.LBB0_5332:
	v_mov_b64_e32 v[4:5], s[0:1]
	s_waitcnt lgkmcnt(0)
	s_barrier
	s_load_dwordx2 s[98:99], s[0:1], 0x28
	s_waitcnt vmcnt(0) lgkmcnt(0)
	v_mov_b32_e32 v2, s98
	v_mov_b32_e32 v3, s99
	s_load_dwordx2 s[98:99], s[0:1], 0x30
	s_waitcnt vmcnt(0) lgkmcnt(0)
	v_mov_b32_e32 v10, s98
	v_mov_b32_e32 v11, s99
	s_load_dwordx2 s[98:99], s[0:1], 0x40
	s_waitcnt vmcnt(0) lgkmcnt(0)
	v_mov_b32_e32 v4, s98
	v_mov_b32_e32 v5, s99
	s_lshl_b32 s6, s5, 2
	s_add_i32 s6, s3, s6
	v_mov_b32_e32 v6, s6
	v_add_u32_e32 v6, 0xc00, v6
	ds_read2_b32 v[6:7], v6 offset1:8
	s_mov_b64 s[8:9], -1
	s_waitcnt lgkmcnt(0)
	v_cmp_gt_i32_e32 vcc, 32, v6
	v_readfirstlane_b32 s10, v6
	v_readfirstlane_b32 s11, v7
	s_cbranch_vccnz .LBB0_5334
	s_add_u32 s6, s18, 0xc00
	s_addc_u32 s7, s19, 0
	s_mov_b64 s[8:9], 0

.LBB0_5542:
	s_or_b64 exec, exec, s[6:7]
	v_mov_b32_e32 v1, v0
	v_mov_b64_e32 v[2:3], s[0:1]
	s_barrier
	s_load_dwordx2 s[98:99], s[0:1], 0x58
	s_waitcnt vmcnt(0) lgkmcnt(0)
	v_mov_b32_e32 v2, s98
	v_mov_b32_e32 v3, s99
	v_readfirstlane_b32 s2, v1
	s_ashr_i32 s2, s2, 4
	s_and_b32 s3, s2, -4
	s_cmp_gt_i32 s3, 31
	s_cbranch_scc1 .LBB0_5545
	v_and_b32_e32 v21, 63, v1
	v_mov_b32_e32 v91, 0
	v_lshlrev_b32_e32 v90, 4, v21
	s_waitcnt lgkmcnt(0)
	v_lshl_add_u64 v[2:3], v[2:3], 0, v[90:91]
	s_movk_i32 s2, 0x5000
	v_add_co_u32_e32 v18, vcc, s2, v2
	v_and_b32_e32 v1, 64, v166
	s_nop 0
	v_addc_co_u32_e32 v19, vcc, 0, v3, vcc
	global_load_dwordx4 v[2:5], v[18:19], off
	global_load_dwordx4 v[6:9], v[18:19], off offset:1024
	global_load_dwordx4 v[10:13], v[18:19], off offset:2048
	global_load_dwordx4 v[14:17], v[18:19], off offset:3072
	v_add_u32_e32 v18, 64, v1
	v_xor_b32_e32 v1, 1, v166
	v_cmp_lt_i32_e32 vcc, v1, v18
	v_xor_b32_e32 v19, 2, v166
	s_lshl_b32 s4, s40, 5
	v_cndmask_b32_e32 v1, v166, v1, vcc
	v_cmp_lt_i32_e32 vcc, v19, v18
	s_add_i32 s3, s4, s3
	s_add_i32 s2, s4, 0x20a0
	v_cndmask_b32_e32 v19, v166, v19, vcc
	v_lshlrev_b32_e32 v167, 2, v19
	v_xor_b32_e32 v19, 4, v166
	v_cmp_lt_i32_e32 vcc, v19, v18
	s_add_i32 s12, s3, 0x2080
	s_add_u32 s3, s68, 0x5800000
	v_cndmask_b32_e32 v19, v166, v19, vcc
	v_lshlrev_b32_e32 v168, 2, v19
	v_xor_b32_e32 v19, 8, v166
	v_cmp_lt_i32_e32 vcc, v19, v18
	s_addc_u32 s4, s69, 0
	s_ashr_i32 s13, s12, 31
	v_cndmask_b32_e32 v19, v166, v19, vcc
	v_lshlrev_b32_e32 v169, 2, v19
	v_xor_b32_e32 v19, 16, v166
	v_cmp_lt_i32_e32 vcc, v19, v18
	s_lshl_b64 s[6:7], s[12:13], 11
	v_lshl_or_b32 v92, v21, 3, s6
	v_cndmask_b32_e32 v19, v166, v19, vcc
	v_lshlrev_b32_e32 v170, 2, v19
	v_xor_b32_e32 v19, 32, v166
	v_cmp_lt_i32_e32 vcc, v19, v18
	v_mov_b32_e32 v93, s7
	s_lshl_b64 s[6:7], s[12:13], 12
	v_cndmask_b32_e32 v18, v166, v19, vcc
	v_lshlrev_b32_e32 v171, 2, v18
	v_lshlrev_b32_e32 v18, 2, v21
	v_or_b32_e32 v20, 0x100, v18
	v_or_b32_e32 v22, 0x200, v18
	v_or_b32_e32 v24, 0x300, v18
	v_lshlrev_b32_e32 v1, 2, v1
	v_or_b32_e32 v94, s6, v90
	v_mov_b32_e32 v95, s7
	v_mov_b32_e32 v172, 0x358637bd
	s_mov_b32 s13, 0xf800000
	v_mov_b32_e32 v173, 0x260
	v_lshlrev_b32_e32 v90, 2, v18
	s_movk_i32 s22, 0x7fff
	s_mov_b32 s23, 0xffff0000
	s_mov_b32 s24, 0xba00000
	v_lshlrev_b32_e32 v96, 2, v20
	v_lshlrev_b32_e32 v98, 2, v22
	v_mov_b32_e32 v99, v91
	v_lshlrev_b32_e32 v100, 2, v24
	v_mov_b32_e32 v101, v91
	s_mov_b32 s25, 0xba01000
	s_mov_b64 s[14:15], 0x10000
	s_mov_b64 s[16:17], 0x20000
	v_mov_b32_e32 v97, v91

.LBB0_5572:
	ds_read2_b32 v[20:21], v18 offset1:2
	ds_read2st64_b32 v[22:23], v19 offset1:4
	s_add_i32 s8, s8, -8
	s_cmp_lg_u32 s8, 0
	s_waitcnt lgkmcnt(0)
	v_mfma_f32_32x32x2_f32 v[2:17], v20, v22, v[2:17]
	v_mfma_f32_32x32x2_f32 v[2:17], v21, v23, v[2:17]
	ds_read2_b32 v[20:21], v18 offset0:4 offset1:6
	ds_read2st64_b32 v[22:23], v19 offset0:8 offset1:12
	s_waitcnt lgkmcnt(0)
	v_mfma_f32_32x32x2_f32 v[2:17], v20, v22, v[2:17]
	v_mfma_f32_32x32x2_f32 v[2:17], v21, v23, v[2:17]
	ds_read2_b32 v[20:21], v18 offset0:8 offset1:10
	ds_read2st64_b32 v[22:23], v19 offset0:16 offset1:20
	s_waitcnt lgkmcnt(0)
	v_mfma_f32_32x32x2_f32 v[2:17], v20, v22, v[2:17]
	v_mfma_f32_32x32x2_f32 v[2:17], v21, v23, v[2:17]
	ds_read2_b32 v[20:21], v18 offset0:12 offset1:14
	ds_read2st64_b32 v[22:23], v19 offset0:24 offset1:28
	v_add_u32_e32 v19, 0x2000, v19
	v_add_u32_e32 v18, 64, v18
	s_waitcnt lgkmcnt(0)
	v_mfma_f32_32x32x2_f32 v[2:17], v20, v22, v[2:17]
	v_mfma_f32_32x32x2_f32 v[2:17], v21, v23, v[2:17]
	s_cbranch_scc1 .LBB0_5572
	v_add_u32_e32 v18, 0xc200, v103
	s_barrier
	s_nop 14
	ds_write2_b32 v18, v2, v3 offset0:64 offset1:196
	v_add_u32_e32 v2, 0xc600, v103
	ds_write2_b32 v2, v4, v5 offset0:72 offset1:204
	v_add_u32_e32 v2, 0xd200, v103
	ds_write2_b32 v2, v6, v7 offset0:96 offset1:228
	v_add_u32_e32 v2, 0xd600, v103
	ds_write2_b32 v2, v8, v9 offset0:104 offset1:236
	v_add_u32_e32 v2, 0xe400, v103
	ds_write2_b32 v2, v10, v11 offset1:132
	v_add_u32_e32 v2, 0xe800, v103
	ds_write2_b32 v2, v12, v13 offset0:8 offset1:140
	v_add_u32_e32 v2, 0xf400, v103
	ds_write2_b32 v2, v14, v15 offset0:32 offset1:164
	v_add_u32_e32 v2, 0xf800, v103
	v_mov_b64_e32 v[18:19], s[0:1]
	ds_write2_b32 v2, v16, v17 offset0:40 offset1:172
	s_waitcnt lgkmcnt(0)
	s_barrier
	ds_read_b128 v[14:17], v95 offset:49920
	ds_read_b128 v[10:13], v95 offset:49936
	ds_read_b128 v[6:9], v95 offset:49952
	ds_read_b128 v[2:5], v95 offset:49968
	s_load_dwordx2 s[98:99], s[0:1], 0xa8
	s_waitcnt vmcnt(0) lgkmcnt(0)
	v_mov_b32_e32 v22, s98
	v_mov_b32_e32 v23, s99
	v_mov_b32_e32 v1, v229
	v_add_u32_e32 v60, s36, v94
	v_mov_b64_e32 v[18:19], s[12:13]
	v_and_b32_e32 v21, 64, v166
	s_lshl_b32 s70, s35, 2
	v_mad_i64_i32 v[18:19], s[8:9], v60, s29, v[18:19]
	v_xor_b32_e32 v20, 1, v166
	v_lshlrev_b32_e32 v42, 2, v54
	v_add_u32_e32 v59, 64, v21
	v_lshl_add_u64 v[18:19], v[18:19], 0, s[70:71]
	v_cmp_lt_i32_e32 vcc, v20, v59
	v_lshl_add_u64 v[30:31], v[18:19], 0, v[42:43]
	s_waitcnt lgkmcnt(0)
	v_mov_b32_e32 v26, v15
	v_cndmask_b32_e32 v20, v166, v20, vcc
	v_add_co_u32_e32 v18, vcc, s28, v30
	v_lshlrev_b32_e32 v61, 2, v20
	s_nop 0
	v_addc_co_u32_e32 v19, vcc, 0, v31, vcc
	global_load_dwordx4 v[18:21], v[18:19], off offset:1184
	v_mov_b32_e32 v27, v11
	v_mov_b32_e32 v24, v14
	v_mov_b32_e32 v25, v10
	v_mov_b32_e32 v36, v7
	v_mov_b32_e32 v37, v3
	v_pk_mul_f32 v[26:27], v[26:27], v[26:27]
	v_mov_b32_e32 v28, v16
	v_mov_b32_e32 v29, v12
	v_mov_b32_e32 v34, v6
	v_mov_b32_e32 v35, v2
	v_pk_mul_f32 v[36:37], v[36:37], v[36:37]
	v_pk_fma_f32 v[24:25], v[24:25], v[24:25], v[26:27]
	v_mov_b32_e32 v32, v17
	v_mov_b32_e32 v33, v13
	v_mov_b32_e32 v38, v8
	v_mov_b32_e32 v39, v4
	v_pk_fma_f32 v[26:27], v[34:35], v[34:35], v[36:37]
	v_pk_fma_f32 v[24:25], v[28:29], v[28:29], v[24:25]
	v_mov_b32_e32 v40, v9
	v_mov_b32_e32 v41, v5
	v_pk_fma_f32 v[26:27], v[38:39], v[38:39], v[26:27]
	v_pk_fma_f32 v[24:25], v[32:33], v[32:33], v[24:25]
	v_pk_fma_f32 v[26:27], v[40:41], v[40:41], v[26:27]
	v_add_f32_e32 v24, v24, v25
	v_add_f32_e32 v24, v24, v26
	v_add_f32_e32 v24, v24, v27
	ds_bpermute_b32 v25, v61, v24
	v_xor_b32_e32 v26, 2, v166
	v_cmp_lt_i32_e32 vcc, v26, v59
	v_lshl_add_u64 v[62:63], v[30:31], 0, s[72:73]
	v_mov_b32_e32 v38, v14
	v_cndmask_b32_e32 v26, v166, v26, vcc
	v_lshlrev_b32_e32 v26, 2, v26
	s_waitcnt lgkmcnt(0)
	v_add_f32_e32 v24, v24, v25
	ds_bpermute_b32 v25, v26, v24
	v_ashrrev_i32_e32 v61, 31, v60
	s_lshl_b32 s70, s35, 1
	s_mov_b64 s[76:77], 0
	s_waitcnt lgkmcnt(0)
	v_add_f32_e32 v32, v24, v25
	v_lshl_add_u64 v[64:65], v[22:23], 0, v[42:43]
	global_load_dwordx4 v[26:29], v[64:65], off offset:512
	v_xor_b32_e32 v22, 4, v166
	v_cmp_lt_i32_e32 vcc, v22, v59
	s_nop 1
	v_cndmask_b32_e32 v22, v166, v22, vcc
	v_lshlrev_b32_e32 v22, 2, v22
	ds_bpermute_b32 v33, v22, v32
	global_load_dwordx4 v[22:25], v[64:65], off offset:528
	s_waitcnt lgkmcnt(0)
	v_add_f32_e32 v30, v32, v33
	v_fmamk_f32 v30, v30, 0x3c000000, v104
	v_mul_f32_e32 v31, 0x4f800000, v30
	v_cmp_gt_f32_e32 vcc, s31, v30
	s_nop 1
	v_cndmask_b32_e32 v39, v30, v31, vcc
	v_sqrt_f32_e32 v40, v39
	global_load_dwordx4 v[30:33], v[62:63], off offset:16
	global_load_dwordx4 v[34:37], v[62:63], off offset:48
	v_add_u32_e32 v14, -1, v40
	v_add_u32_e32 v41, 1, v40
	v_fma_f32 v42, -v14, v40, v39
	v_fma_f32 v59, -v41, v40, v39
	v_cmp_ge_f32_e64 s[8:9], 0, v42
	s_nop 1
	v_cndmask_b32_e64 v14, v40, v14, s[8:9]
	v_cmp_lt_f32_e64 s[8:9], 0, v59
	s_nop 1
	v_cndmask_b32_e64 v14, v14, v41, s[8:9]
	v_mul_f32_e32 v40, 0x37800000, v14
	v_cndmask_b32_e32 v14, v14, v40, vcc
	v_cmp_class_f32_e32 vcc, v39, v105
	s_nop 1
	v_cndmask_b32_e32 v14, v14, v39, vcc
	v_div_scale_f32 v40, s[8:9], v14, v14, 1.0
	v_rcp_f32_e32 v41, v40
	v_mov_b32_e32 v39, v16
	v_div_scale_f32 v16, vcc, 1.0, v14, 1.0
	v_fma_f32 v42, -v40, v41, 1.0
	v_fmac_f32_e32 v41, v42, v41
	v_mul_f32_e32 v42, v16, v41
	v_fma_f32 v59, -v40, v42, v16
	v_fmac_f32_e32 v42, v59, v41
	v_fma_f32 v16, -v40, v42, v16
	v_div_fmas_f32 v16, v16, v41, v42
	v_div_fixup_f32 v14, v16, v14, 1.0
	v_pk_mul_f32 v[110:111], v[38:39], v[14:15] op_sel_hi:[1,0]
	s_waitcnt vmcnt(0)
	v_mul_f32_e32 v16, 0xbfb8aa3b, v18
	v_mul_f32_e32 v38, 0xbfb8aa3b, v20
	v_exp_f32_e32 v112, v16
	v_exp_f32_e32 v113, v38
	v_mul_f32_e32 v16, 0xbfb8aa3b, v19
	global_load_dwordx4 v[38:41], v[64:65], off offset:560
	global_load_dwordx4 v[106:109], v[64:65], off offset:544
	v_exp_f32_e32 v64, v16
	v_pk_add_f32 v[112:113], v[112:113], 1.0 op_sel_hi:[1,0]
	s_nop 0
	v_div_scale_f32 v16, s[8:9], v113, v113, v20
	v_rcp_f32_e32 v65, v16
	v_div_scale_f32 v59, s[8:9], v112, v112, v18
	v_rcp_f32_e32 v116, v59
	v_fma_f32 v114, -v16, v65, 1.0
	v_div_scale_f32 v42, vcc, v20, v113, v20
	v_fmac_f32_e32 v65, v114, v65
	v_fma_f32 v115, -v59, v116, 1.0
	v_mul_f32_e32 v114, v42, v65
	v_fmac_f32_e32 v116, v115, v116
	v_fma_f32 v115, -v16, v114, v42
	v_fmac_f32_e32 v114, v115, v65
	v_fma_f32 v16, -v16, v114, v42
	v_div_fmas_f32 v16, v16, v65, v114
	v_div_scale_f32 v117, s[8:9], v18, v112, v18
	v_div_fixup_f32 v113, v16, v113, v20
	v_mul_f32_e32 v20, 0xbfb8aa3b, v21
	v_mul_f32_e32 v118, v117, v116
	v_exp_f32_e32 v65, v20
	v_fma_f32 v119, -v59, v118, v117
	v_fmac_f32_e32 v118, v119, v116
	v_fma_f32 v16, -v59, v118, v117
	s_mov_b64 vcc, s[8:9]
	v_div_fmas_f32 v16, v16, v116, v118
	v_pk_add_f32 v[64:65], v[64:65], 1.0 op_sel_hi:[1,0]
	v_div_fixup_f32 v112, v16, v112, v18
	v_mov_b32_e32 v16, v15
	v_div_scale_f32 v15, s[8:9], v65, v65, v21
	v_rcp_f32_e32 v18, v15
	v_mov_b32_e32 v114, v26
	v_mov_b32_e32 v115, v28
	v_mov_b32_e32 v28, v27
	v_fma_f32 v20, -v15, v18, 1.0
	v_fmac_f32_e32 v18, v20, v18
	v_div_scale_f32 v20, vcc, v21, v65, v21
	v_mul_f32_e32 v26, v20, v18
	v_fma_f32 v27, -v15, v26, v20
	v_fmac_f32_e32 v26, v27, v18
	v_pk_mul_f32 v[16:17], v[16:17], v[14:15] op_sel_hi:[1,0]
	v_fma_f32 v15, -v15, v26, v20
	v_div_scale_f32 v20, s[8:9], v64, v64, v19
	v_rcp_f32_e32 v27, v20
	v_div_fmas_f32 v15, v15, v18, v26
	v_div_fixup_f32 v21, v15, v65, v21
	v_pk_mul_f32 v[16:17], v[28:29], v[16:17]
	v_fma_f32 v15, -v20, v27, 1.0
	v_fmac_f32_e32 v27, v15, v27
	v_div_scale_f32 v15, vcc, v19, v64, v19
	v_mul_f32_e32 v18, v15, v27
	v_fma_f32 v26, -v20, v18, v15
	v_fmac_f32_e32 v18, v26, v27
	v_fma_f32 v15, -v20, v18, v15
	v_div_fmas_f32 v15, v15, v27, v18
	v_div_fixup_f32 v20, v15, v64, v19
	v_pk_mul_f32 v[20:21], v[20:21], v[16:17]
	global_load_dwordx4 v[16:19], v[62:63], off offset:32
	s_waitcnt lgkmcnt(0)
	v_mul_f32_e32 v15, 0xbfb8aa3b, v30
	v_exp_f32_e32 v26, v15
	v_mul_f32_e32 v15, 0xbfb8aa3b, v31
	v_exp_f32_e32 v28, v15
	v_mul_f32_e32 v15, 0xbfb8aa3b, v32
	v_exp_f32_e32 v27, v15
	v_mov_b32_e32 v62, v10
	v_mov_b32_e32 v63, v12
	v_pk_mul_f32 v[62:63], v[62:63], v[14:15] op_sel_hi:[1,0]
	v_pk_add_f32 v[26:27], v[26:27], 1.0 op_sel_hi:[1,0]
	v_mov_b32_e32 v64, v22
	v_div_scale_f32 v10, s[8:9], v27, v27, v32
	v_rcp_f32_e32 v12, v10
	v_mov_b32_e32 v65, v24
	v_pk_mul_f32 v[110:111], v[114:115], v[110:111]
	v_pk_mul_f32 v[62:63], v[62:63], v[64:65]
	v_fma_f32 v15, -v10, v12, 1.0
	v_fmac_f32_e32 v12, v15, v12
	v_div_scale_f32 v15, vcc, v32, v27, v32
	v_mul_f32_e32 v22, v15, v12
	v_fma_f32 v24, -v10, v22, v15
	v_fmac_f32_e32 v22, v24, v12
	v_fma_f32 v10, -v10, v22, v15
	v_div_scale_f32 v15, s[8:9], v26, v26, v30
	v_rcp_f32_e32 v24, v15
	v_div_fmas_f32 v10, v10, v12, v22
	v_div_fixup_f32 v27, v10, v27, v32
	v_pk_mul_f32 v[110:111], v[112:113], v[110:111]
	v_fma_f32 v10, -v15, v24, 1.0
	v_fmac_f32_e32 v24, v10, v24
	v_div_scale_f32 v10, vcc, v30, v26, v30
	v_mul_f32_e32 v12, v10, v24
	v_fma_f32 v22, -v15, v12, v10
	v_fmac_f32_e32 v12, v22, v24
	v_fma_f32 v10, -v15, v12, v10
	v_div_fmas_f32 v10, v10, v24, v12
	v_mul_f32_e32 v12, 0xbfb8aa3b, v33
	v_exp_f32_e32 v29, v12
	v_div_fixup_f32 v26, v10, v26, v30
	v_mov_b32_e32 v12, v11
	v_mov_b32_e32 v24, v23
	v_pk_add_f32 v[10:11], v[28:29], 1.0 op_sel_hi:[1,0]
	v_pk_mul_f32 v[26:27], v[62:63], v[26:27]
	v_div_scale_f32 v15, s[8:9], v11, v11, v33
	v_rcp_f32_e32 v22, v15
	v_pk_mul_f32 v[12:13], v[12:13], v[14:15] op_sel_hi:[1,0]
	v_lshlrev_b32_e32 v42, 1, v54
	v_pk_mul_f32 v[12:13], v[12:13], v[24:25]
	v_fma_f32 v23, -v15, v22, 1.0
	v_fmac_f32_e32 v22, v23, v22
	v_div_scale_f32 v23, vcc, v33, v11, v33
	v_mul_f32_e32 v24, v23, v22
	v_fma_f32 v25, -v15, v24, v23
	v_fmac_f32_e32 v24, v25, v22
	v_fma_f32 v15, -v15, v24, v23
	v_div_scale_f32 v23, s[8:9], v10, v10, v31
	v_rcp_f32_e32 v25, v23
	v_div_fmas_f32 v15, v15, v22, v24
	v_div_fixup_f32 v11, v15, v11, v33
	v_fma_f32 v15, -v23, v25, 1.0
	v_fmac_f32_e32 v25, v15, v25
	v_div_scale_f32 v15, vcc, v31, v10, v31
	v_mul_f32_e32 v22, v15, v25
	v_fma_f32 v24, -v23, v22, v15
	v_fmac_f32_e32 v22, v24, v25
	v_fma_f32 v15, -v23, v22, v15
	v_div_fmas_f32 v15, v15, v25, v22
	v_div_fixup_f32 v10, v15, v10, v31
	v_pk_mul_f32 v[10:11], v[12:13], v[10:11]
	v_cvt_pk_bf16_f32 v13, v27, v11
	v_cvt_pk_bf16_f32 v11, v111, v21
	s_waitcnt vmcnt(0)
	v_mul_f32_e32 v15, 0xbfb8aa3b, v16
	v_cvt_pk_bf16_f32 v12, v26, v10
	v_cvt_pk_bf16_f32 v10, v110, v20
	v_exp_f32_e32 v20, v15
	v_mul_f32_e32 v15, 0xbfb8aa3b, v17
	v_exp_f32_e32 v22, v15
	v_mul_f32_e32 v15, 0xbfb8aa3b, v18
	v_exp_f32_e32 v21, v15
	v_mov_b32_e32 v24, v6
	v_mov_b32_e32 v25, v8
	v_pk_mul_f32 v[24:25], v[24:25], v[14:15] op_sel_hi:[1,0]
	v_pk_add_f32 v[20:21], v[20:21], 1.0 op_sel_hi:[1,0]
	v_mov_b32_e32 v26, v106
	v_div_scale_f32 v6, s[8:9], v21, v21, v18
	v_rcp_f32_e32 v8, v6
	v_mov_b32_e32 v27, v108
	v_pk_mul_f32 v[24:25], v[24:25], v[26:27]
	v_mov_b32_e32 v108, v107
	v_fma_f32 v15, -v6, v8, 1.0
	v_fmac_f32_e32 v8, v15, v8
	v_div_scale_f32 v15, vcc, v18, v21, v18
	v_mul_f32_e32 v23, v15, v8
	v_fma_f32 v26, -v6, v23, v15
	v_fmac_f32_e32 v23, v26, v8
	v_fma_f32 v6, -v6, v23, v15
	v_div_scale_f32 v15, s[8:9], v20, v20, v16
	v_rcp_f32_e32 v26, v15
	v_div_fmas_f32 v6, v6, v8, v23
	v_div_fixup_f32 v21, v6, v21, v18
	v_fma_f32 v6, -v15, v26, 1.0
	v_fmac_f32_e32 v26, v6, v26
	v_div_scale_f32 v6, vcc, v16, v20, v16
	v_mul_f32_e32 v8, v6, v26
	v_fma_f32 v18, -v15, v8, v6
	v_fmac_f32_e32 v8, v18, v26
	v_fma_f32 v6, -v15, v8, v6
	v_div_fmas_f32 v6, v6, v26, v8
	v_mul_f32_e32 v8, 0xbfb8aa3b, v19
	v_exp_f32_e32 v23, v8
	v_div_fixup_f32 v20, v6, v20, v16
	v_mov_b32_e32 v8, v7
	v_pk_mul_f32 v[20:21], v[24:25], v[20:21]
	v_pk_add_f32 v[6:7], v[22:23], 1.0 op_sel_hi:[1,0]
	s_nop 0
	v_div_scale_f32 v15, s[8:9], v7, v7, v19
	v_rcp_f32_e32 v16, v15
	v_pk_mul_f32 v[8:9], v[8:9], v[14:15] op_sel_hi:[1,0]
	v_fma_f32 v18, -v15, v16, 1.0
	v_fmac_f32_e32 v16, v18, v16
	v_div_scale_f32 v18, vcc, v19, v7, v19
	v_mul_f32_e32 v22, v18, v16
	v_fma_f32 v23, -v15, v22, v18
	v_fmac_f32_e32 v22, v23, v16
	v_fma_f32 v15, -v15, v22, v18
	v_div_scale_f32 v18, s[8:9], v6, v6, v17
	v_rcp_f32_e32 v23, v18
	v_div_fmas_f32 v15, v15, v16, v22
	v_div_fixup_f32 v7, v15, v7, v19
	v_pk_mul_f32 v[8:9], v[8:9], v[108:109]
	v_fma_f32 v15, -v18, v23, 1.0
	v_fmac_f32_e32 v23, v15, v23
	v_div_scale_f32 v15, vcc, v17, v6, v17
	v_mul_f32_e32 v16, v15, v23
	v_fma_f32 v19, -v18, v16, v15
	v_fmac_f32_e32 v16, v19, v23
	v_fma_f32 v15, -v18, v16, v15
	v_div_fmas_f32 v15, v15, v23, v16
	v_div_fixup_f32 v6, v15, v6, v17
	v_pk_mul_f32 v[6:7], v[8:9], v[6:7]
	v_mul_f32_e32 v9, 0xbfb8aa3b, v35
	v_mul_f32_e32 v8, 0xbfb8aa3b, v34
	v_exp_f32_e32 v16, v9
	v_mul_f32_e32 v9, 0xbfb8aa3b, v36
	v_exp_f32_e32 v8, v8
	v_exp_f32_e32 v9, v9
	v_mov_b32_e32 v18, v2
	v_mov_b32_e32 v19, v4
	v_pk_mul_f32 v[18:19], v[18:19], v[14:15] op_sel_hi:[1,0]
	v_pk_add_f32 v[8:9], v[8:9], 1.0 op_sel_hi:[1,0]
	v_mov_b32_e32 v22, v38
	v_div_scale_f32 v2, s[8:9], v9, v9, v36
	v_rcp_f32_e32 v4, v2
	v_mov_b32_e32 v23, v40
	v_pk_mul_f32 v[18:19], v[18:19], v[22:23]
	v_mov_b32_e32 v40, v39
	v_fma_f32 v15, -v2, v4, 1.0
	v_fmac_f32_e32 v4, v15, v4
	v_div_scale_f32 v15, vcc, v36, v9, v36
	v_mul_f32_e32 v17, v15, v4
	v_fma_f32 v22, -v2, v17, v15
	v_fmac_f32_e32 v17, v22, v4
	v_fma_f32 v2, -v2, v17, v15
	v_div_scale_f32 v15, s[8:9], v8, v8, v34
	v_rcp_f32_e32 v22, v15
	v_div_fmas_f32 v2, v2, v4, v17
	v_div_fixup_f32 v9, v2, v9, v36
	v_fma_f32 v2, -v15, v22, 1.0
	v_fmac_f32_e32 v22, v2, v22
	v_div_scale_f32 v2, vcc, v34, v8, v34
	v_mul_f32_e32 v4, v2, v22
	v_fma_f32 v17, -v15, v4, v2
	v_fmac_f32_e32 v4, v17, v22
	v_fma_f32 v2, -v15, v4, v2
	v_div_fmas_f32 v2, v2, v22, v4
	v_mul_f32_e32 v4, 0xbfb8aa3b, v37
	v_exp_f32_e32 v17, v4
	v_div_fixup_f32 v8, v2, v8, v34
	v_mov_b32_e32 v4, v3
	v_pk_mul_f32 v[8:9], v[18:19], v[8:9]
	v_pk_add_f32 v[2:3], v[16:17], 1.0 op_sel_hi:[1,0]
	s_nop 0
	v_div_scale_f32 v15, s[8:9], v3, v3, v37
	v_rcp_f32_e32 v16, v15
	v_pk_mul_f32 v[4:5], v[4:5], v[14:15] op_sel_hi:[1,0]
	v_fma_f32 v14, -v15, v16, 1.0
	v_fmac_f32_e32 v16, v14, v16
	v_div_scale_f32 v14, vcc, v37, v3, v37
	v_mul_f32_e32 v17, v14, v16
	v_fma_f32 v18, -v15, v17, v14
	v_fmac_f32_e32 v17, v18, v16
	v_fma_f32 v14, -v15, v17, v14
	v_div_scale_f32 v15, s[8:9], v2, v2, v35
	v_rcp_f32_e32 v18, v15
	v_div_fmas_f32 v14, v14, v16, v17
	v_div_fixup_f32 v3, v14, v3, v37
	v_pk_mul_f32 v[4:5], v[4:5], v[40:41]
	v_fma_f32 v14, -v15, v18, 1.0
	v_fmac_f32_e32 v18, v14, v18
	v_div_scale_f32 v14, vcc, v35, v2, v35
	v_mul_f32_e32 v16, v14, v18
	v_fma_f32 v17, -v15, v16, v14
	v_fmac_f32_e32 v16, v17, v18
	v_fma_f32 v14, -v15, v16, v14
	v_div_fmas_f32 v14, v14, v18, v16
	v_div_fixup_f32 v2, v14, v2, v35
	v_pk_mul_f32 v[2:3], v[4:5], v[2:3]
	v_bfe_u32 v5, v2, 16, 1
	v_add3_u32 v2, v2, v5, s33
	v_bfe_u32 v14, v8, 16, 1
	v_add3_u32 v8, v8, v14, s33
	v_lshrrev_b32_e32 v4, 16, v8
	v_cvt_pk_bf16_f32 v5, v9, v3
	v_and_or_b32 v4, v2, s34, v4
	v_cvt_pk_bf16_f32 v3, v21, v7
	v_cvt_pk_bf16_f32 v2, v20, v6
	v_lshlrev_b64 v[6:7], 11, v[60:61]
	v_lshl_add_u64 v[6:7], s[68:69], 0, v[6:7]
	v_lshl_add_u64 v[6:7], v[6:7], 0, s[70:71]
	v_lshl_add_u64 v[6:7], v[6:7], 0, v[42:43]
	v_lshl_add_u64 v[8:9], v[6:7], 0, s[74:75]
	v_add_co_u32_e32 v6, vcc, 0xdc00000, v6
	s_nop 1
	v_addc_co_u32_e32 v7, vcc, 0, v7, vcc
	global_store_dwordx4 v[6:7], v[10:13], off offset:1024
	global_store_dwordx4 v[8:9], v[2:5], off offset:16
	s_branch .LBB0_5556

.LBB0_5691:
	s_or_b64 exec, exec, s[10:11]
	v_mov_b32_e32 v1, v0
	v_mov_b64_e32 v[2:3], s[0:1]
	s_barrier
	s_load_dwordx2 s[98:99], s[0:1], 0x58
	s_waitcnt vmcnt(0) lgkmcnt(0)
	v_mov_b32_e32 v2, s98
	v_mov_b32_e32 v3, s99
	v_readfirstlane_b32 s5, v1
	s_ashr_i32 s5, s5, 4
	s_and_b32 s6, s5, -4
	s_cmp_gt_i32 s6, 63
	s_cbranch_scc1 .LBB0_5694
	v_and_b32_e32 v21, 63, v1
	v_mov_b32_e32 v91, 0
	v_lshlrev_b32_e32 v90, 4, v21
	s_waitcnt lgkmcnt(0)
	v_lshl_add_u64 v[2:3], v[2:3], 0, v[90:91]
	s_movk_i32 s5, 0x5000
	v_add_co_u32_e32 v18, vcc, s5, v2
	v_mbcnt_lo_u32_b32 v1, -1, 0
	s_nop 0
	v_addc_co_u32_e32 v19, vcc, 0, v3, vcc
	global_load_dwordx4 v[2:5], v[18:19], off
	global_load_dwordx4 v[6:9], v[18:19], off offset:1024
	global_load_dwordx4 v[10:13], v[18:19], off offset:2048
	global_load_dwordx4 v[14:17], v[18:19], off offset:3072
	v_mbcnt_hi_u32_b32 v18, -1, v1
	v_and_b32_e32 v1, 64, v18
	v_add_u32_e32 v19, 64, v1
	v_xor_b32_e32 v1, 1, v18
	v_cmp_lt_i32_e32 vcc, v1, v19
	v_xor_b32_e32 v20, 2, v18
	s_lshl_b32 s7, s28, 8
	v_cndmask_b32_e32 v1, v18, v1, vcc
	v_cmp_lt_i32_e32 vcc, v20, v19
	s_lshl_b32 s4, s4, 6
	s_add_i32 s8, s7, s4
	v_cndmask_b32_e32 v20, v18, v20, vcc
	v_lshlrev_b32_e32 v166, 2, v20
	v_xor_b32_e32 v20, 4, v18
	v_cmp_lt_i32_e32 vcc, v20, v19
	s_add_i32 s10, s6, s8
	s_add_u32 s4, s68, 0x5800000
	v_cndmask_b32_e32 v20, v18, v20, vcc
	v_lshlrev_b32_e32 v167, 2, v20
	v_xor_b32_e32 v20, 8, v18
	v_cmp_lt_i32_e32 vcc, v20, v19
	s_addc_u32 s5, s69, 0
	s_lshl_b32 s3, s3, 6
	v_cndmask_b32_e32 v20, v18, v20, vcc
	v_lshlrev_b32_e32 v168, 2, v20
	v_xor_b32_e32 v20, 16, v18
	v_cmp_lt_i32_e32 vcc, v20, v19
	s_add_i32 s3, s7, s3
	s_add_i32 s3, s3, s6
	v_cndmask_b32_e32 v20, v18, v20, vcc
	v_lshlrev_b32_e32 v169, 2, v20
	v_xor_b32_e32 v20, 32, v18
	v_cmp_lt_i32_e32 vcc, v20, v19
	s_lshl_b32 s2, s2, 6
	s_sub_i32 s2, s3, s2
	v_cndmask_b32_e32 v18, v18, v20, vcc
	s_ashr_i32 s11, s10, 31
	v_lshlrev_b32_e32 v170, 2, v18
	v_lshlrev_b32_e32 v18, 2, v21
	s_or_b32 s20, s8, 32
	s_sub_i32 s8, s2, 32
	s_lshl_b64 s[2:3], s[10:11], 11
	v_or_b32_e32 v20, 0x100, v18
	v_or_b32_e32 v22, 0x200, v18
	v_or_b32_e32 v24, 0x300, v18
	v_lshl_or_b32 v92, v21, 3, s2
	v_mov_b32_e32 v93, s3
	s_lshl_b64 s[2:3], s[10:11], 12
	v_lshlrev_b32_e32 v1, 2, v1
	v_or_b32_e32 v94, s2, v90
	v_mov_b32_e32 v95, s3
	v_mov_b32_e32 v171, 0x358637bd
	s_mov_b32 s2, 0xf800000
	v_mov_b32_e32 v172, 0x260
	v_lshlrev_b32_e32 v90, 2, v18
	s_movk_i32 s3, 0x7fff
	s_mov_b32 s21, 0xffff0000
	s_mov_b32 s22, 0xba00000
	v_lshlrev_b32_e32 v96, 2, v20
	v_lshlrev_b32_e32 v98, 2, v22
	v_mov_b32_e32 v99, v91
	v_lshlrev_b32_e32 v100, 2, v24
	v_mov_b32_e32 v101, v91
	s_mov_b32 s23, 0xba01000
	s_mov_b64 s[12:13], 0x10000
	s_mov_b64 s[14:15], 0x20000
	v_mov_b32_e32 v97, v91

.LBB0_5799:
	s_or_b64 exec, exec, s[6:7]
	v_mov_b32_e32 v1, v0
	v_mov_b64_e32 v[2:3], s[0:1]
	s_barrier
	s_load_dwordx2 s[98:99], s[0:1], 0xc8
	s_waitcnt vmcnt(0) lgkmcnt(0)
	v_mov_b32_e32 v2, s98
	v_mov_b32_e32 v3, s99
	v_readfirstlane_b32 s5, v1
	s_ashr_i32 s6, s5, 6
	s_cmp_gt_i32 s6, 7
	s_cbranch_scc1 .LBB0_5802
	v_and_b32_e32 v20, 63, v1
	v_mov_b32_e32 v83, 0
	v_lshlrev_b32_e32 v82, 4, v20
	s_waitcnt lgkmcnt(0)
	v_lshl_add_u64 v[18:19], v[2:3], 0, v[82:83]
	global_load_dwordx4 v[2:5], v[18:19], off
	global_load_dwordx4 v[6:9], v[18:19], off offset:1024
	global_load_dwordx4 v[10:13], v[18:19], off offset:2048
	global_load_dwordx4 v[14:17], v[18:19], off offset:3072
	v_mbcnt_lo_u32_b32 v1, -1, 0
	v_mbcnt_hi_u32_b32 v18, -1, v1
	v_and_b32_e32 v1, 64, v18
	v_add_u32_e32 v19, 64, v1
	v_xor_b32_e32 v1, 1, v18
	v_cmp_lt_i32_e32 vcc, v1, v19
	v_xor_b32_e32 v21, 2, v18
	s_lshl_b32 s7, s82, 5
	v_cndmask_b32_e32 v1, v18, v1, vcc
	v_cmp_lt_i32_e32 vcc, v21, v19
	s_lshl_b32 s6, s6, 2
	s_add_i32 s6, s7, s6
	v_cndmask_b32_e32 v21, v18, v21, vcc
	v_lshlrev_b32_e32 v94, 2, v21
	v_xor_b32_e32 v21, 4, v18
	v_cmp_lt_i32_e32 vcc, v21, v19
	s_add_i32 s5, s7, 0x20a0
	s_add_i32 s20, s6, 0x2080
	v_cndmask_b32_e32 v21, v18, v21, vcc
	v_lshlrev_b32_e32 v95, 2, v21
	v_xor_b32_e32 v21, 8, v18
	v_cmp_lt_i32_e32 vcc, v21, v19
	s_add_u32 s28, s68, 0x4000000
	s_addc_u32 s29, s69, 0
	v_cndmask_b32_e32 v21, v18, v21, vcc
	v_lshlrev_b32_e32 v96, 2, v21
	v_xor_b32_e32 v21, 16, v18
	v_cmp_lt_i32_e32 vcc, v21, v19
	s_ashr_i32 s21, s20, 31
	s_mov_b32 s23, 0
	v_cndmask_b32_e32 v21, v18, v21, vcc
	v_lshlrev_b32_e32 v97, 2, v21
	v_xor_b32_e32 v21, 32, v18
	v_cmp_lt_i32_e32 vcc, v21, v19
	v_lshlrev_b32_e32 v1, 2, v1
	s_lshl_b64 s[24:25], s[20:21], 12
	v_cndmask_b32_e32 v18, v18, v21, vcc
	v_lshlrev_b32_e32 v98, 2, v18
	v_lshlrev_b32_e32 v18, 2, v20
	v_lshl_add_u64 v[84:85], s[70:71], 0, v[82:83]
	v_mov_b32_e32 v99, 0x358637bd
	s_mov_b32 s21, 0xf800000
	v_mov_b32_e32 v100, 0x260
	v_lshlrev_b32_e32 v82, 2, v18
	s_mov_b64 s[26:27], 0x20000
	s_mov_b64 s[38:39], s[68:69]

.LBB0_5946:
	s_or_b64 exec, exec, s[6:7]
	v_mov_b64_e32 v[2:3], s[0:1]
	s_barrier
	s_load_dwordx2 s[98:99], s[0:1], 0xc8
	s_waitcnt vmcnt(0) lgkmcnt(0)
	v_mov_b32_e32 v2, s98
	v_mov_b32_e32 v3, s99
	v_readfirstlane_b32 s0, v0
	s_ashr_i32 s0, s0, 6
	s_cmp_gt_i32 s0, 15
	s_cbranch_scc1 .LBB0_5949
	v_and_b32_e32 v18, 63, v0
	v_mov_b32_e32 v81, 0
	v_lshlrev_b32_e32 v80, 4, v18
	s_waitcnt lgkmcnt(0)
	v_lshl_add_u64 v[16:17], v[2:3], 0, v[80:81]
	global_load_dwordx4 v[0:3], v[16:17], off
	global_load_dwordx4 v[4:7], v[16:17], off offset:1024
	global_load_dwordx4 v[8:11], v[16:17], off offset:2048
	global_load_dwordx4 v[12:15], v[16:17], off offset:3072
	v_mbcnt_lo_u32_b32 v16, -1, 0
	v_mbcnt_hi_u32_b32 v16, -1, v16
	v_and_b32_e32 v17, 64, v16
	v_add_u32_e32 v17, 64, v17
	v_xor_b32_e32 v19, 1, v16
	v_cmp_lt_i32_e32 vcc, v19, v17
	s_lshl_b32 s1, s31, 8
	s_lshl_b32 s2, s30, 6
	v_cndmask_b32_e32 v19, v16, v19, vcc
	v_lshlrev_b32_e32 v92, 2, v19
	v_xor_b32_e32 v19, 2, v16
	v_cmp_lt_i32_e32 vcc, v19, v17
	s_add_i32 s2, s1, s2
	s_lshl_b32 s3, s0, 2
	v_cndmask_b32_e32 v19, v16, v19, vcc
	v_lshlrev_b32_e32 v93, 2, v19
	v_xor_b32_e32 v19, 4, v16
	v_cmp_lt_i32_e32 vcc, v19, v17
	s_add_i32 s0, s3, s2
	s_or_b32 s14, s2, 32
	v_cndmask_b32_e32 v19, v16, v19, vcc
	v_lshlrev_b32_e32 v94, 2, v19
	v_xor_b32_e32 v19, 8, v16
	v_cmp_lt_i32_e32 vcc, v19, v17
	s_add_u32 s15, s68, 0x4000000
	s_addc_u32 s16, s69, 0
	v_cndmask_b32_e32 v19, v16, v19, vcc
	v_lshlrev_b32_e32 v95, 2, v19
	v_xor_b32_e32 v19, 16, v16
	v_cmp_lt_i32_e32 vcc, v19, v17
	s_lshl_b32 s2, s29, 6
	s_add_i32 s1, s1, s2
	v_cndmask_b32_e32 v19, v16, v19, vcc
	v_lshlrev_b32_e32 v96, 2, v19
	v_xor_b32_e32 v19, 32, v16
	v_cmp_lt_i32_e32 vcc, v19, v17
	s_add_i32 s1, s1, s3
	s_lshl_b32 s2, s28, 6
	v_cndmask_b32_e32 v16, v16, v19, vcc
	s_sub_i32 s1, s1, s2
	v_lshlrev_b32_e32 v97, 2, v16
	v_lshlrev_b32_e32 v16, 2, v18
	s_sub_i32 s17, s1, 32
	s_ashr_i32 s1, s0, 31
	s_mov_b32 s9, 0
	s_lshl_b64 s[10:11], s[0:1], 12
	v_lshl_add_u64 v[82:83], s[70:71], 0, v[80:81]
	v_mov_b32_e32 v98, 0x358637bd
	s_mov_b32 s18, 0xf800000
	v_mov_b32_e32 v99, 0x260
	v_lshlrev_b32_e32 v80, 2, v16
	s_mov_b64 s[12:13], 0x20000
